# plus: hand-scheduled token-parallel gla chunk-summary front end (gates/decay/scaling) in phase 5
# speedup vs baseline: 1.0311x; 1.0039x over previous
; __device__ __forceinline__ unsigned pk2(float lo, float hi) { unsigned r; asm("v_cvt_pk_bf16_f32 %0, %1, %2" : "=v"(r) : "v"(lo), "v"(hi)); return r; }
; __device__ __forceinline__ void gl1_item(PREF p, int l, int item, bool valid, LAS unsigned char* pl, int sw, int lane) {
;     ...
;     if (valid) {
;         const bf16_t* prl = P + (size_t)(row0 + lane * rstride) * PW + 2560 + d * 16;
;         const u32x4 lra = *(const u32x4*)prl, lrb = *(const u32x4*)(prl + 8);
;         unsigned lrp[8] = {lra.x, lra.y, lra.z, lra.w, lrb.x, lrb.y, lrb.z, lrb.w};
;         float qc[16], kc[16];
; #pragma unroll
;         for (int ss = 0; ss < 16; ++ss) { const int i = d ? 63 - ss : ss; const bf16_t* pr = P + (size_t)(row0 + i * rstride) * PW + h * 64 + lane;
;             qc[ss] = __builtin_bit_cast(float, (unsigned)pr[1024]); kc[ss] = __builtin_bit_cast(float, (unsigned)pr[1280]); }
;         __builtin_amdgcn_sched_barrier(0);
; #pragma unroll
;         for (int ss = 0; ss < 16; ++ss) { qc[ss] = bf2f(__builtin_bit_cast(unsigned, qc[ss])); kc[ss] = bf2f(__builtin_bit_cast(unsigned, kc[ss])); }
;         unsigned wupp[8];
; #pragma unroll
;         for (int r2 = 0; r2 < 8; ++r2) wupp[r2] = pk2(p.gla_wup[(size_t)((l * 2 + d) * 16 + 2 * r2) * 256 + h * 64 + lane], p.gla_wup[(size_t)((l * 2 + d) * 16 + 2 * r2 + 1) * 256 + h * 64 + lane]);
;         const float bup = p.gla_bup[(l * 2 + d) * 256 + h * 64 + lane];
; #pragma unroll 1
;         for (int g2 = 0; g2 < 2; ++g2) {
;             unsigned vr[16];
; #pragma unroll
;             for (int ii = 0; ii < 16; ++ii) { const int i = 32 * sw + g2 * 16 + ii; vr[ii] = *(const unsigned*)(P + (size_t)(row0 + i * rstride) * PW + 1536 + h * 128 + 2 * lane); }
.LBB0_188:
	s_cmpk_lt_i32 s0, 0x820
	s_cselect_b64 s[12:13], -1, 0
	s_and_b64 s[4:5], s[4:5], exec
	s_cselect_b32 s41, s3, s1
	s_cselect_b32 s1, s30, s2
	s_lshl_b32 s42, s1, 3
	s_cmpk_gt_i32 s0, 0x81f
	s_cbranch_scc1 .LBB0_199
	v_readlane_b32 s52, v253, 55
	v_readlane_b32 s53, v253, 56
	s_and_b32 s1, s0, 3
	s_nop 3
	s_load_dwordx2 s[2:3], s[52:53], 0xc0
	s_load_dwordx4 s[4:7], s[52:53], 0x90
	v_readlane_b32 s30, v254, 5
	v_readlane_b32 s45, v254, 11
	s_and_b32 s46, s38, 1
	v_lshlrev_b32_e32 v134, 1, v64
	v_lshlrev_b32_e32 v135, 2, v64
	s_lshr_b32 s47, s45, 7
	s_mul_i32 s47, s47, 0x9200
	s_lshl_b32 s48, s30, 1
	s_add_i32 s48, s48, s46
	s_waitcnt lgkmcnt(0)
	v_mul_lo_u32 v86, v64, s44
	v_add_u32_e32 v86, s43, v86
	s_mov_b32 s49, 0x1600
	s_lshl_b32 s50, s46, 5
	s_add_i32 s50, s50, 0x1400
	s_add_u32 s52, s2, 0xbc00000
	s_addc_u32 s53, s3, 0
	v_mul_lo_u32 v88, v86, s49
	v_add_u32_e32 v88, s50, v88
	global_load_dwordx4 v[0:3], v88, s[52:53]
	global_load_dwordx4 v[4:7], v88, s[52:53] offset:16
	s_lshl_b32 s50, s48, 14
	s_lshl_b32 s51, s1, 8
	s_add_i32 s50, s50, s51
	s_add_u32 s4, s4, s50
	s_addc_u32 s5, s5, 0
	global_load_dword v90, v135, s[4:5]
	global_load_dword v91, v135, s[4:5] offset:1024
	global_load_dword v92, v135, s[4:5] offset:2048
	global_load_dword v93, v135, s[4:5] offset:3072
	s_add_u32 s4, s4, 0x1000
	s_addc_u32 s5, s5, 0
	global_load_dword v94, v135, s[4:5]
	global_load_dword v95, v135, s[4:5] offset:1024
	global_load_dword v96, v135, s[4:5] offset:2048
	global_load_dword v97, v135, s[4:5] offset:3072
	s_add_u32 s4, s4, 0x1000
	s_addc_u32 s5, s5, 0
	global_load_dword v98, v135, s[4:5]
	global_load_dword v99, v135, s[4:5] offset:1024
	global_load_dword v100, v135, s[4:5] offset:2048
	global_load_dword v101, v135, s[4:5] offset:3072
	s_add_u32 s4, s4, 0x1000
	s_addc_u32 s5, s5, 0
	global_load_dword v102, v135, s[4:5]
	global_load_dword v103, v135, s[4:5] offset:1024
	global_load_dword v104, v135, s[4:5] offset:2048
	global_load_dword v105, v135, s[4:5] offset:3072
	s_lshl_b32 s50, s48, 10
	s_add_i32 s50, s50, s51
	s_add_u32 s6, s6, s50
	s_addc_u32 s7, s7, 0
	global_load_dword v16, v135, s[6:7]
	s_mul_i32 s54, s44, 0x1600
	s_lshl_b32 s50, s46, 5
	s_mul_i32 s50, s50, s44
	s_add_i32 s50, s50, s43
	s_mul_hi_u32 s7, s50, 0x1600
	s_mul_i32 s6, s50, 0x1600
	s_add_u32 s6, s6, s52
	s_addc_u32 s7, s7, s53
	s_add_i32 s51, s51, 0xc00
	s_add_u32 s6, s6, s51
	s_addc_u32 s7, s7, 0
	global_load_dword v34, v135, s[6:7]
	s_add_u32 s6, s6, s54
	s_addc_u32 s7, s7, 0
	global_load_dword v35, v135, s[6:7]
	s_add_u32 s6, s6, s54
	s_addc_u32 s7, s7, 0
	global_load_dword v36, v135, s[6:7]
	s_add_u32 s6, s6, s54
	s_addc_u32 s7, s7, 0
	global_load_dword v37, v135, s[6:7]
	s_add_u32 s6, s6, s54
	s_addc_u32 s7, s7, 0
	global_load_dword v38, v135, s[6:7]
	s_add_u32 s6, s6, s54
	s_addc_u32 s7, s7, 0
	global_load_dword v39, v135, s[6:7]
	s_add_u32 s6, s6, s54
	s_addc_u32 s7, s7, 0
	global_load_dword v40, v135, s[6:7]
	s_add_u32 s6, s6, s54
	s_addc_u32 s7, s7, 0
	global_load_dword v41, v135, s[6:7]
	s_add_u32 s6, s6, s54
	s_addc_u32 s7, s7, 0
	global_load_dword v42, v135, s[6:7]
	s_add_u32 s6, s6, s54
	s_addc_u32 s7, s7, 0
	global_load_dword v43, v135, s[6:7]
	s_add_u32 s6, s6, s54
	s_addc_u32 s7, s7, 0
	global_load_dword v44, v135, s[6:7]
	s_add_u32 s6, s6, s54
	s_addc_u32 s7, s7, 0
	global_load_dword v45, v135, s[6:7]
	s_add_u32 s6, s6, s54
	s_addc_u32 s7, s7, 0
	global_load_dword v46, v135, s[6:7]
	s_add_u32 s6, s6, s54
	s_addc_u32 s7, s7, 0
	global_load_dword v47, v135, s[6:7]
	s_add_u32 s6, s6, s54
	s_addc_u32 s7, s7, 0
	global_load_dword v212, v135, s[6:7]
	s_add_u32 s6, s6, s54
	s_addc_u32 s7, s7, 0
	global_load_dword v213, v135, s[6:7]
	s_add_u32 s6, s6, s54
	s_addc_u32 s7, s7, 0
	global_load_dword v214, v135, s[6:7]
	s_add_u32 s6, s6, s54
	s_addc_u32 s7, s7, 0
	global_load_dword v215, v135, s[6:7]
	s_add_u32 s6, s6, s54
	s_addc_u32 s7, s7, 0
	global_load_dword v216, v135, s[6:7]
	s_add_u32 s6, s6, s54
	s_addc_u32 s7, s7, 0
	global_load_dword v217, v135, s[6:7]
	s_add_u32 s6, s6, s54
	s_addc_u32 s7, s7, 0
	global_load_dword v218, v135, s[6:7]
	s_add_u32 s6, s6, s54
	s_addc_u32 s7, s7, 0
	global_load_dword v219, v135, s[6:7]
	s_add_u32 s6, s6, s54
	s_addc_u32 s7, s7, 0
	global_load_dword v222, v135, s[6:7]
	s_add_u32 s6, s6, s54
	s_addc_u32 s7, s7, 0
	global_load_dword v223, v135, s[6:7]
	s_add_u32 s6, s6, s54
	s_addc_u32 s7, s7, 0
	global_load_dword v228, v135, s[6:7]
	s_add_u32 s6, s6, s54
	s_addc_u32 s7, s7, 0
	global_load_dword v229, v135, s[6:7]
	s_add_u32 s6, s6, s54
	s_addc_u32 s7, s7, 0
	global_load_dword v230, v135, s[6:7]
	s_add_u32 s6, s6, s54
	s_addc_u32 s7, s7, 0
	global_load_dword v231, v135, s[6:7]
	s_add_u32 s6, s6, s54
	s_addc_u32 s7, s7, 0
	global_load_dword v232, v135, s[6:7]
	s_add_u32 s6, s6, s54
	s_addc_u32 s7, s7, 0
	global_load_dword v233, v135, s[6:7]
	s_add_u32 s6, s6, s54
	s_addc_u32 s7, s7, 0
	global_load_dword v234, v135, s[6:7]
	s_add_u32 s6, s6, s54
	s_addc_u32 s7, s7, 0
	global_load_dword v235, v135, s[6:7]
	s_mul_i32 s50, s46, 63
	s_mov_b32 s30, s50
	s_mul_i32 s50, s50, s44
	s_add_i32 s50, s50, s43
	s_mul_hi_u32 s7, s50, 0x1600
	s_mul_i32 s6, s50, 0x1600
	s_add_u32 s6, s6, s52
	s_addc_u32 s7, s7, s53
	s_lshl_b32 s51, s1, 7
	s_add_i32 s45, s51, 0x800
	s_add_u32 s6, s6, s45
	s_addc_u32 s7, s7, 0
	s_lshl_b32 s45, s50, 11
	s_add_u32 s4, s2, 0x16f00000
	s_addc_u32 s5, s3, 0
	s_add_u32 s4, s4, s45
	s_addc_u32 s5, s5, 0
	s_lshl_b32 s45, s46, 10
	s_add_i32 s45, s45, s51
	s_add_u32 s4, s4, s45
	s_addc_u32 s5, s5, 0
	s_lshl_b32 s56, s44, 11
	s_mov_b32 s55, 0
	s_mov_b32 s3, 0
	s_mov_b32 s2, 1
	s_cmp_eq_u32 s46, 0
	s_cbranch_scc1 .Lgl1v_fwd
	s_sub_u32 s54, 0, s54
	s_subb_u32 s55, 0, 0
	s_sub_u32 s56, 0, s56
	s_subb_u32 s3, 0, 0
	s_mov_b32 s2, -1
; __device__ __forceinline__ unsigned pk2(float lo, float hi) { unsigned r; asm("v_cvt_pk_bf16_f32 %0, %1, %2" : "=v"(r) : "v"(lo), "v"(hi)); return r; }
; __device__ __forceinline__ void gl1_item(PREF p, int l, int item, bool valid, LAS unsigned char* pl, int sw, int lane) {
;     ...
;         unsigned wupp[8];
; #pragma unroll
;         for (int r2 = 0; r2 < 8; ++r2) wupp[r2] = pk2(p.gla_wup[(size_t)((l * 2 + d) * 16 + 2 * r2) * 256 + h * 64 + lane], p.gla_wup[(size_t)((l * 2 + d) * 16 + 2 * r2 + 1) * 256 + h * 64 + lane]);
;         const float bup = p.gla_bup[(l * 2 + d) * 256 + h * 64 + lane];
; #pragma unroll 1
;         for (int g2 = 0; g2 < 2; ++g2) {
;             unsigned vr[16];
; #pragma unroll
;             for (int ii = 0; ii < 16; ++ii) { const int i = 32 * sw + g2 * 16 + ii; vr[ii] = *(const unsigned*)(P + (size_t)(row0 + i * rstride) * PW + 1536 + h * 128 + 2 * lane); }
; #pragma unroll
;             for (int ii = 0; ii < 16; ++ii) { const int i = 32 * sw + g2 * 16 + ii; sVt[(2 * lane) * 72 + i] = (bf16_t)(vr[ii] & 0xffffu); sVt[(2 * lane + 1) * 72 + i] = (bf16_t)(vr[ii] >> 16); }
;         }
;         float bc = 0.f;
; #pragma unroll 1
;         for (int g4 = 0; g4 < 4; ++g4) {
;             float qn[16], kn[16];
;             if (g4 < 3) {
; #pragma unroll
;                 for (int ss = 0; ss < 16; ++ss) { const int s = (g4 + 1) * 16 + ss; const int i = d ? 63 - s : s; const bf16_t* pr = P + (size_t)(row0 + i * rstride) * PW + h * 64 + lane;
;                     qn[ss] = __builtin_bit_cast(float, (unsigned)pr[1024]); kn[ss] = __builtin_bit_cast(float, (unsigned)pr[1280]); }
;                 __builtin_amdgcn_sched_barrier(0);
;             }
;             float gv[16];
; #pragma unroll
;             for (int ss = 0; ss < 16; ++ss) { const int s = g4 * 16 + ss; const int i = d ? 63 - s : s;
;                 float z = bup;
; #pragma unroll
;                 for (int r2 = 0; r2 < 8; ++r2) { const unsigned w = (unsigned)__builtin_amdgcn_readlane((int)lrp[r2], i);
;                     z = __builtin_amdgcn_fdot2_f32_bf16(__builtin_bit_cast(bf16x2_t, w), __builtin_bit_cast(bf16x2_t, wupp[r2]), z, false); }
.Lgl1v_fwd:
	s_mul_i32 s45, s46, 0x2400
	s_add_i32 s45, s45, s47
	s_add_i32 s45, s45, 0x4800
	s_lshl_b32 s50, s30, 1
	s_add_i32 s45, s45, s50
	s_movk_i32 s50, 0x90
	v_mul_u32_u24_e32 v60, 0x90, v64
	v_add_u32_e32 v60, s45, v60
	s_lshl_b32 s50, s2, 1
	v_mov_b32_e32 v61, s50
	s_waitcnt vmcnt(32)
	v_cvt_pk_bf16_f32 v8, v90, v91
	v_cvt_pk_bf16_f32 v9, v92, v93
	v_cvt_pk_bf16_f32 v10, v94, v95
	v_cvt_pk_bf16_f32 v11, v96, v97
	v_cvt_pk_bf16_f32 v12, v98, v99
	v_cvt_pk_bf16_f32 v13, v100, v101
	v_cvt_pk_bf16_f32 v14, v102, v103
	v_cvt_pk_bf16_f32 v15, v104, v105
	s_waitcnt vmcnt(0)
	v_mul_u32_u24_e32 v86, 0x120, v64
	s_lshl_b32 s45, s46, 6
	s_add_i32 s45, s45, s47
	v_add_u32_e32 v86, s45, v86
	ds_write_b16 v86, v34 offset:0
	ds_write_b16_d16_hi v86, v34 offset:144
	ds_write_b16 v86, v35 offset:2
	ds_write_b16_d16_hi v86, v35 offset:146
	ds_write_b16 v86, v36 offset:4
	ds_write_b16_d16_hi v86, v36 offset:148
	ds_write_b16 v86, v37 offset:6
	ds_write_b16_d16_hi v86, v37 offset:150
	ds_write_b16 v86, v38 offset:8
	ds_write_b16_d16_hi v86, v38 offset:152
	ds_write_b16 v86, v39 offset:10
	ds_write_b16_d16_hi v86, v39 offset:154
	ds_write_b16 v86, v40 offset:12
	ds_write_b16_d16_hi v86, v40 offset:156
	ds_write_b16 v86, v41 offset:14
	ds_write_b16_d16_hi v86, v41 offset:158
	ds_write_b16 v86, v42 offset:16
	ds_write_b16_d16_hi v86, v42 offset:160
	ds_write_b16 v86, v43 offset:18
	ds_write_b16_d16_hi v86, v43 offset:162
	ds_write_b16 v86, v44 offset:20
	ds_write_b16_d16_hi v86, v44 offset:164
	ds_write_b16 v86, v45 offset:22
	ds_write_b16_d16_hi v86, v45 offset:166
	ds_write_b16 v86, v46 offset:24
	ds_write_b16_d16_hi v86, v46 offset:168
	ds_write_b16 v86, v47 offset:26
	ds_write_b16_d16_hi v86, v47 offset:170
	ds_write_b16 v86, v212 offset:28
	ds_write_b16_d16_hi v86, v212 offset:172
	ds_write_b16 v86, v213 offset:30
	ds_write_b16_d16_hi v86, v213 offset:174
	ds_write_b16 v86, v214 offset:32
	ds_write_b16_d16_hi v86, v214 offset:176
	ds_write_b16 v86, v215 offset:34
	ds_write_b16_d16_hi v86, v215 offset:178
	ds_write_b16 v86, v216 offset:36
	ds_write_b16_d16_hi v86, v216 offset:180
	ds_write_b16 v86, v217 offset:38
	ds_write_b16_d16_hi v86, v217 offset:182
	ds_write_b16 v86, v218 offset:40
	ds_write_b16_d16_hi v86, v218 offset:184
	ds_write_b16 v86, v219 offset:42
	ds_write_b16_d16_hi v86, v219 offset:186
	ds_write_b16 v86, v222 offset:44
	ds_write_b16_d16_hi v86, v222 offset:188
	ds_write_b16 v86, v223 offset:46
	ds_write_b16_d16_hi v86, v223 offset:190
	ds_write_b16 v86, v228 offset:48
	ds_write_b16_d16_hi v86, v228 offset:192
	ds_write_b16 v86, v229 offset:50
	ds_write_b16_d16_hi v86, v229 offset:194
	ds_write_b16 v86, v230 offset:52
	ds_write_b16_d16_hi v86, v230 offset:196
	ds_write_b16 v86, v231 offset:54
	ds_write_b16_d16_hi v86, v231 offset:198
	ds_write_b16 v86, v232 offset:56
	ds_write_b16_d16_hi v86, v232 offset:200
	ds_write_b16 v86, v233 offset:58
	ds_write_b16_d16_hi v86, v233 offset:202
	ds_write_b16 v86, v234 offset:60
	ds_write_b16_d16_hi v86, v234 offset:204
	ds_write_b16 v86, v235 offset:62
	ds_write_b16_d16_hi v86, v235 offset:206
	global_load_ushort v148, v134, s[6:7]
	global_load_ushort v164, v134, s[6:7] offset:512
	s_add_u32 s6, s6, s54
	s_addc_u32 s7, s7, s55
	global_load_ushort v149, v134, s[6:7]
	global_load_ushort v165, v134, s[6:7] offset:512
	s_add_u32 s6, s6, s54
	s_addc_u32 s7, s7, s55
	global_load_ushort v150, v134, s[6:7]
	global_load_ushort v166, v134, s[6:7] offset:512
	s_add_u32 s6, s6, s54
	s_addc_u32 s7, s7, s55
	global_load_ushort v151, v134, s[6:7]
	global_load_ushort v167, v134, s[6:7] offset:512
	s_add_u32 s6, s6, s54
	s_addc_u32 s7, s7, s55
	global_load_ushort v152, v134, s[6:7]
	global_load_ushort v168, v134, s[6:7] offset:512
	s_add_u32 s6, s6, s54
	s_addc_u32 s7, s7, s55
	global_load_ushort v153, v134, s[6:7]
	global_load_ushort v169, v134, s[6:7] offset:512
	s_add_u32 s6, s6, s54
	s_addc_u32 s7, s7, s55
	global_load_ushort v154, v134, s[6:7]
	global_load_ushort v170, v134, s[6:7] offset:512
	s_add_u32 s6, s6, s54
	s_addc_u32 s7, s7, s55
	global_load_ushort v155, v134, s[6:7]
	global_load_ushort v171, v134, s[6:7] offset:512
	s_add_u32 s6, s6, s54
	s_addc_u32 s7, s7, s55
	global_load_ushort v156, v134, s[6:7]
	global_load_ushort v172, v134, s[6:7] offset:512
	s_add_u32 s6, s6, s54
	s_addc_u32 s7, s7, s55
	global_load_ushort v157, v134, s[6:7]
	global_load_ushort v173, v134, s[6:7] offset:512
	s_add_u32 s6, s6, s54
	s_addc_u32 s7, s7, s55
	global_load_ushort v158, v134, s[6:7]
	global_load_ushort v174, v134, s[6:7] offset:512
	s_add_u32 s6, s6, s54
	s_addc_u32 s7, s7, s55
	global_load_ushort v159, v134, s[6:7]
	global_load_ushort v175, v134, s[6:7] offset:512
	s_add_u32 s6, s6, s54
	s_addc_u32 s7, s7, s55
	global_load_ushort v160, v134, s[6:7]
	global_load_ushort v176, v134, s[6:7] offset:512
	s_add_u32 s6, s6, s54
	s_addc_u32 s7, s7, s55
	global_load_ushort v161, v134, s[6:7]
	global_load_ushort v177, v134, s[6:7] offset:512
	s_add_u32 s6, s6, s54
	s_addc_u32 s7, s7, s55
	global_load_ushort v162, v134, s[6:7]
	global_load_ushort v178, v134, s[6:7] offset:512
	s_add_u32 s6, s6, s54
	s_addc_u32 s7, s7, s55
	global_load_ushort v163, v134, s[6:7]
	global_load_ushort v179, v134, s[6:7] offset:512
	s_add_u32 s6, s6, s54
	s_addc_u32 s7, s7, s55
	v_mov_b32_e32 v17, 0
	s_mov_b32 s1, 0xbfb8aa3b
	v_mov_b32_e32 v236, v16
	v_readlane_b32 s45, v0, s30
	v_readlane_b32 s46, v1, s30
	v_readlane_b32 s47, v2, s30
	v_readlane_b32 s48, v3, s30
	v_readlane_b32 s49, v4, s30
	v_readlane_b32 s50, v5, s30
	v_readlane_b32 s51, v6, s30
	v_readlane_b32 s52, v7, s30
	s_add_i32 s30, s30, s2
	v_dot2c_f32_bf16_e32 v236, s45, v8
; __device__ __forceinline__ void gl1_item(PREF p, int l, int item, bool valid, LAS unsigned char* pl, int sw, int lane) {
;     ...
;             for (int ss = 0; ss < 16; ++ss) { const int s = g4 * 16 + ss; const int i = d ? 63 - s : s;
;                 float z = bup;
; #pragma unroll
;                 for (int r2 = 0; r2 < 8; ++r2) { const unsigned w = (unsigned)__builtin_amdgcn_readlane((int)lrp[r2], i);
;                     z = __builtin_amdgcn_fdot2_f32_bf16(__builtin_bit_cast(bf16x2_t, w), __builtin_bit_cast(bf16x2_t, wupp[r2]), z, false); }
	v_dot2c_f32_bf16_e32 v236, s46, v9
	v_dot2c_f32_bf16_e32 v236, s47, v10
	v_dot2c_f32_bf16_e32 v236, s48, v11
	v_dot2c_f32_bf16_e32 v236, s49, v12
	v_dot2c_f32_bf16_e32 v236, s50, v13
	v_dot2c_f32_bf16_e32 v236, s51, v14
	v_dot2c_f32_bf16_e32 v236, s52, v15
	v_mov_b32_e32 v237, v16
	v_readlane_b32 s45, v0, s30
	v_readlane_b32 s46, v1, s30
	v_readlane_b32 s47, v2, s30
	v_readlane_b32 s48, v3, s30
	v_readlane_b32 s49, v4, s30
	v_readlane_b32 s50, v5, s30
	v_readlane_b32 s51, v6, s30
	v_readlane_b32 s52, v7, s30
	s_add_i32 s30, s30, s2
	v_dot2c_f32_bf16_e32 v237, s45, v8
	v_dot2c_f32_bf16_e32 v237, s46, v9
	v_dot2c_f32_bf16_e32 v237, s47, v10
	v_dot2c_f32_bf16_e32 v237, s48, v11
	v_dot2c_f32_bf16_e32 v237, s49, v12
	v_dot2c_f32_bf16_e32 v237, s50, v13
	v_dot2c_f32_bf16_e32 v237, s51, v14
	v_dot2c_f32_bf16_e32 v237, s52, v15
	v_mov_b32_e32 v238, v16
	v_readlane_b32 s45, v0, s30
	v_readlane_b32 s46, v1, s30
	v_readlane_b32 s47, v2, s30
	v_readlane_b32 s48, v3, s30
	v_readlane_b32 s49, v4, s30
	v_readlane_b32 s50, v5, s30
	v_readlane_b32 s51, v6, s30
	v_readlane_b32 s52, v7, s30
	s_add_i32 s30, s30, s2
	v_dot2c_f32_bf16_e32 v238, s45, v8
	v_dot2c_f32_bf16_e32 v238, s46, v9
	v_dot2c_f32_bf16_e32 v238, s47, v10
	v_dot2c_f32_bf16_e32 v238, s48, v11
	v_dot2c_f32_bf16_e32 v238, s49, v12
	v_dot2c_f32_bf16_e32 v238, s50, v13
	v_dot2c_f32_bf16_e32 v238, s51, v14
	v_dot2c_f32_bf16_e32 v238, s52, v15
	v_mov_b32_e32 v239, v16
	v_readlane_b32 s45, v0, s30
	v_readlane_b32 s46, v1, s30
	v_readlane_b32 s47, v2, s30
	v_readlane_b32 s48, v3, s30
	v_readlane_b32 s49, v4, s30
	v_readlane_b32 s50, v5, s30
	v_readlane_b32 s51, v6, s30
	v_readlane_b32 s52, v7, s30
	s_add_i32 s30, s30, s2
	v_dot2c_f32_bf16_e32 v239, s45, v8
	v_dot2c_f32_bf16_e32 v239, s46, v9
	v_dot2c_f32_bf16_e32 v239, s47, v10
	v_dot2c_f32_bf16_e32 v239, s48, v11
	v_dot2c_f32_bf16_e32 v239, s49, v12
	v_dot2c_f32_bf16_e32 v239, s50, v13
	v_dot2c_f32_bf16_e32 v239, s51, v14
	v_dot2c_f32_bf16_e32 v239, s52, v15
	v_mov_b32_e32 v240, v16
	v_readlane_b32 s45, v0, s30
	v_readlane_b32 s46, v1, s30
	v_readlane_b32 s47, v2, s30
	v_readlane_b32 s48, v3, s30
	v_readlane_b32 s49, v4, s30
	v_readlane_b32 s50, v5, s30
	v_readlane_b32 s51, v6, s30
	v_readlane_b32 s52, v7, s30
	s_add_i32 s30, s30, s2
	v_dot2c_f32_bf16_e32 v240, s45, v8
	v_dot2c_f32_bf16_e32 v240, s46, v9
	v_dot2c_f32_bf16_e32 v240, s47, v10
	v_dot2c_f32_bf16_e32 v240, s48, v11
	v_dot2c_f32_bf16_e32 v240, s49, v12
	v_dot2c_f32_bf16_e32 v240, s50, v13
	v_dot2c_f32_bf16_e32 v240, s51, v14
	v_dot2c_f32_bf16_e32 v240, s52, v15
	v_mov_b32_e32 v241, v16
	v_readlane_b32 s45, v0, s30
	v_readlane_b32 s46, v1, s30
	v_readlane_b32 s47, v2, s30
	v_readlane_b32 s48, v3, s30
	v_readlane_b32 s49, v4, s30
	v_readlane_b32 s50, v5, s30
	v_readlane_b32 s51, v6, s30
	v_readlane_b32 s52, v7, s30
	s_add_i32 s30, s30, s2
	v_dot2c_f32_bf16_e32 v241, s45, v8
	v_dot2c_f32_bf16_e32 v241, s46, v9
	v_dot2c_f32_bf16_e32 v241, s47, v10
	v_dot2c_f32_bf16_e32 v241, s48, v11
	v_dot2c_f32_bf16_e32 v241, s49, v12
	v_dot2c_f32_bf16_e32 v241, s50, v13
	v_dot2c_f32_bf16_e32 v241, s51, v14
	v_dot2c_f32_bf16_e32 v241, s52, v15
	v_mov_b32_e32 v242, v16
	v_readlane_b32 s45, v0, s30
	v_readlane_b32 s46, v1, s30
	v_readlane_b32 s47, v2, s30
	v_readlane_b32 s48, v3, s30
	v_readlane_b32 s49, v4, s30
	v_readlane_b32 s50, v5, s30
	v_readlane_b32 s51, v6, s30
	v_readlane_b32 s52, v7, s30
	s_add_i32 s30, s30, s2
	v_dot2c_f32_bf16_e32 v242, s45, v8
	v_dot2c_f32_bf16_e32 v242, s46, v9
	v_dot2c_f32_bf16_e32 v242, s47, v10
	v_dot2c_f32_bf16_e32 v242, s48, v11
	v_dot2c_f32_bf16_e32 v242, s49, v12
	v_dot2c_f32_bf16_e32 v242, s50, v13
	v_dot2c_f32_bf16_e32 v242, s51, v14
	v_dot2c_f32_bf16_e32 v242, s52, v15
	v_mov_b32_e32 v243, v16
	v_readlane_b32 s45, v0, s30
	v_readlane_b32 s46, v1, s30
	v_readlane_b32 s47, v2, s30
	v_readlane_b32 s48, v3, s30
	v_readlane_b32 s49, v4, s30
	v_readlane_b32 s50, v5, s30
	v_readlane_b32 s51, v6, s30
	v_readlane_b32 s52, v7, s30
	s_add_i32 s30, s30, s2
	v_dot2c_f32_bf16_e32 v243, s45, v8
	v_dot2c_f32_bf16_e32 v243, s46, v9
	v_dot2c_f32_bf16_e32 v243, s47, v10
	v_dot2c_f32_bf16_e32 v243, s48, v11
	v_dot2c_f32_bf16_e32 v243, s49, v12
	v_dot2c_f32_bf16_e32 v243, s50, v13
	v_dot2c_f32_bf16_e32 v243, s51, v14
	v_dot2c_f32_bf16_e32 v243, s52, v15
	v_mov_b32_e32 v244, v16
	v_readlane_b32 s45, v0, s30
	v_readlane_b32 s46, v1, s30
	v_readlane_b32 s47, v2, s30
	v_readlane_b32 s48, v3, s30
	v_readlane_b32 s49, v4, s30
	v_readlane_b32 s50, v5, s30
	v_readlane_b32 s51, v6, s30
	v_readlane_b32 s52, v7, s30
	s_add_i32 s30, s30, s2
	v_dot2c_f32_bf16_e32 v244, s45, v8
	v_dot2c_f32_bf16_e32 v244, s46, v9
	v_dot2c_f32_bf16_e32 v244, s47, v10
	v_dot2c_f32_bf16_e32 v244, s48, v11
	v_dot2c_f32_bf16_e32 v244, s49, v12
	v_dot2c_f32_bf16_e32 v244, s50, v13
	v_dot2c_f32_bf16_e32 v244, s51, v14
	v_dot2c_f32_bf16_e32 v244, s52, v15
	v_mov_b32_e32 v245, v16
	v_readlane_b32 s45, v0, s30
	v_readlane_b32 s46, v1, s30
	v_readlane_b32 s47, v2, s30
	v_readlane_b32 s48, v3, s30
	v_readlane_b32 s49, v4, s30
	v_readlane_b32 s50, v5, s30
	v_readlane_b32 s51, v6, s30
	v_readlane_b32 s52, v7, s30
	s_add_i32 s30, s30, s2
	v_dot2c_f32_bf16_e32 v245, s45, v8
	v_dot2c_f32_bf16_e32 v245, s46, v9
	v_dot2c_f32_bf16_e32 v245, s47, v10
	v_dot2c_f32_bf16_e32 v245, s48, v11
	v_dot2c_f32_bf16_e32 v245, s49, v12
	v_dot2c_f32_bf16_e32 v245, s50, v13
	v_dot2c_f32_bf16_e32 v245, s51, v14
	v_dot2c_f32_bf16_e32 v245, s52, v15
	v_mov_b32_e32 v246, v16
	v_readlane_b32 s45, v0, s30
	v_readlane_b32 s46, v1, s30
	v_readlane_b32 s47, v2, s30
	v_readlane_b32 s48, v3, s30
	v_readlane_b32 s49, v4, s30
	v_readlane_b32 s50, v5, s30
; __device__ __forceinline__ void gl1_item(PREF p, int l, int item, bool valid, LAS unsigned char* pl, int sw, int lane) {
;     ...
;             for (int ss = 0; ss < 16; ++ss) { const int s = g4 * 16 + ss; const int i = d ? 63 - s : s;
;                 float z = bup;
; #pragma unroll
;                 for (int r2 = 0; r2 < 8; ++r2) { const unsigned w = (unsigned)__builtin_amdgcn_readlane((int)lrp[r2], i);
;                     z = __builtin_amdgcn_fdot2_f32_bf16(__builtin_bit_cast(bf16x2_t, w), __builtin_bit_cast(bf16x2_t, wupp[r2]), z, false); }
;                 gv[ss] = -(fmaxf(-z, 0.f) + __logf(1.f + __expf(-fabsf(z)))) * (1.f / 16.f);
	v_readlane_b32 s51, v6, s30
	v_readlane_b32 s52, v7, s30
	s_add_i32 s30, s30, s2
	v_dot2c_f32_bf16_e32 v246, s45, v8
	v_dot2c_f32_bf16_e32 v246, s46, v9
	v_dot2c_f32_bf16_e32 v246, s47, v10
	v_dot2c_f32_bf16_e32 v246, s48, v11
	v_dot2c_f32_bf16_e32 v246, s49, v12
	v_dot2c_f32_bf16_e32 v246, s50, v13
	v_dot2c_f32_bf16_e32 v246, s51, v14
	v_dot2c_f32_bf16_e32 v246, s52, v15
	v_mov_b32_e32 v247, v16
	v_readlane_b32 s45, v0, s30
	v_readlane_b32 s46, v1, s30
	v_readlane_b32 s47, v2, s30
	v_readlane_b32 s48, v3, s30
	v_readlane_b32 s49, v4, s30
	v_readlane_b32 s50, v5, s30
	v_readlane_b32 s51, v6, s30
	v_readlane_b32 s52, v7, s30
	s_add_i32 s30, s30, s2
	v_dot2c_f32_bf16_e32 v247, s45, v8
	v_dot2c_f32_bf16_e32 v247, s46, v9
	v_dot2c_f32_bf16_e32 v247, s47, v10
	v_dot2c_f32_bf16_e32 v247, s48, v11
	v_dot2c_f32_bf16_e32 v247, s49, v12
	v_dot2c_f32_bf16_e32 v247, s50, v13
	v_dot2c_f32_bf16_e32 v247, s51, v14
	v_dot2c_f32_bf16_e32 v247, s52, v15
	v_mov_b32_e32 v248, v16
	v_readlane_b32 s45, v0, s30
	v_readlane_b32 s46, v1, s30
	v_readlane_b32 s47, v2, s30
	v_readlane_b32 s48, v3, s30
	v_readlane_b32 s49, v4, s30
	v_readlane_b32 s50, v5, s30
	v_readlane_b32 s51, v6, s30
	v_readlane_b32 s52, v7, s30
	s_add_i32 s30, s30, s2
	v_dot2c_f32_bf16_e32 v248, s45, v8
	v_dot2c_f32_bf16_e32 v248, s46, v9
	v_dot2c_f32_bf16_e32 v248, s47, v10
	v_dot2c_f32_bf16_e32 v248, s48, v11
	v_dot2c_f32_bf16_e32 v248, s49, v12
	v_dot2c_f32_bf16_e32 v248, s50, v13
	v_dot2c_f32_bf16_e32 v248, s51, v14
	v_dot2c_f32_bf16_e32 v248, s52, v15
	v_mov_b32_e32 v249, v16
	v_readlane_b32 s45, v0, s30
	v_readlane_b32 s46, v1, s30
	v_readlane_b32 s47, v2, s30
	v_readlane_b32 s48, v3, s30
	v_readlane_b32 s49, v4, s30
	v_readlane_b32 s50, v5, s30
	v_readlane_b32 s51, v6, s30
	v_readlane_b32 s52, v7, s30
	s_add_i32 s30, s30, s2
	v_dot2c_f32_bf16_e32 v249, s45, v8
	v_dot2c_f32_bf16_e32 v249, s46, v9
	v_dot2c_f32_bf16_e32 v249, s47, v10
	v_dot2c_f32_bf16_e32 v249, s48, v11
	v_dot2c_f32_bf16_e32 v249, s49, v12
	v_dot2c_f32_bf16_e32 v249, s50, v13
	v_dot2c_f32_bf16_e32 v249, s51, v14
	v_dot2c_f32_bf16_e32 v249, s52, v15
	v_mov_b32_e32 v250, v16
	v_readlane_b32 s45, v0, s30
	v_readlane_b32 s46, v1, s30
	v_readlane_b32 s47, v2, s30
	v_readlane_b32 s48, v3, s30
	v_readlane_b32 s49, v4, s30
	v_readlane_b32 s50, v5, s30
	v_readlane_b32 s51, v6, s30
	v_readlane_b32 s52, v7, s30
	s_add_i32 s30, s30, s2
	v_dot2c_f32_bf16_e32 v250, s45, v8
	v_dot2c_f32_bf16_e32 v250, s46, v9
	v_dot2c_f32_bf16_e32 v250, s47, v10
	v_dot2c_f32_bf16_e32 v250, s48, v11
	v_dot2c_f32_bf16_e32 v250, s49, v12
	v_dot2c_f32_bf16_e32 v250, s50, v13
	v_dot2c_f32_bf16_e32 v250, s51, v14
	v_dot2c_f32_bf16_e32 v250, s52, v15
	v_mov_b32_e32 v251, v16
	v_readlane_b32 s45, v0, s30
	v_readlane_b32 s46, v1, s30
	v_readlane_b32 s47, v2, s30
	v_readlane_b32 s48, v3, s30
	v_readlane_b32 s49, v4, s30
	v_readlane_b32 s50, v5, s30
	v_readlane_b32 s51, v6, s30
	v_readlane_b32 s52, v7, s30
	s_add_i32 s30, s30, s2
	v_dot2c_f32_bf16_e32 v251, s45, v8
	v_dot2c_f32_bf16_e32 v251, s46, v9
	v_dot2c_f32_bf16_e32 v251, s47, v10
	v_dot2c_f32_bf16_e32 v251, s48, v11
	v_dot2c_f32_bf16_e32 v251, s49, v12
	v_dot2c_f32_bf16_e32 v251, s50, v13
	v_dot2c_f32_bf16_e32 v251, s51, v14
	v_dot2c_f32_bf16_e32 v251, s52, v15
	s_nop 2
	v_mul_f32_e64 v18, |v236|, s1
	v_mul_f32_e64 v19, |v237|, s1
	v_mul_f32_e64 v20, |v238|, s1
	v_mul_f32_e64 v21, |v239|, s1
	v_mul_f32_e64 v22, |v240|, s1
	v_mul_f32_e64 v23, |v241|, s1
	v_mul_f32_e64 v24, |v242|, s1
	v_mul_f32_e64 v25, |v243|, s1
	v_mul_f32_e64 v26, |v244|, s1
	v_mul_f32_e64 v27, |v245|, s1
	v_mul_f32_e64 v28, |v246|, s1
	v_mul_f32_e64 v29, |v247|, s1
	v_mul_f32_e64 v30, |v248|, s1
	v_mul_f32_e64 v31, |v249|, s1
	v_mul_f32_e64 v32, |v250|, s1
	v_mul_f32_e64 v33, |v251|, s1
	v_exp_f32_e32 v18, v18
	v_exp_f32_e32 v19, v19
	v_exp_f32_e32 v20, v20
	v_exp_f32_e32 v21, v21
	v_exp_f32_e32 v22, v22
	v_exp_f32_e32 v23, v23
	v_exp_f32_e32 v24, v24
	v_exp_f32_e32 v25, v25
	v_exp_f32_e32 v26, v26
	v_exp_f32_e32 v27, v27
	v_exp_f32_e32 v28, v28
	v_exp_f32_e32 v29, v29
	v_exp_f32_e32 v30, v30
	v_exp_f32_e32 v31, v31
	v_exp_f32_e32 v32, v32
	v_exp_f32_e32 v33, v33
	v_max_f32_e64 v236, -v236, -v236
	v_max_f32_e64 v237, -v237, -v237
	v_max_f32_e64 v238, -v238, -v238
	v_max_f32_e64 v239, -v239, -v239
	v_max_f32_e64 v240, -v240, -v240
	v_max_f32_e64 v241, -v241, -v241
	v_max_f32_e64 v242, -v242, -v242
	v_max_f32_e64 v243, -v243, -v243
	v_max_f32_e64 v244, -v244, -v244
	v_max_f32_e64 v245, -v245, -v245
	v_max_f32_e64 v246, -v246, -v246
	v_max_f32_e64 v247, -v247, -v247
	v_max_f32_e64 v248, -v248, -v248
	v_max_f32_e64 v249, -v249, -v249
	v_max_f32_e64 v250, -v250, -v250
	v_max_f32_e64 v251, -v251, -v251
	v_max_f32_e32 v236, 0, v236
	v_max_f32_e32 v237, 0, v237
	v_max_f32_e32 v238, 0, v238
	v_max_f32_e32 v239, 0, v239
	v_max_f32_e32 v240, 0, v240
	v_max_f32_e32 v241, 0, v241
	v_max_f32_e32 v242, 0, v242
	v_max_f32_e32 v243, 0, v243
	v_max_f32_e32 v244, 0, v244
	v_max_f32_e32 v245, 0, v245
	v_max_f32_e32 v246, 0, v246
	v_max_f32_e32 v247, 0, v247
	v_max_f32_e32 v248, 0, v248
	v_max_f32_e32 v249, 0, v249
	v_max_f32_e32 v250, 0, v250
	v_max_f32_e32 v251, 0, v251
	v_add_f32_e32 v18, 1.0, v18
	v_add_f32_e32 v19, 1.0, v19
	v_add_f32_e32 v20, 1.0, v20
	v_add_f32_e32 v21, 1.0, v21
	v_add_f32_e32 v22, 1.0, v22
	v_add_f32_e32 v23, 1.0, v23
	v_add_f32_e32 v24, 1.0, v24
	v_add_f32_e32 v25, 1.0, v25
	v_add_f32_e32 v26, 1.0, v26
	v_add_f32_e32 v27, 1.0, v27
	v_add_f32_e32 v28, 1.0, v28
	v_add_f32_e32 v29, 1.0, v29
	v_add_f32_e32 v30, 1.0, v30
	v_add_f32_e32 v31, 1.0, v31
	v_add_f32_e32 v32, 1.0, v32
	v_add_f32_e32 v33, 1.0, v33
	v_log_f32_e32 v18, v18
; __device__ __forceinline__ void gl1_item(PREF p, int l, int item, bool valid, LAS unsigned char* pl, int sw, int lane) {
;     ...
;                 for (int ss = 0; ss < 16; ++ss) { const int s = (g4 + 1) * 16 + ss; const int i = d ? 63 - s : s; const bf16_t* pr = P + (size_t)(row0 + i * rstride) * PW + h * 64 + lane;
;                     qn[ss] = __builtin_bit_cast(float, (unsigned)pr[1024]); kn[ss] = __builtin_bit_cast(float, (unsigned)pr[1280]); }
;                 __builtin_amdgcn_sched_barrier(0);
;             }
;             float gv[16];
; #pragma unroll
;             for (int ss = 0; ss < 16; ++ss) { const int s = g4 * 16 + ss; const int i = d ? 63 - s : s;
;                 float z = bup;
; #pragma unroll
;                 for (int r2 = 0; r2 < 8; ++r2) { const unsigned w = (unsigned)__builtin_amdgcn_readlane((int)lrp[r2], i);
;                     z = __builtin_amdgcn_fdot2_f32_bf16(__builtin_bit_cast(bf16x2_t, w), __builtin_bit_cast(bf16x2_t, wupp[r2]), z, false); }
;                 gv[ss] = -(fmaxf(-z, 0.f) + __logf(1.f + __expf(-fabsf(z)))) * (1.f / 16.f);
;                 __builtin_amdgcn_sched_barrier(0);
;             }
; #pragma unroll
;             for (int ss = 0; ss < 16; ++ss) { const int s = g4 * 16 + ss; const int i = d ? 63 - s : s; const size_t rowi = (size_t)(row0 + i * rstride);
;                 bc += gv[ss];
;                 const float en = __expf(-bc), ep = __expf(bc);
;                 const float kt = kc[ss] * en, qt = qc[ss] * 0.125f * ep;
	v_log_f32_e32 v19, v19
	v_log_f32_e32 v20, v20
	v_log_f32_e32 v21, v21
	v_log_f32_e32 v22, v22
	v_log_f32_e32 v23, v23
	v_log_f32_e32 v24, v24
	v_log_f32_e32 v25, v25
	v_log_f32_e32 v26, v26
	v_log_f32_e32 v27, v27
	v_log_f32_e32 v28, v28
	v_log_f32_e32 v29, v29
	v_log_f32_e32 v30, v30
	v_log_f32_e32 v31, v31
	v_log_f32_e32 v32, v32
	v_log_f32_e32 v33, v33
	s_mov_b32 s45, 0x3f317217
	v_mul_f32_e32 v70, 0x3f317217, v18
	v_mul_f32_e32 v71, 0x3f317217, v19
	v_mul_f32_e32 v72, 0x3f317217, v20
	v_mul_f32_e32 v73, 0x3f317217, v21
	v_mul_f32_e32 v74, 0x3f317217, v22
	v_mul_f32_e32 v75, 0x3f317217, v23
	v_mul_f32_e32 v76, 0x3f317217, v24
	v_mul_f32_e32 v77, 0x3f317217, v25
	v_mul_f32_e32 v78, 0x3f317217, v26
	v_mul_f32_e32 v79, 0x3f317217, v27
	v_mul_f32_e32 v80, 0x3f317217, v28
	v_mul_f32_e32 v81, 0x3f317217, v29
	v_mul_f32_e32 v82, 0x3f317217, v30
	v_mul_f32_e32 v83, 0x3f317217, v31
	v_mul_f32_e32 v84, 0x3f317217, v32
	v_mul_f32_e32 v85, 0x3f317217, v33
	v_fma_f32 v70, v18, s45, -v70
	v_fma_f32 v71, v19, s45, -v71
	v_fma_f32 v72, v20, s45, -v72
	v_fma_f32 v73, v21, s45, -v73
	v_fma_f32 v74, v22, s45, -v74
	v_fma_f32 v75, v23, s45, -v75
	v_fma_f32 v76, v24, s45, -v76
	v_fma_f32 v77, v25, s45, -v77
	v_fma_f32 v78, v26, s45, -v78
	v_fma_f32 v79, v27, s45, -v79
	v_fma_f32 v80, v28, s45, -v80
	v_fma_f32 v81, v29, s45, -v81
	v_fma_f32 v82, v30, s45, -v82
	v_fma_f32 v83, v31, s45, -v83
	v_fma_f32 v84, v32, s45, -v84
	v_fma_f32 v85, v33, s45, -v85
	v_fmac_f32_e32 v70, 0x3377d1cf, v18
	v_fmac_f32_e32 v71, 0x3377d1cf, v19
	v_fmac_f32_e32 v72, 0x3377d1cf, v20
	v_fmac_f32_e32 v73, 0x3377d1cf, v21
	v_fmac_f32_e32 v74, 0x3377d1cf, v22
	v_fmac_f32_e32 v75, 0x3377d1cf, v23
	v_fmac_f32_e32 v76, 0x3377d1cf, v24
	v_fmac_f32_e32 v77, 0x3377d1cf, v25
	v_fmac_f32_e32 v78, 0x3377d1cf, v26
	v_fmac_f32_e32 v79, 0x3377d1cf, v27
	v_fmac_f32_e32 v80, 0x3377d1cf, v28
	v_fmac_f32_e32 v81, 0x3377d1cf, v29
	v_fmac_f32_e32 v82, 0x3377d1cf, v30
	v_fmac_f32_e32 v83, 0x3377d1cf, v31
	v_fmac_f32_e32 v84, 0x3377d1cf, v32
	v_fmac_f32_e32 v85, 0x3377d1cf, v33
	v_fmac_f32_e32 v70, 0x3f317217, v18
	v_fmac_f32_e32 v71, 0x3f317217, v19
	v_fmac_f32_e32 v72, 0x3f317217, v20
	v_fmac_f32_e32 v73, 0x3f317217, v21
	v_fmac_f32_e32 v74, 0x3f317217, v22
	v_fmac_f32_e32 v75, 0x3f317217, v23
	v_fmac_f32_e32 v76, 0x3f317217, v24
	v_fmac_f32_e32 v77, 0x3f317217, v25
	v_fmac_f32_e32 v78, 0x3f317217, v26
	v_fmac_f32_e32 v79, 0x3f317217, v27
	v_fmac_f32_e32 v80, 0x3f317217, v28
	v_fmac_f32_e32 v81, 0x3f317217, v29
	v_fmac_f32_e32 v82, 0x3f317217, v30
	v_fmac_f32_e32 v83, 0x3f317217, v31
	v_fmac_f32_e32 v84, 0x3f317217, v32
	v_fmac_f32_e32 v85, 0x3f317217, v33
	v_add_f32_e32 v236, v236, v70
	v_add_f32_e32 v237, v237, v71
	v_add_f32_e32 v238, v238, v72
	v_add_f32_e32 v239, v239, v73
	v_add_f32_e32 v240, v240, v74
	v_add_f32_e32 v241, v241, v75
	v_add_f32_e32 v242, v242, v76
	v_add_f32_e32 v243, v243, v77
	v_add_f32_e32 v244, v244, v78
	v_add_f32_e32 v245, v245, v79
	v_add_f32_e32 v246, v246, v80
	v_add_f32_e32 v247, v247, v81
	v_add_f32_e32 v248, v248, v82
	v_add_f32_e32 v249, v249, v83
	v_add_f32_e32 v250, v250, v84
	v_add_f32_e32 v251, v251, v85
	v_mov_b32_e32 v70, v17
	v_fmac_f32_e32 v70, 0xbd800000, v236
	v_mov_b32_e32 v71, v70
	v_fmac_f32_e32 v71, 0xbd800000, v237
	v_mov_b32_e32 v72, v71
	v_fmac_f32_e32 v72, 0xbd800000, v238
	v_mov_b32_e32 v73, v72
	v_fmac_f32_e32 v73, 0xbd800000, v239
	v_mov_b32_e32 v74, v73
	v_fmac_f32_e32 v74, 0xbd800000, v240
	v_mov_b32_e32 v75, v74
	v_fmac_f32_e32 v75, 0xbd800000, v241
	v_mov_b32_e32 v76, v75
	v_fmac_f32_e32 v76, 0xbd800000, v242
	v_mov_b32_e32 v77, v76
	v_fmac_f32_e32 v77, 0xbd800000, v243
	v_mov_b32_e32 v78, v77
	v_fmac_f32_e32 v78, 0xbd800000, v244
	v_mov_b32_e32 v79, v78
	v_fmac_f32_e32 v79, 0xbd800000, v245
	v_mov_b32_e32 v80, v79
	v_fmac_f32_e32 v80, 0xbd800000, v246
	v_mov_b32_e32 v81, v80
	v_fmac_f32_e32 v81, 0xbd800000, v247
	v_mov_b32_e32 v82, v81
	v_fmac_f32_e32 v82, 0xbd800000, v248
	v_mov_b32_e32 v83, v82
	v_fmac_f32_e32 v83, 0xbd800000, v249
	v_mov_b32_e32 v84, v83
	v_fmac_f32_e32 v84, 0xbd800000, v250
	v_mov_b32_e32 v85, v84
	v_fmac_f32_e32 v85, 0xbd800000, v251
	v_mov_b32_e32 v17, v85
	s_waitcnt vmcnt(0)
	global_load_ushort v180, v134, s[6:7]
	global_load_ushort v196, v134, s[6:7] offset:512
	s_add_u32 s6, s6, s54
	s_addc_u32 s7, s7, s55
	global_load_ushort v181, v134, s[6:7]
	global_load_ushort v197, v134, s[6:7] offset:512
	s_add_u32 s6, s6, s54
	s_addc_u32 s7, s7, s55
	global_load_ushort v182, v134, s[6:7]
	global_load_ushort v198, v134, s[6:7] offset:512
	s_add_u32 s6, s6, s54
	s_addc_u32 s7, s7, s55
	global_load_ushort v183, v134, s[6:7]
	global_load_ushort v199, v134, s[6:7] offset:512
	s_add_u32 s6, s6, s54
	s_addc_u32 s7, s7, s55
	global_load_ushort v184, v134, s[6:7]
	global_load_ushort v200, v134, s[6:7] offset:512
	s_add_u32 s6, s6, s54
	s_addc_u32 s7, s7, s55
	global_load_ushort v185, v134, s[6:7]
	global_load_ushort v201, v134, s[6:7] offset:512
	s_add_u32 s6, s6, s54
	s_addc_u32 s7, s7, s55
	global_load_ushort v186, v134, s[6:7]
	global_load_ushort v202, v134, s[6:7] offset:512
	s_add_u32 s6, s6, s54
	s_addc_u32 s7, s7, s55
	global_load_ushort v187, v134, s[6:7]
	global_load_ushort v203, v134, s[6:7] offset:512
	s_add_u32 s6, s6, s54
	s_addc_u32 s7, s7, s55
	global_load_ushort v188, v134, s[6:7]
	global_load_ushort v204, v134, s[6:7] offset:512
	s_add_u32 s6, s6, s54
	s_addc_u32 s7, s7, s55
	global_load_ushort v189, v134, s[6:7]
	global_load_ushort v205, v134, s[6:7] offset:512
	s_add_u32 s6, s6, s54
	s_addc_u32 s7, s7, s55
	global_load_ushort v190, v134, s[6:7]
	global_load_ushort v206, v134, s[6:7] offset:512
	s_add_u32 s6, s6, s54
; __device__ __forceinline__ unsigned f2bf(float f) { unsigned r; asm("v_cvt_pk_bf16_f32 %0, %1, %1" : "=v"(r) : "v"(f)); return r & 0xffffu; }
; __device__ __forceinline__ void gl1_item(PREF p, int l, int item, bool valid, LAS unsigned char* pl, int sw, int lane) {
;     ...
;                 for (int ss = 0; ss < 16; ++ss) { const int s = (g4 + 1) * 16 + ss; const int i = d ? 63 - s : s; const bf16_t* pr = P + (size_t)(row0 + i * rstride) * PW + h * 64 + lane;
;                     qn[ss] = __builtin_bit_cast(float, (unsigned)pr[1024]); kn[ss] = __builtin_bit_cast(float, (unsigned)pr[1280]); }
;                 __builtin_amdgcn_sched_barrier(0);
;             }
;             float gv[16];
; #pragma unroll
;             for (int ss = 0; ss < 16; ++ss) { const int s = g4 * 16 + ss; const int i = d ? 63 - s : s;
;                 float z = bup;
; #pragma unroll
;                 for (int r2 = 0; r2 < 8; ++r2) { const unsigned w = (unsigned)__builtin_amdgcn_readlane((int)lrp[r2], i);
;                     z = __builtin_amdgcn_fdot2_f32_bf16(__builtin_bit_cast(bf16x2_t, w), __builtin_bit_cast(bf16x2_t, wupp[r2]), z, false); }
;                 gv[ss] = -(fmaxf(-z, 0.f) + __logf(1.f + __expf(-fabsf(z)))) * (1.f / 16.f);
;                 __builtin_amdgcn_sched_barrier(0);
;             }
; #pragma unroll
;             for (int ss = 0; ss < 16; ++ss) { const int s = g4 * 16 + ss; const int i = d ? 63 - s : s; const size_t rowi = (size_t)(row0 + i * rstride);
;                 bc += gv[ss];
;                 const float en = __expf(-bc), ep = __expf(bc);
;                 const float kt = kc[ss] * en, qt = qc[ss] * 0.125f * ep;
;                 const unsigned ktb = f2bf(kt);
	s_addc_u32 s7, s7, s55
	global_load_ushort v191, v134, s[6:7]
	global_load_ushort v207, v134, s[6:7] offset:512
	s_add_u32 s6, s6, s54
	s_addc_u32 s7, s7, s55
	global_load_ushort v192, v134, s[6:7]
	global_load_ushort v208, v134, s[6:7] offset:512
	s_add_u32 s6, s6, s54
	s_addc_u32 s7, s7, s55
	global_load_ushort v193, v134, s[6:7]
	global_load_ushort v209, v134, s[6:7] offset:512
	s_add_u32 s6, s6, s54
	s_addc_u32 s7, s7, s55
	global_load_ushort v194, v134, s[6:7]
	global_load_ushort v210, v134, s[6:7] offset:512
	s_add_u32 s6, s6, s54
	s_addc_u32 s7, s7, s55
	global_load_ushort v195, v134, s[6:7]
	global_load_ushort v211, v134, s[6:7] offset:512
	s_add_u32 s6, s6, s54
	s_addc_u32 s7, s7, s55
	v_mul_f32_e32 v18, 0xbfb8aa3b, v70
	v_mul_f32_e32 v19, 0xbfb8aa3b, v71
	v_mul_f32_e32 v20, 0xbfb8aa3b, v72
	v_mul_f32_e32 v21, 0xbfb8aa3b, v73
	v_mul_f32_e32 v22, 0xbfb8aa3b, v74
	v_mul_f32_e32 v23, 0xbfb8aa3b, v75
	v_mul_f32_e32 v24, 0xbfb8aa3b, v76
	v_mul_f32_e32 v25, 0xbfb8aa3b, v77
	v_mul_f32_e32 v26, 0xbfb8aa3b, v78
	v_mul_f32_e32 v27, 0xbfb8aa3b, v79
	v_mul_f32_e32 v28, 0xbfb8aa3b, v80
	v_mul_f32_e32 v29, 0xbfb8aa3b, v81
	v_mul_f32_e32 v30, 0xbfb8aa3b, v82
	v_mul_f32_e32 v31, 0xbfb8aa3b, v83
	v_mul_f32_e32 v32, 0xbfb8aa3b, v84
	v_mul_f32_e32 v33, 0xbfb8aa3b, v85
	v_mul_f32_e32 v236, 0x3fb8aa3b, v70
	v_mul_f32_e32 v237, 0x3fb8aa3b, v71
	v_mul_f32_e32 v238, 0x3fb8aa3b, v72
	v_mul_f32_e32 v239, 0x3fb8aa3b, v73
	v_mul_f32_e32 v240, 0x3fb8aa3b, v74
	v_mul_f32_e32 v241, 0x3fb8aa3b, v75
	v_mul_f32_e32 v242, 0x3fb8aa3b, v76
	v_mul_f32_e32 v243, 0x3fb8aa3b, v77
	v_mul_f32_e32 v244, 0x3fb8aa3b, v78
	v_mul_f32_e32 v245, 0x3fb8aa3b, v79
	v_mul_f32_e32 v246, 0x3fb8aa3b, v80
	v_mul_f32_e32 v247, 0x3fb8aa3b, v81
	v_mul_f32_e32 v248, 0x3fb8aa3b, v82
	v_mul_f32_e32 v249, 0x3fb8aa3b, v83
	v_mul_f32_e32 v250, 0x3fb8aa3b, v84
	v_mul_f32_e32 v251, 0x3fb8aa3b, v85
	v_exp_f32_e32 v18, v18
	v_exp_f32_e32 v19, v19
	v_exp_f32_e32 v20, v20
	v_exp_f32_e32 v21, v21
	v_exp_f32_e32 v22, v22
	v_exp_f32_e32 v23, v23
	v_exp_f32_e32 v24, v24
	v_exp_f32_e32 v25, v25
	v_exp_f32_e32 v26, v26
	v_exp_f32_e32 v27, v27
	v_exp_f32_e32 v28, v28
	v_exp_f32_e32 v29, v29
	v_exp_f32_e32 v30, v30
	v_exp_f32_e32 v31, v31
	v_exp_f32_e32 v32, v32
	v_exp_f32_e32 v33, v33
	v_exp_f32_e32 v236, v236
	v_exp_f32_e32 v237, v237
	v_exp_f32_e32 v238, v238
	v_exp_f32_e32 v239, v239
	v_exp_f32_e32 v240, v240
	v_exp_f32_e32 v241, v241
	v_exp_f32_e32 v242, v242
	v_exp_f32_e32 v243, v243
	v_exp_f32_e32 v244, v244
	v_exp_f32_e32 v245, v245
	v_exp_f32_e32 v246, v246
	v_exp_f32_e32 v247, v247
	v_exp_f32_e32 v248, v248
	v_exp_f32_e32 v249, v249
	v_exp_f32_e32 v250, v250
	v_exp_f32_e32 v251, v251
	v_lshlrev_b32_e32 v164, 16, v164
	v_lshlrev_b32_e32 v165, 16, v165
	v_lshlrev_b32_e32 v166, 16, v166
	v_lshlrev_b32_e32 v167, 16, v167
	v_lshlrev_b32_e32 v168, 16, v168
	v_lshlrev_b32_e32 v169, 16, v169
	v_lshlrev_b32_e32 v170, 16, v170
	v_lshlrev_b32_e32 v171, 16, v171
	v_lshlrev_b32_e32 v172, 16, v172
	v_lshlrev_b32_e32 v173, 16, v173
	v_lshlrev_b32_e32 v174, 16, v174
	v_lshlrev_b32_e32 v175, 16, v175
	v_lshlrev_b32_e32 v176, 16, v176
	v_lshlrev_b32_e32 v177, 16, v177
	v_lshlrev_b32_e32 v178, 16, v178
	v_lshlrev_b32_e32 v179, 16, v179
	v_lshlrev_b32_e32 v148, 16, v148
	v_lshlrev_b32_e32 v149, 16, v149
	v_lshlrev_b32_e32 v150, 16, v150
	v_lshlrev_b32_e32 v151, 16, v151
	v_lshlrev_b32_e32 v152, 16, v152
	v_lshlrev_b32_e32 v153, 16, v153
	v_lshlrev_b32_e32 v154, 16, v154
	v_lshlrev_b32_e32 v155, 16, v155
	v_lshlrev_b32_e32 v156, 16, v156
	v_lshlrev_b32_e32 v157, 16, v157
	v_lshlrev_b32_e32 v158, 16, v158
	v_lshlrev_b32_e32 v159, 16, v159
	v_lshlrev_b32_e32 v160, 16, v160
	v_lshlrev_b32_e32 v161, 16, v161
	v_lshlrev_b32_e32 v162, 16, v162
	v_lshlrev_b32_e32 v163, 16, v163
	v_mul_f32_e32 v164, v18, v164
	v_mul_f32_e32 v165, v19, v165
	v_mul_f32_e32 v166, v20, v166
	v_mul_f32_e32 v167, v21, v167
	v_mul_f32_e32 v168, v22, v168
	v_mul_f32_e32 v169, v23, v169
	v_mul_f32_e32 v170, v24, v170
	v_mul_f32_e32 v171, v25, v171
	v_mul_f32_e32 v172, v26, v172
	v_mul_f32_e32 v173, v27, v173
	v_mul_f32_e32 v174, v28, v174
	v_mul_f32_e32 v175, v29, v175
	v_mul_f32_e32 v176, v30, v176
	v_mul_f32_e32 v177, v31, v177
	v_mul_f32_e32 v178, v32, v178
	v_mul_f32_e32 v179, v33, v179
	v_mul_f32_e32 v148, 0x3e000000, v148
	v_mul_f32_e32 v149, 0x3e000000, v149
	v_mul_f32_e32 v150, 0x3e000000, v150
	v_mul_f32_e32 v151, 0x3e000000, v151
	v_mul_f32_e32 v152, 0x3e000000, v152
	v_mul_f32_e32 v153, 0x3e000000, v153
	v_mul_f32_e32 v154, 0x3e000000, v154
	v_mul_f32_e32 v155, 0x3e000000, v155
	v_mul_f32_e32 v156, 0x3e000000, v156
	v_mul_f32_e32 v157, 0x3e000000, v157
	v_mul_f32_e32 v158, 0x3e000000, v158
	v_mul_f32_e32 v159, 0x3e000000, v159
	v_mul_f32_e32 v160, 0x3e000000, v160
	v_mul_f32_e32 v161, 0x3e000000, v161
	v_mul_f32_e32 v162, 0x3e000000, v162
	v_mul_f32_e32 v163, 0x3e000000, v163
	v_mul_f32_e32 v148, v148, v236
	v_mul_f32_e32 v149, v149, v237
	v_mul_f32_e32 v150, v150, v238
	v_mul_f32_e32 v151, v151, v239
	v_mul_f32_e32 v152, v152, v240
	v_mul_f32_e32 v153, v153, v241
	v_mul_f32_e32 v154, v154, v242
	v_mul_f32_e32 v155, v155, v243
	v_mul_f32_e32 v156, v156, v244
	v_mul_f32_e32 v157, v157, v245
	v_mul_f32_e32 v158, v158, v246
	v_mul_f32_e32 v159, v159, v247
	v_mul_f32_e32 v160, v160, v248
	v_mul_f32_e32 v161, v161, v249
	v_mul_f32_e32 v162, v162, v250
	v_mul_f32_e32 v163, v163, v251
	v_cvt_pk_bf16_f32 v164, v164, v164
	v_cvt_pk_bf16_f32 v165, v165, v165
	v_cvt_pk_bf16_f32 v166, v166, v166
	v_cvt_pk_bf16_f32 v167, v167, v167
	v_cvt_pk_bf16_f32 v168, v168, v168
	v_cvt_pk_bf16_f32 v169, v169, v169
	v_cvt_pk_bf16_f32 v170, v170, v170
; __device__ __forceinline__ unsigned f2bf(float f) { unsigned r; asm("v_cvt_pk_bf16_f32 %0, %1, %1" : "=v"(r) : "v"(f)); return r & 0xffffu; }
; __device__ __forceinline__ void gl1_item(PREF p, int l, int item, bool valid, LAS unsigned char* pl, int sw, int lane) {
;     ...
;             for (int ss = 0; ss < 16; ++ss) { const int s = g4 * 16 + ss; const int i = d ? 63 - s : s;
;                 float z = bup;
; #pragma unroll
;                 for (int r2 = 0; r2 < 8; ++r2) { const unsigned w = (unsigned)__builtin_amdgcn_readlane((int)lrp[r2], i);
;                     z = __builtin_amdgcn_fdot2_f32_bf16(__builtin_bit_cast(bf16x2_t, w), __builtin_bit_cast(bf16x2_t, wupp[r2]), z, false); }
;                 gv[ss] = -(fmaxf(-z, 0.f) + __logf(1.f + __expf(-fabsf(z)))) * (1.f / 16.f);
;                 __builtin_amdgcn_sched_barrier(0);
;             }
; #pragma unroll
;             for (int ss = 0; ss < 16; ++ss) { const int s = g4 * 16 + ss; const int i = d ? 63 - s : s; const size_t rowi = (size_t)(row0 + i * rstride);
;                 bc += gv[ss];
;                 const float en = __expf(-bc), ep = __expf(bc);
;                 const float kt = kc[ss] * en, qt = qc[ss] * 0.125f * ep;
;                 const unsigned ktb = f2bf(kt);
;                 sKt[lane * 72 + i] = (bf16_t)ktb;
;                 QK[rowi * 1024 + d * 512 + h * 64 + lane] = (bf16_t)f2bf(qt);
;                 QK[rowi * 1024 + d * 512 + 256 + h * 64 + lane] = (bf16_t)ktb;
;             }
	v_cvt_pk_bf16_f32 v171, v171, v171
	v_cvt_pk_bf16_f32 v172, v172, v172
	v_cvt_pk_bf16_f32 v173, v173, v173
	v_cvt_pk_bf16_f32 v174, v174, v174
	v_cvt_pk_bf16_f32 v175, v175, v175
	v_cvt_pk_bf16_f32 v176, v176, v176
	v_cvt_pk_bf16_f32 v177, v177, v177
	v_cvt_pk_bf16_f32 v178, v178, v178
	v_cvt_pk_bf16_f32 v179, v179, v179
	v_cvt_pk_bf16_f32 v148, v148, v148
	v_cvt_pk_bf16_f32 v149, v149, v149
	v_cvt_pk_bf16_f32 v150, v150, v150
	v_cvt_pk_bf16_f32 v151, v151, v151
	v_cvt_pk_bf16_f32 v152, v152, v152
	v_cvt_pk_bf16_f32 v153, v153, v153
	v_cvt_pk_bf16_f32 v154, v154, v154
	v_cvt_pk_bf16_f32 v155, v155, v155
	v_cvt_pk_bf16_f32 v156, v156, v156
	v_cvt_pk_bf16_f32 v157, v157, v157
	v_cvt_pk_bf16_f32 v158, v158, v158
	v_cvt_pk_bf16_f32 v159, v159, v159
	v_cvt_pk_bf16_f32 v160, v160, v160
	v_cvt_pk_bf16_f32 v161, v161, v161
	v_cvt_pk_bf16_f32 v162, v162, v162
	v_cvt_pk_bf16_f32 v163, v163, v163
	ds_write_b16 v60, v164
	v_add_u32_e32 v60, v61, v60
	global_store_short v134, v148, s[4:5]
	global_store_short v134, v164, s[4:5] offset:512
	s_add_u32 s4, s4, s56
	s_addc_u32 s5, s5, s3
	ds_write_b16 v60, v165
	v_add_u32_e32 v60, v61, v60
	global_store_short v134, v149, s[4:5]
	global_store_short v134, v165, s[4:5] offset:512
	s_add_u32 s4, s4, s56
	s_addc_u32 s5, s5, s3
	ds_write_b16 v60, v166
	v_add_u32_e32 v60, v61, v60
	global_store_short v134, v150, s[4:5]
	global_store_short v134, v166, s[4:5] offset:512
	s_add_u32 s4, s4, s56
	s_addc_u32 s5, s5, s3
	ds_write_b16 v60, v167
	v_add_u32_e32 v60, v61, v60
	global_store_short v134, v151, s[4:5]
	global_store_short v134, v167, s[4:5] offset:512
	s_add_u32 s4, s4, s56
	s_addc_u32 s5, s5, s3
	ds_write_b16 v60, v168
	v_add_u32_e32 v60, v61, v60
	global_store_short v134, v152, s[4:5]
	global_store_short v134, v168, s[4:5] offset:512
	s_add_u32 s4, s4, s56
	s_addc_u32 s5, s5, s3
	ds_write_b16 v60, v169
	v_add_u32_e32 v60, v61, v60
	global_store_short v134, v153, s[4:5]
	global_store_short v134, v169, s[4:5] offset:512
	s_add_u32 s4, s4, s56
	s_addc_u32 s5, s5, s3
	ds_write_b16 v60, v170
	v_add_u32_e32 v60, v61, v60
	global_store_short v134, v154, s[4:5]
	global_store_short v134, v170, s[4:5] offset:512
	s_add_u32 s4, s4, s56
	s_addc_u32 s5, s5, s3
	ds_write_b16 v60, v171
	v_add_u32_e32 v60, v61, v60
	global_store_short v134, v155, s[4:5]
	global_store_short v134, v171, s[4:5] offset:512
	s_add_u32 s4, s4, s56
	s_addc_u32 s5, s5, s3
	ds_write_b16 v60, v172
	v_add_u32_e32 v60, v61, v60
	global_store_short v134, v156, s[4:5]
	global_store_short v134, v172, s[4:5] offset:512
	s_add_u32 s4, s4, s56
	s_addc_u32 s5, s5, s3
	ds_write_b16 v60, v173
	v_add_u32_e32 v60, v61, v60
	global_store_short v134, v157, s[4:5]
	global_store_short v134, v173, s[4:5] offset:512
	s_add_u32 s4, s4, s56
	s_addc_u32 s5, s5, s3
	ds_write_b16 v60, v174
	v_add_u32_e32 v60, v61, v60
	global_store_short v134, v158, s[4:5]
	global_store_short v134, v174, s[4:5] offset:512
	s_add_u32 s4, s4, s56
	s_addc_u32 s5, s5, s3
	ds_write_b16 v60, v175
	v_add_u32_e32 v60, v61, v60
	global_store_short v134, v159, s[4:5]
	global_store_short v134, v175, s[4:5] offset:512
	s_add_u32 s4, s4, s56
	s_addc_u32 s5, s5, s3
	ds_write_b16 v60, v176
	v_add_u32_e32 v60, v61, v60
	global_store_short v134, v160, s[4:5]
	global_store_short v134, v176, s[4:5] offset:512
	s_add_u32 s4, s4, s56
	s_addc_u32 s5, s5, s3
	ds_write_b16 v60, v177
	v_add_u32_e32 v60, v61, v60
	global_store_short v134, v161, s[4:5]
	global_store_short v134, v177, s[4:5] offset:512
	s_add_u32 s4, s4, s56
	s_addc_u32 s5, s5, s3
	ds_write_b16 v60, v178
	v_add_u32_e32 v60, v61, v60
	global_store_short v134, v162, s[4:5]
	global_store_short v134, v178, s[4:5] offset:512
	s_add_u32 s4, s4, s56
	s_addc_u32 s5, s5, s3
	ds_write_b16 v60, v179
	v_add_u32_e32 v60, v61, v60
	global_store_short v134, v163, s[4:5]
	global_store_short v134, v179, s[4:5] offset:512
	s_add_u32 s4, s4, s56
	s_addc_u32 s5, s5, s3
	v_mov_b32_e32 v236, v16
	v_readlane_b32 s45, v0, s30
	v_readlane_b32 s46, v1, s30
	v_readlane_b32 s47, v2, s30
	v_readlane_b32 s48, v3, s30
	v_readlane_b32 s49, v4, s30
	v_readlane_b32 s50, v5, s30
	v_readlane_b32 s51, v6, s30
	v_readlane_b32 s52, v7, s30
	s_add_i32 s30, s30, s2
	v_dot2c_f32_bf16_e32 v236, s45, v8
	v_dot2c_f32_bf16_e32 v236, s46, v9
	v_dot2c_f32_bf16_e32 v236, s47, v10
	v_dot2c_f32_bf16_e32 v236, s48, v11
	v_dot2c_f32_bf16_e32 v236, s49, v12
	v_dot2c_f32_bf16_e32 v236, s50, v13
	v_dot2c_f32_bf16_e32 v236, s51, v14
	v_dot2c_f32_bf16_e32 v236, s52, v15
	v_mov_b32_e32 v237, v16
	v_readlane_b32 s45, v0, s30
	v_readlane_b32 s46, v1, s30
	v_readlane_b32 s47, v2, s30
	v_readlane_b32 s48, v3, s30
	v_readlane_b32 s49, v4, s30
	v_readlane_b32 s50, v5, s30
	v_readlane_b32 s51, v6, s30
	v_readlane_b32 s52, v7, s30
	s_add_i32 s30, s30, s2
	v_dot2c_f32_bf16_e32 v237, s45, v8
	v_dot2c_f32_bf16_e32 v237, s46, v9
	v_dot2c_f32_bf16_e32 v237, s47, v10
	v_dot2c_f32_bf16_e32 v237, s48, v11
	v_dot2c_f32_bf16_e32 v237, s49, v12
	v_dot2c_f32_bf16_e32 v237, s50, v13
	v_dot2c_f32_bf16_e32 v237, s51, v14
	v_dot2c_f32_bf16_e32 v237, s52, v15
	v_mov_b32_e32 v238, v16
	v_readlane_b32 s45, v0, s30
	v_readlane_b32 s46, v1, s30
	v_readlane_b32 s47, v2, s30
	v_readlane_b32 s48, v3, s30
	v_readlane_b32 s49, v4, s30
	v_readlane_b32 s50, v5, s30
	v_readlane_b32 s51, v6, s30
	v_readlane_b32 s52, v7, s30
	s_add_i32 s30, s30, s2
	v_dot2c_f32_bf16_e32 v238, s45, v8
	v_dot2c_f32_bf16_e32 v238, s46, v9
	v_dot2c_f32_bf16_e32 v238, s47, v10
	v_dot2c_f32_bf16_e32 v238, s48, v11
	v_dot2c_f32_bf16_e32 v238, s49, v12
	v_dot2c_f32_bf16_e32 v238, s50, v13
	v_dot2c_f32_bf16_e32 v238, s51, v14
	v_dot2c_f32_bf16_e32 v238, s52, v15
; __device__ __forceinline__ void gl1_item(PREF p, int l, int item, bool valid, LAS unsigned char* pl, int sw, int lane) {
;     ...
;             for (int ss = 0; ss < 16; ++ss) { const int s = g4 * 16 + ss; const int i = d ? 63 - s : s;
;                 float z = bup;
; #pragma unroll
;                 for (int r2 = 0; r2 < 8; ++r2) { const unsigned w = (unsigned)__builtin_amdgcn_readlane((int)lrp[r2], i);
;                     z = __builtin_amdgcn_fdot2_f32_bf16(__builtin_bit_cast(bf16x2_t, w), __builtin_bit_cast(bf16x2_t, wupp[r2]), z, false); }
	v_mov_b32_e32 v239, v16
	v_readlane_b32 s45, v0, s30
	v_readlane_b32 s46, v1, s30
	v_readlane_b32 s47, v2, s30
	v_readlane_b32 s48, v3, s30
	v_readlane_b32 s49, v4, s30
	v_readlane_b32 s50, v5, s30
	v_readlane_b32 s51, v6, s30
	v_readlane_b32 s52, v7, s30
	s_add_i32 s30, s30, s2
	v_dot2c_f32_bf16_e32 v239, s45, v8
	v_dot2c_f32_bf16_e32 v239, s46, v9
	v_dot2c_f32_bf16_e32 v239, s47, v10
	v_dot2c_f32_bf16_e32 v239, s48, v11
	v_dot2c_f32_bf16_e32 v239, s49, v12
	v_dot2c_f32_bf16_e32 v239, s50, v13
	v_dot2c_f32_bf16_e32 v239, s51, v14
	v_dot2c_f32_bf16_e32 v239, s52, v15
	v_mov_b32_e32 v240, v16
	v_readlane_b32 s45, v0, s30
	v_readlane_b32 s46, v1, s30
	v_readlane_b32 s47, v2, s30
	v_readlane_b32 s48, v3, s30
	v_readlane_b32 s49, v4, s30
	v_readlane_b32 s50, v5, s30
	v_readlane_b32 s51, v6, s30
	v_readlane_b32 s52, v7, s30
	s_add_i32 s30, s30, s2
	v_dot2c_f32_bf16_e32 v240, s45, v8
	v_dot2c_f32_bf16_e32 v240, s46, v9
	v_dot2c_f32_bf16_e32 v240, s47, v10
	v_dot2c_f32_bf16_e32 v240, s48, v11
	v_dot2c_f32_bf16_e32 v240, s49, v12
	v_dot2c_f32_bf16_e32 v240, s50, v13
	v_dot2c_f32_bf16_e32 v240, s51, v14
	v_dot2c_f32_bf16_e32 v240, s52, v15
	v_mov_b32_e32 v241, v16
	v_readlane_b32 s45, v0, s30
	v_readlane_b32 s46, v1, s30
	v_readlane_b32 s47, v2, s30
	v_readlane_b32 s48, v3, s30
	v_readlane_b32 s49, v4, s30
	v_readlane_b32 s50, v5, s30
	v_readlane_b32 s51, v6, s30
	v_readlane_b32 s52, v7, s30
	s_add_i32 s30, s30, s2
	v_dot2c_f32_bf16_e32 v241, s45, v8
	v_dot2c_f32_bf16_e32 v241, s46, v9
	v_dot2c_f32_bf16_e32 v241, s47, v10
	v_dot2c_f32_bf16_e32 v241, s48, v11
	v_dot2c_f32_bf16_e32 v241, s49, v12
	v_dot2c_f32_bf16_e32 v241, s50, v13
	v_dot2c_f32_bf16_e32 v241, s51, v14
	v_dot2c_f32_bf16_e32 v241, s52, v15
	v_mov_b32_e32 v242, v16
	v_readlane_b32 s45, v0, s30
	v_readlane_b32 s46, v1, s30
	v_readlane_b32 s47, v2, s30
	v_readlane_b32 s48, v3, s30
	v_readlane_b32 s49, v4, s30
	v_readlane_b32 s50, v5, s30
	v_readlane_b32 s51, v6, s30
	v_readlane_b32 s52, v7, s30
	s_add_i32 s30, s30, s2
	v_dot2c_f32_bf16_e32 v242, s45, v8
	v_dot2c_f32_bf16_e32 v242, s46, v9
	v_dot2c_f32_bf16_e32 v242, s47, v10
	v_dot2c_f32_bf16_e32 v242, s48, v11
	v_dot2c_f32_bf16_e32 v242, s49, v12
	v_dot2c_f32_bf16_e32 v242, s50, v13
	v_dot2c_f32_bf16_e32 v242, s51, v14
	v_dot2c_f32_bf16_e32 v242, s52, v15
	v_mov_b32_e32 v243, v16
	v_readlane_b32 s45, v0, s30
	v_readlane_b32 s46, v1, s30
	v_readlane_b32 s47, v2, s30
	v_readlane_b32 s48, v3, s30
	v_readlane_b32 s49, v4, s30
	v_readlane_b32 s50, v5, s30
	v_readlane_b32 s51, v6, s30
	v_readlane_b32 s52, v7, s30
	s_add_i32 s30, s30, s2
	v_dot2c_f32_bf16_e32 v243, s45, v8
	v_dot2c_f32_bf16_e32 v243, s46, v9
	v_dot2c_f32_bf16_e32 v243, s47, v10
	v_dot2c_f32_bf16_e32 v243, s48, v11
	v_dot2c_f32_bf16_e32 v243, s49, v12
	v_dot2c_f32_bf16_e32 v243, s50, v13
	v_dot2c_f32_bf16_e32 v243, s51, v14
	v_dot2c_f32_bf16_e32 v243, s52, v15
	v_mov_b32_e32 v244, v16
	v_readlane_b32 s45, v0, s30
	v_readlane_b32 s46, v1, s30
	v_readlane_b32 s47, v2, s30
	v_readlane_b32 s48, v3, s30
	v_readlane_b32 s49, v4, s30
	v_readlane_b32 s50, v5, s30
	v_readlane_b32 s51, v6, s30
	v_readlane_b32 s52, v7, s30
	s_add_i32 s30, s30, s2
	v_dot2c_f32_bf16_e32 v244, s45, v8
	v_dot2c_f32_bf16_e32 v244, s46, v9
	v_dot2c_f32_bf16_e32 v244, s47, v10
	v_dot2c_f32_bf16_e32 v244, s48, v11
	v_dot2c_f32_bf16_e32 v244, s49, v12
	v_dot2c_f32_bf16_e32 v244, s50, v13
	v_dot2c_f32_bf16_e32 v244, s51, v14
	v_dot2c_f32_bf16_e32 v244, s52, v15
	v_mov_b32_e32 v245, v16
	v_readlane_b32 s45, v0, s30
	v_readlane_b32 s46, v1, s30
	v_readlane_b32 s47, v2, s30
	v_readlane_b32 s48, v3, s30
	v_readlane_b32 s49, v4, s30
	v_readlane_b32 s50, v5, s30
	v_readlane_b32 s51, v6, s30
	v_readlane_b32 s52, v7, s30
	s_add_i32 s30, s30, s2
	v_dot2c_f32_bf16_e32 v245, s45, v8
	v_dot2c_f32_bf16_e32 v245, s46, v9
	v_dot2c_f32_bf16_e32 v245, s47, v10
	v_dot2c_f32_bf16_e32 v245, s48, v11
	v_dot2c_f32_bf16_e32 v245, s49, v12
	v_dot2c_f32_bf16_e32 v245, s50, v13
	v_dot2c_f32_bf16_e32 v245, s51, v14
	v_dot2c_f32_bf16_e32 v245, s52, v15
	v_mov_b32_e32 v246, v16
	v_readlane_b32 s45, v0, s30
	v_readlane_b32 s46, v1, s30
	v_readlane_b32 s47, v2, s30
	v_readlane_b32 s48, v3, s30
	v_readlane_b32 s49, v4, s30
	v_readlane_b32 s50, v5, s30
	v_readlane_b32 s51, v6, s30
	v_readlane_b32 s52, v7, s30
	s_add_i32 s30, s30, s2
	v_dot2c_f32_bf16_e32 v246, s45, v8
	v_dot2c_f32_bf16_e32 v246, s46, v9
	v_dot2c_f32_bf16_e32 v246, s47, v10
	v_dot2c_f32_bf16_e32 v246, s48, v11
	v_dot2c_f32_bf16_e32 v246, s49, v12
	v_dot2c_f32_bf16_e32 v246, s50, v13
	v_dot2c_f32_bf16_e32 v246, s51, v14
	v_dot2c_f32_bf16_e32 v246, s52, v15
	v_mov_b32_e32 v247, v16
	v_readlane_b32 s45, v0, s30
	v_readlane_b32 s46, v1, s30
	v_readlane_b32 s47, v2, s30
	v_readlane_b32 s48, v3, s30
	v_readlane_b32 s49, v4, s30
	v_readlane_b32 s50, v5, s30
	v_readlane_b32 s51, v6, s30
	v_readlane_b32 s52, v7, s30
	s_add_i32 s30, s30, s2
	v_dot2c_f32_bf16_e32 v247, s45, v8
	v_dot2c_f32_bf16_e32 v247, s46, v9
	v_dot2c_f32_bf16_e32 v247, s47, v10
	v_dot2c_f32_bf16_e32 v247, s48, v11
	v_dot2c_f32_bf16_e32 v247, s49, v12
	v_dot2c_f32_bf16_e32 v247, s50, v13
	v_dot2c_f32_bf16_e32 v247, s51, v14
	v_dot2c_f32_bf16_e32 v247, s52, v15
	v_mov_b32_e32 v248, v16
	v_readlane_b32 s45, v0, s30
	v_readlane_b32 s46, v1, s30
	v_readlane_b32 s47, v2, s30
	v_readlane_b32 s48, v3, s30
	v_readlane_b32 s49, v4, s30
	v_readlane_b32 s50, v5, s30
	v_readlane_b32 s51, v6, s30
	v_readlane_b32 s52, v7, s30
	s_add_i32 s30, s30, s2
	v_dot2c_f32_bf16_e32 v248, s45, v8
	v_dot2c_f32_bf16_e32 v248, s46, v9
	v_dot2c_f32_bf16_e32 v248, s47, v10
	v_dot2c_f32_bf16_e32 v248, s48, v11
	v_dot2c_f32_bf16_e32 v248, s49, v12
; __device__ __forceinline__ void gl1_item(PREF p, int l, int item, bool valid, LAS unsigned char* pl, int sw, int lane) {
;     ...
;             for (int ss = 0; ss < 16; ++ss) { const int s = g4 * 16 + ss; const int i = d ? 63 - s : s;
;                 float z = bup;
; #pragma unroll
;                 for (int r2 = 0; r2 < 8; ++r2) { const unsigned w = (unsigned)__builtin_amdgcn_readlane((int)lrp[r2], i);
;                     z = __builtin_amdgcn_fdot2_f32_bf16(__builtin_bit_cast(bf16x2_t, w), __builtin_bit_cast(bf16x2_t, wupp[r2]), z, false); }
;                 gv[ss] = -(fmaxf(-z, 0.f) + __logf(1.f + __expf(-fabsf(z)))) * (1.f / 16.f);
	v_dot2c_f32_bf16_e32 v248, s50, v13
	v_dot2c_f32_bf16_e32 v248, s51, v14
	v_dot2c_f32_bf16_e32 v248, s52, v15
	v_mov_b32_e32 v249, v16
	v_readlane_b32 s45, v0, s30
	v_readlane_b32 s46, v1, s30
	v_readlane_b32 s47, v2, s30
	v_readlane_b32 s48, v3, s30
	v_readlane_b32 s49, v4, s30
	v_readlane_b32 s50, v5, s30
	v_readlane_b32 s51, v6, s30
	v_readlane_b32 s52, v7, s30
	s_add_i32 s30, s30, s2
	v_dot2c_f32_bf16_e32 v249, s45, v8
	v_dot2c_f32_bf16_e32 v249, s46, v9
	v_dot2c_f32_bf16_e32 v249, s47, v10
	v_dot2c_f32_bf16_e32 v249, s48, v11
	v_dot2c_f32_bf16_e32 v249, s49, v12
	v_dot2c_f32_bf16_e32 v249, s50, v13
	v_dot2c_f32_bf16_e32 v249, s51, v14
	v_dot2c_f32_bf16_e32 v249, s52, v15
	v_mov_b32_e32 v250, v16
	v_readlane_b32 s45, v0, s30
	v_readlane_b32 s46, v1, s30
	v_readlane_b32 s47, v2, s30
	v_readlane_b32 s48, v3, s30
	v_readlane_b32 s49, v4, s30
	v_readlane_b32 s50, v5, s30
	v_readlane_b32 s51, v6, s30
	v_readlane_b32 s52, v7, s30
	s_add_i32 s30, s30, s2
	v_dot2c_f32_bf16_e32 v250, s45, v8
	v_dot2c_f32_bf16_e32 v250, s46, v9
	v_dot2c_f32_bf16_e32 v250, s47, v10
	v_dot2c_f32_bf16_e32 v250, s48, v11
	v_dot2c_f32_bf16_e32 v250, s49, v12
	v_dot2c_f32_bf16_e32 v250, s50, v13
	v_dot2c_f32_bf16_e32 v250, s51, v14
	v_dot2c_f32_bf16_e32 v250, s52, v15
	v_mov_b32_e32 v251, v16
	v_readlane_b32 s45, v0, s30
	v_readlane_b32 s46, v1, s30
	v_readlane_b32 s47, v2, s30
	v_readlane_b32 s48, v3, s30
	v_readlane_b32 s49, v4, s30
	v_readlane_b32 s50, v5, s30
	v_readlane_b32 s51, v6, s30
	v_readlane_b32 s52, v7, s30
	s_add_i32 s30, s30, s2
	v_dot2c_f32_bf16_e32 v251, s45, v8
	v_dot2c_f32_bf16_e32 v251, s46, v9
	v_dot2c_f32_bf16_e32 v251, s47, v10
	v_dot2c_f32_bf16_e32 v251, s48, v11
	v_dot2c_f32_bf16_e32 v251, s49, v12
	v_dot2c_f32_bf16_e32 v251, s50, v13
	v_dot2c_f32_bf16_e32 v251, s51, v14
	v_dot2c_f32_bf16_e32 v251, s52, v15
	s_nop 2
	v_mul_f32_e64 v18, |v236|, s1
	v_mul_f32_e64 v19, |v237|, s1
	v_mul_f32_e64 v20, |v238|, s1
	v_mul_f32_e64 v21, |v239|, s1
	v_mul_f32_e64 v22, |v240|, s1
	v_mul_f32_e64 v23, |v241|, s1
	v_mul_f32_e64 v24, |v242|, s1
	v_mul_f32_e64 v25, |v243|, s1
	v_mul_f32_e64 v26, |v244|, s1
	v_mul_f32_e64 v27, |v245|, s1
	v_mul_f32_e64 v28, |v246|, s1
	v_mul_f32_e64 v29, |v247|, s1
	v_mul_f32_e64 v30, |v248|, s1
	v_mul_f32_e64 v31, |v249|, s1
	v_mul_f32_e64 v32, |v250|, s1
	v_mul_f32_e64 v33, |v251|, s1
	v_exp_f32_e32 v18, v18
	v_exp_f32_e32 v19, v19
	v_exp_f32_e32 v20, v20
	v_exp_f32_e32 v21, v21
	v_exp_f32_e32 v22, v22
	v_exp_f32_e32 v23, v23
	v_exp_f32_e32 v24, v24
	v_exp_f32_e32 v25, v25
	v_exp_f32_e32 v26, v26
	v_exp_f32_e32 v27, v27
	v_exp_f32_e32 v28, v28
	v_exp_f32_e32 v29, v29
	v_exp_f32_e32 v30, v30
	v_exp_f32_e32 v31, v31
	v_exp_f32_e32 v32, v32
	v_exp_f32_e32 v33, v33
	v_max_f32_e64 v236, -v236, -v236
	v_max_f32_e64 v237, -v237, -v237
	v_max_f32_e64 v238, -v238, -v238
	v_max_f32_e64 v239, -v239, -v239
	v_max_f32_e64 v240, -v240, -v240
	v_max_f32_e64 v241, -v241, -v241
	v_max_f32_e64 v242, -v242, -v242
	v_max_f32_e64 v243, -v243, -v243
	v_max_f32_e64 v244, -v244, -v244
	v_max_f32_e64 v245, -v245, -v245
	v_max_f32_e64 v246, -v246, -v246
	v_max_f32_e64 v247, -v247, -v247
	v_max_f32_e64 v248, -v248, -v248
	v_max_f32_e64 v249, -v249, -v249
	v_max_f32_e64 v250, -v250, -v250
	v_max_f32_e64 v251, -v251, -v251
	v_max_f32_e32 v236, 0, v236
	v_max_f32_e32 v237, 0, v237
	v_max_f32_e32 v238, 0, v238
	v_max_f32_e32 v239, 0, v239
	v_max_f32_e32 v240, 0, v240
	v_max_f32_e32 v241, 0, v241
	v_max_f32_e32 v242, 0, v242
	v_max_f32_e32 v243, 0, v243
	v_max_f32_e32 v244, 0, v244
	v_max_f32_e32 v245, 0, v245
	v_max_f32_e32 v246, 0, v246
	v_max_f32_e32 v247, 0, v247
	v_max_f32_e32 v248, 0, v248
	v_max_f32_e32 v249, 0, v249
	v_max_f32_e32 v250, 0, v250
	v_max_f32_e32 v251, 0, v251
	v_add_f32_e32 v18, 1.0, v18
	v_add_f32_e32 v19, 1.0, v19
	v_add_f32_e32 v20, 1.0, v20
	v_add_f32_e32 v21, 1.0, v21
	v_add_f32_e32 v22, 1.0, v22
	v_add_f32_e32 v23, 1.0, v23
	v_add_f32_e32 v24, 1.0, v24
	v_add_f32_e32 v25, 1.0, v25
	v_add_f32_e32 v26, 1.0, v26
	v_add_f32_e32 v27, 1.0, v27
	v_add_f32_e32 v28, 1.0, v28
	v_add_f32_e32 v29, 1.0, v29
	v_add_f32_e32 v30, 1.0, v30
	v_add_f32_e32 v31, 1.0, v31
	v_add_f32_e32 v32, 1.0, v32
	v_add_f32_e32 v33, 1.0, v33
	v_log_f32_e32 v18, v18
	v_log_f32_e32 v19, v19
	v_log_f32_e32 v20, v20
	v_log_f32_e32 v21, v21
	v_log_f32_e32 v22, v22
	v_log_f32_e32 v23, v23
	v_log_f32_e32 v24, v24
	v_log_f32_e32 v25, v25
	v_log_f32_e32 v26, v26
	v_log_f32_e32 v27, v27
	v_log_f32_e32 v28, v28
	v_log_f32_e32 v29, v29
	v_log_f32_e32 v30, v30
	v_log_f32_e32 v31, v31
	v_log_f32_e32 v32, v32
	v_log_f32_e32 v33, v33
	s_mov_b32 s45, 0x3f317217
	v_mul_f32_e32 v70, 0x3f317217, v18
	v_mul_f32_e32 v71, 0x3f317217, v19
	v_mul_f32_e32 v72, 0x3f317217, v20
	v_mul_f32_e32 v73, 0x3f317217, v21
	v_mul_f32_e32 v74, 0x3f317217, v22
	v_mul_f32_e32 v75, 0x3f317217, v23
	v_mul_f32_e32 v76, 0x3f317217, v24
	v_mul_f32_e32 v77, 0x3f317217, v25
	v_mul_f32_e32 v78, 0x3f317217, v26
	v_mul_f32_e32 v79, 0x3f317217, v27
	v_mul_f32_e32 v80, 0x3f317217, v28
	v_mul_f32_e32 v81, 0x3f317217, v29
	v_mul_f32_e32 v82, 0x3f317217, v30
	v_mul_f32_e32 v83, 0x3f317217, v31
	v_mul_f32_e32 v84, 0x3f317217, v32
	v_mul_f32_e32 v85, 0x3f317217, v33
	v_fma_f32 v70, v18, s45, -v70
	v_fma_f32 v71, v19, s45, -v71
	v_fma_f32 v72, v20, s45, -v72
	v_fma_f32 v73, v21, s45, -v73
	v_fma_f32 v74, v22, s45, -v74
	v_fma_f32 v75, v23, s45, -v75
	v_fma_f32 v76, v24, s45, -v76
	v_fma_f32 v77, v25, s45, -v77
	v_fma_f32 v78, v26, s45, -v78
	v_fma_f32 v79, v27, s45, -v79
	v_fma_f32 v80, v28, s45, -v80
	v_fma_f32 v81, v29, s45, -v81
	v_fma_f32 v82, v30, s45, -v82
	v_fma_f32 v83, v31, s45, -v83
	v_fma_f32 v84, v32, s45, -v84
; __device__ __forceinline__ void gl1_item(PREF p, int l, int item, bool valid, LAS unsigned char* pl, int sw, int lane) {
;     ...
;                 for (int ss = 0; ss < 16; ++ss) { const int s = (g4 + 1) * 16 + ss; const int i = d ? 63 - s : s; const bf16_t* pr = P + (size_t)(row0 + i * rstride) * PW + h * 64 + lane;
;                     qn[ss] = __builtin_bit_cast(float, (unsigned)pr[1024]); kn[ss] = __builtin_bit_cast(float, (unsigned)pr[1280]); }
;                 __builtin_amdgcn_sched_barrier(0);
;             }
;             float gv[16];
; #pragma unroll
;             for (int ss = 0; ss < 16; ++ss) { const int s = g4 * 16 + ss; const int i = d ? 63 - s : s;
;                 float z = bup;
; #pragma unroll
;                 for (int r2 = 0; r2 < 8; ++r2) { const unsigned w = (unsigned)__builtin_amdgcn_readlane((int)lrp[r2], i);
;                     z = __builtin_amdgcn_fdot2_f32_bf16(__builtin_bit_cast(bf16x2_t, w), __builtin_bit_cast(bf16x2_t, wupp[r2]), z, false); }
;                 gv[ss] = -(fmaxf(-z, 0.f) + __logf(1.f + __expf(-fabsf(z)))) * (1.f / 16.f);
;                 __builtin_amdgcn_sched_barrier(0);
;             }
; #pragma unroll
;             for (int ss = 0; ss < 16; ++ss) { const int s = g4 * 16 + ss; const int i = d ? 63 - s : s; const size_t rowi = (size_t)(row0 + i * rstride);
;                 bc += gv[ss];
;                 const float en = __expf(-bc), ep = __expf(bc);
;                 const float kt = kc[ss] * en, qt = qc[ss] * 0.125f * ep;
	v_fma_f32 v85, v33, s45, -v85
	v_fmac_f32_e32 v70, 0x3377d1cf, v18
	v_fmac_f32_e32 v71, 0x3377d1cf, v19
	v_fmac_f32_e32 v72, 0x3377d1cf, v20
	v_fmac_f32_e32 v73, 0x3377d1cf, v21
	v_fmac_f32_e32 v74, 0x3377d1cf, v22
	v_fmac_f32_e32 v75, 0x3377d1cf, v23
	v_fmac_f32_e32 v76, 0x3377d1cf, v24
	v_fmac_f32_e32 v77, 0x3377d1cf, v25
	v_fmac_f32_e32 v78, 0x3377d1cf, v26
	v_fmac_f32_e32 v79, 0x3377d1cf, v27
	v_fmac_f32_e32 v80, 0x3377d1cf, v28
	v_fmac_f32_e32 v81, 0x3377d1cf, v29
	v_fmac_f32_e32 v82, 0x3377d1cf, v30
	v_fmac_f32_e32 v83, 0x3377d1cf, v31
	v_fmac_f32_e32 v84, 0x3377d1cf, v32
	v_fmac_f32_e32 v85, 0x3377d1cf, v33
	v_fmac_f32_e32 v70, 0x3f317217, v18
	v_fmac_f32_e32 v71, 0x3f317217, v19
	v_fmac_f32_e32 v72, 0x3f317217, v20
	v_fmac_f32_e32 v73, 0x3f317217, v21
	v_fmac_f32_e32 v74, 0x3f317217, v22
	v_fmac_f32_e32 v75, 0x3f317217, v23
	v_fmac_f32_e32 v76, 0x3f317217, v24
	v_fmac_f32_e32 v77, 0x3f317217, v25
	v_fmac_f32_e32 v78, 0x3f317217, v26
	v_fmac_f32_e32 v79, 0x3f317217, v27
	v_fmac_f32_e32 v80, 0x3f317217, v28
	v_fmac_f32_e32 v81, 0x3f317217, v29
	v_fmac_f32_e32 v82, 0x3f317217, v30
	v_fmac_f32_e32 v83, 0x3f317217, v31
	v_fmac_f32_e32 v84, 0x3f317217, v32
	v_fmac_f32_e32 v85, 0x3f317217, v33
	v_add_f32_e32 v236, v236, v70
	v_add_f32_e32 v237, v237, v71
	v_add_f32_e32 v238, v238, v72
	v_add_f32_e32 v239, v239, v73
	v_add_f32_e32 v240, v240, v74
	v_add_f32_e32 v241, v241, v75
	v_add_f32_e32 v242, v242, v76
	v_add_f32_e32 v243, v243, v77
	v_add_f32_e32 v244, v244, v78
	v_add_f32_e32 v245, v245, v79
	v_add_f32_e32 v246, v246, v80
	v_add_f32_e32 v247, v247, v81
	v_add_f32_e32 v248, v248, v82
	v_add_f32_e32 v249, v249, v83
	v_add_f32_e32 v250, v250, v84
	v_add_f32_e32 v251, v251, v85
	v_mov_b32_e32 v70, v17
	v_fmac_f32_e32 v70, 0xbd800000, v236
	v_mov_b32_e32 v71, v70
	v_fmac_f32_e32 v71, 0xbd800000, v237
	v_mov_b32_e32 v72, v71
	v_fmac_f32_e32 v72, 0xbd800000, v238
	v_mov_b32_e32 v73, v72
	v_fmac_f32_e32 v73, 0xbd800000, v239
	v_mov_b32_e32 v74, v73
	v_fmac_f32_e32 v74, 0xbd800000, v240
	v_mov_b32_e32 v75, v74
	v_fmac_f32_e32 v75, 0xbd800000, v241
	v_mov_b32_e32 v76, v75
	v_fmac_f32_e32 v76, 0xbd800000, v242
	v_mov_b32_e32 v77, v76
	v_fmac_f32_e32 v77, 0xbd800000, v243
	v_mov_b32_e32 v78, v77
	v_fmac_f32_e32 v78, 0xbd800000, v244
	v_mov_b32_e32 v79, v78
	v_fmac_f32_e32 v79, 0xbd800000, v245
	v_mov_b32_e32 v80, v79
	v_fmac_f32_e32 v80, 0xbd800000, v246
	v_mov_b32_e32 v81, v80
	v_fmac_f32_e32 v81, 0xbd800000, v247
	v_mov_b32_e32 v82, v81
	v_fmac_f32_e32 v82, 0xbd800000, v248
	v_mov_b32_e32 v83, v82
	v_fmac_f32_e32 v83, 0xbd800000, v249
	v_mov_b32_e32 v84, v83
	v_fmac_f32_e32 v84, 0xbd800000, v250
	v_mov_b32_e32 v85, v84
	v_fmac_f32_e32 v85, 0xbd800000, v251
	v_mov_b32_e32 v17, v85
	s_waitcnt vmcnt(32)
	global_load_ushort v148, v134, s[6:7]
	global_load_ushort v164, v134, s[6:7] offset:512
	s_add_u32 s6, s6, s54
	s_addc_u32 s7, s7, s55
	global_load_ushort v149, v134, s[6:7]
	global_load_ushort v165, v134, s[6:7] offset:512
	s_add_u32 s6, s6, s54
	s_addc_u32 s7, s7, s55
	global_load_ushort v150, v134, s[6:7]
	global_load_ushort v166, v134, s[6:7] offset:512
	s_add_u32 s6, s6, s54
	s_addc_u32 s7, s7, s55
	global_load_ushort v151, v134, s[6:7]
	global_load_ushort v167, v134, s[6:7] offset:512
	s_add_u32 s6, s6, s54
	s_addc_u32 s7, s7, s55
	global_load_ushort v152, v134, s[6:7]
	global_load_ushort v168, v134, s[6:7] offset:512
	s_add_u32 s6, s6, s54
	s_addc_u32 s7, s7, s55
	global_load_ushort v153, v134, s[6:7]
	global_load_ushort v169, v134, s[6:7] offset:512
	s_add_u32 s6, s6, s54
	s_addc_u32 s7, s7, s55
	global_load_ushort v154, v134, s[6:7]
	global_load_ushort v170, v134, s[6:7] offset:512
	s_add_u32 s6, s6, s54
	s_addc_u32 s7, s7, s55
	global_load_ushort v155, v134, s[6:7]
	global_load_ushort v171, v134, s[6:7] offset:512
	s_add_u32 s6, s6, s54
	s_addc_u32 s7, s7, s55
	global_load_ushort v156, v134, s[6:7]
	global_load_ushort v172, v134, s[6:7] offset:512
	s_add_u32 s6, s6, s54
	s_addc_u32 s7, s7, s55
	global_load_ushort v157, v134, s[6:7]
	global_load_ushort v173, v134, s[6:7] offset:512
	s_add_u32 s6, s6, s54
	s_addc_u32 s7, s7, s55
	global_load_ushort v158, v134, s[6:7]
	global_load_ushort v174, v134, s[6:7] offset:512
	s_add_u32 s6, s6, s54
	s_addc_u32 s7, s7, s55
	global_load_ushort v159, v134, s[6:7]
	global_load_ushort v175, v134, s[6:7] offset:512
	s_add_u32 s6, s6, s54
	s_addc_u32 s7, s7, s55
	global_load_ushort v160, v134, s[6:7]
	global_load_ushort v176, v134, s[6:7] offset:512
	s_add_u32 s6, s6, s54
	s_addc_u32 s7, s7, s55
	global_load_ushort v161, v134, s[6:7]
	global_load_ushort v177, v134, s[6:7] offset:512
	s_add_u32 s6, s6, s54
	s_addc_u32 s7, s7, s55
	global_load_ushort v162, v134, s[6:7]
	global_load_ushort v178, v134, s[6:7] offset:512
	s_add_u32 s6, s6, s54
	s_addc_u32 s7, s7, s55
	global_load_ushort v163, v134, s[6:7]
	global_load_ushort v179, v134, s[6:7] offset:512
	s_add_u32 s6, s6, s54
	s_addc_u32 s7, s7, s55
	v_mul_f32_e32 v18, 0xbfb8aa3b, v70
	v_mul_f32_e32 v19, 0xbfb8aa3b, v71
	v_mul_f32_e32 v20, 0xbfb8aa3b, v72
	v_mul_f32_e32 v21, 0xbfb8aa3b, v73
	v_mul_f32_e32 v22, 0xbfb8aa3b, v74
	v_mul_f32_e32 v23, 0xbfb8aa3b, v75
	v_mul_f32_e32 v24, 0xbfb8aa3b, v76
	v_mul_f32_e32 v25, 0xbfb8aa3b, v77
	v_mul_f32_e32 v26, 0xbfb8aa3b, v78
	v_mul_f32_e32 v27, 0xbfb8aa3b, v79
	v_mul_f32_e32 v28, 0xbfb8aa3b, v80
	v_mul_f32_e32 v29, 0xbfb8aa3b, v81
	v_mul_f32_e32 v30, 0xbfb8aa3b, v82
	v_mul_f32_e32 v31, 0xbfb8aa3b, v83
	v_mul_f32_e32 v32, 0xbfb8aa3b, v84
	v_mul_f32_e32 v33, 0xbfb8aa3b, v85
	v_mul_f32_e32 v236, 0x3fb8aa3b, v70
	v_mul_f32_e32 v237, 0x3fb8aa3b, v71
	v_mul_f32_e32 v238, 0x3fb8aa3b, v72
	v_mul_f32_e32 v239, 0x3fb8aa3b, v73
; __device__ __forceinline__ unsigned f2bf(float f) { unsigned r; asm("v_cvt_pk_bf16_f32 %0, %1, %1" : "=v"(r) : "v"(f)); return r & 0xffffu; }
; __device__ __forceinline__ void gl1_item(PREF p, int l, int item, bool valid, LAS unsigned char* pl, int sw, int lane) {
;     ...
;             for (int ss = 0; ss < 16; ++ss) { const int s = g4 * 16 + ss; const int i = d ? 63 - s : s; const size_t rowi = (size_t)(row0 + i * rstride);
;                 bc += gv[ss];
;                 const float en = __expf(-bc), ep = __expf(bc);
;                 const float kt = kc[ss] * en, qt = qc[ss] * 0.125f * ep;
;                 const unsigned ktb = f2bf(kt);
;                 sKt[lane * 72 + i] = (bf16_t)ktb;
;                 QK[rowi * 1024 + d * 512 + h * 64 + lane] = (bf16_t)f2bf(qt);
;                 QK[rowi * 1024 + d * 512 + 256 + h * 64 + lane] = (bf16_t)ktb;
;             }
	v_mul_f32_e32 v240, 0x3fb8aa3b, v74
	v_mul_f32_e32 v241, 0x3fb8aa3b, v75
	v_mul_f32_e32 v242, 0x3fb8aa3b, v76
	v_mul_f32_e32 v243, 0x3fb8aa3b, v77
	v_mul_f32_e32 v244, 0x3fb8aa3b, v78
	v_mul_f32_e32 v245, 0x3fb8aa3b, v79
	v_mul_f32_e32 v246, 0x3fb8aa3b, v80
	v_mul_f32_e32 v247, 0x3fb8aa3b, v81
	v_mul_f32_e32 v248, 0x3fb8aa3b, v82
	v_mul_f32_e32 v249, 0x3fb8aa3b, v83
	v_mul_f32_e32 v250, 0x3fb8aa3b, v84
	v_mul_f32_e32 v251, 0x3fb8aa3b, v85
	v_exp_f32_e32 v18, v18
	v_exp_f32_e32 v19, v19
	v_exp_f32_e32 v20, v20
	v_exp_f32_e32 v21, v21
	v_exp_f32_e32 v22, v22
	v_exp_f32_e32 v23, v23
	v_exp_f32_e32 v24, v24
	v_exp_f32_e32 v25, v25
	v_exp_f32_e32 v26, v26
	v_exp_f32_e32 v27, v27
	v_exp_f32_e32 v28, v28
	v_exp_f32_e32 v29, v29
	v_exp_f32_e32 v30, v30
	v_exp_f32_e32 v31, v31
	v_exp_f32_e32 v32, v32
	v_exp_f32_e32 v33, v33
	v_exp_f32_e32 v236, v236
	v_exp_f32_e32 v237, v237
	v_exp_f32_e32 v238, v238
	v_exp_f32_e32 v239, v239
	v_exp_f32_e32 v240, v240
	v_exp_f32_e32 v241, v241
	v_exp_f32_e32 v242, v242
	v_exp_f32_e32 v243, v243
	v_exp_f32_e32 v244, v244
	v_exp_f32_e32 v245, v245
	v_exp_f32_e32 v246, v246
	v_exp_f32_e32 v247, v247
	v_exp_f32_e32 v248, v248
	v_exp_f32_e32 v249, v249
	v_exp_f32_e32 v250, v250
	v_exp_f32_e32 v251, v251
	v_lshlrev_b32_e32 v196, 16, v196
	v_lshlrev_b32_e32 v197, 16, v197
	v_lshlrev_b32_e32 v198, 16, v198
	v_lshlrev_b32_e32 v199, 16, v199
	v_lshlrev_b32_e32 v200, 16, v200
	v_lshlrev_b32_e32 v201, 16, v201
	v_lshlrev_b32_e32 v202, 16, v202
	v_lshlrev_b32_e32 v203, 16, v203
	v_lshlrev_b32_e32 v204, 16, v204
	v_lshlrev_b32_e32 v205, 16, v205
	v_lshlrev_b32_e32 v206, 16, v206
	v_lshlrev_b32_e32 v207, 16, v207
	v_lshlrev_b32_e32 v208, 16, v208
	v_lshlrev_b32_e32 v209, 16, v209
	v_lshlrev_b32_e32 v210, 16, v210
	v_lshlrev_b32_e32 v211, 16, v211
	v_lshlrev_b32_e32 v180, 16, v180
	v_lshlrev_b32_e32 v181, 16, v181
	v_lshlrev_b32_e32 v182, 16, v182
	v_lshlrev_b32_e32 v183, 16, v183
	v_lshlrev_b32_e32 v184, 16, v184
	v_lshlrev_b32_e32 v185, 16, v185
	v_lshlrev_b32_e32 v186, 16, v186
	v_lshlrev_b32_e32 v187, 16, v187
	v_lshlrev_b32_e32 v188, 16, v188
	v_lshlrev_b32_e32 v189, 16, v189
	v_lshlrev_b32_e32 v190, 16, v190
	v_lshlrev_b32_e32 v191, 16, v191
	v_lshlrev_b32_e32 v192, 16, v192
	v_lshlrev_b32_e32 v193, 16, v193
	v_lshlrev_b32_e32 v194, 16, v194
	v_lshlrev_b32_e32 v195, 16, v195
	v_mul_f32_e32 v196, v18, v196
	v_mul_f32_e32 v197, v19, v197
	v_mul_f32_e32 v198, v20, v198
	v_mul_f32_e32 v199, v21, v199
	v_mul_f32_e32 v200, v22, v200
	v_mul_f32_e32 v201, v23, v201
	v_mul_f32_e32 v202, v24, v202
	v_mul_f32_e32 v203, v25, v203
	v_mul_f32_e32 v204, v26, v204
	v_mul_f32_e32 v205, v27, v205
	v_mul_f32_e32 v206, v28, v206
	v_mul_f32_e32 v207, v29, v207
	v_mul_f32_e32 v208, v30, v208
	v_mul_f32_e32 v209, v31, v209
	v_mul_f32_e32 v210, v32, v210
	v_mul_f32_e32 v211, v33, v211
	v_mul_f32_e32 v180, 0x3e000000, v180
	v_mul_f32_e32 v181, 0x3e000000, v181
	v_mul_f32_e32 v182, 0x3e000000, v182
	v_mul_f32_e32 v183, 0x3e000000, v183
	v_mul_f32_e32 v184, 0x3e000000, v184
	v_mul_f32_e32 v185, 0x3e000000, v185
	v_mul_f32_e32 v186, 0x3e000000, v186
	v_mul_f32_e32 v187, 0x3e000000, v187
	v_mul_f32_e32 v188, 0x3e000000, v188
	v_mul_f32_e32 v189, 0x3e000000, v189
	v_mul_f32_e32 v190, 0x3e000000, v190
	v_mul_f32_e32 v191, 0x3e000000, v191
	v_mul_f32_e32 v192, 0x3e000000, v192
	v_mul_f32_e32 v193, 0x3e000000, v193
	v_mul_f32_e32 v194, 0x3e000000, v194
	v_mul_f32_e32 v195, 0x3e000000, v195
	v_mul_f32_e32 v180, v180, v236
	v_mul_f32_e32 v181, v181, v237
	v_mul_f32_e32 v182, v182, v238
	v_mul_f32_e32 v183, v183, v239
	v_mul_f32_e32 v184, v184, v240
	v_mul_f32_e32 v185, v185, v241
	v_mul_f32_e32 v186, v186, v242
	v_mul_f32_e32 v187, v187, v243
	v_mul_f32_e32 v188, v188, v244
	v_mul_f32_e32 v189, v189, v245
	v_mul_f32_e32 v190, v190, v246
	v_mul_f32_e32 v191, v191, v247
	v_mul_f32_e32 v192, v192, v248
	v_mul_f32_e32 v193, v193, v249
	v_mul_f32_e32 v194, v194, v250
	v_mul_f32_e32 v195, v195, v251
	v_cvt_pk_bf16_f32 v196, v196, v196
	v_cvt_pk_bf16_f32 v197, v197, v197
	v_cvt_pk_bf16_f32 v198, v198, v198
	v_cvt_pk_bf16_f32 v199, v199, v199
	v_cvt_pk_bf16_f32 v200, v200, v200
	v_cvt_pk_bf16_f32 v201, v201, v201
	v_cvt_pk_bf16_f32 v202, v202, v202
	v_cvt_pk_bf16_f32 v203, v203, v203
	v_cvt_pk_bf16_f32 v204, v204, v204
	v_cvt_pk_bf16_f32 v205, v205, v205
	v_cvt_pk_bf16_f32 v206, v206, v206
	v_cvt_pk_bf16_f32 v207, v207, v207
	v_cvt_pk_bf16_f32 v208, v208, v208
	v_cvt_pk_bf16_f32 v209, v209, v209
	v_cvt_pk_bf16_f32 v210, v210, v210
	v_cvt_pk_bf16_f32 v211, v211, v211
	v_cvt_pk_bf16_f32 v180, v180, v180
	v_cvt_pk_bf16_f32 v181, v181, v181
	v_cvt_pk_bf16_f32 v182, v182, v182
	v_cvt_pk_bf16_f32 v183, v183, v183
	v_cvt_pk_bf16_f32 v184, v184, v184
	v_cvt_pk_bf16_f32 v185, v185, v185
	v_cvt_pk_bf16_f32 v186, v186, v186
	v_cvt_pk_bf16_f32 v187, v187, v187
	v_cvt_pk_bf16_f32 v188, v188, v188
	v_cvt_pk_bf16_f32 v189, v189, v189
	v_cvt_pk_bf16_f32 v190, v190, v190
	v_cvt_pk_bf16_f32 v191, v191, v191
	v_cvt_pk_bf16_f32 v192, v192, v192
	v_cvt_pk_bf16_f32 v193, v193, v193
	v_cvt_pk_bf16_f32 v194, v194, v194
	v_cvt_pk_bf16_f32 v195, v195, v195
	ds_write_b16 v60, v196
	v_add_u32_e32 v60, v61, v60
	global_store_short v134, v180, s[4:5]
	global_store_short v134, v196, s[4:5] offset:512
	s_add_u32 s4, s4, s56
	s_addc_u32 s5, s5, s3
	ds_write_b16 v60, v197
	v_add_u32_e32 v60, v61, v60
	global_store_short v134, v181, s[4:5]
	global_store_short v134, v197, s[4:5] offset:512
	s_add_u32 s4, s4, s56
	s_addc_u32 s5, s5, s3
	ds_write_b16 v60, v198
	v_add_u32_e32 v60, v61, v60
	global_store_short v134, v182, s[4:5]
	global_store_short v134, v198, s[4:5] offset:512
	s_add_u32 s4, s4, s56
; __device__ __forceinline__ unsigned f2bf(float f) { unsigned r; asm("v_cvt_pk_bf16_f32 %0, %1, %1" : "=v"(r) : "v"(f)); return r & 0xffffu; }
; __device__ __forceinline__ void gl1_item(PREF p, int l, int item, bool valid, LAS unsigned char* pl, int sw, int lane) {
;     ...
;             for (int ss = 0; ss < 16; ++ss) { const int s = g4 * 16 + ss; const int i = d ? 63 - s : s;
;                 float z = bup;
; #pragma unroll
;                 for (int r2 = 0; r2 < 8; ++r2) { const unsigned w = (unsigned)__builtin_amdgcn_readlane((int)lrp[r2], i);
;                     z = __builtin_amdgcn_fdot2_f32_bf16(__builtin_bit_cast(bf16x2_t, w), __builtin_bit_cast(bf16x2_t, wupp[r2]), z, false); }
;     ...
;             for (int ss = 0; ss < 16; ++ss) { const int s = g4 * 16 + ss; const int i = d ? 63 - s : s; const size_t rowi = (size_t)(row0 + i * rstride);
;                 bc += gv[ss];
;                 const float en = __expf(-bc), ep = __expf(bc);
;                 const float kt = kc[ss] * en, qt = qc[ss] * 0.125f * ep;
;                 const unsigned ktb = f2bf(kt);
;                 sKt[lane * 72 + i] = (bf16_t)ktb;
;                 QK[rowi * 1024 + d * 512 + h * 64 + lane] = (bf16_t)f2bf(qt);
;                 QK[rowi * 1024 + d * 512 + 256 + h * 64 + lane] = (bf16_t)ktb;
;             }
	s_addc_u32 s5, s5, s3
	ds_write_b16 v60, v199
	v_add_u32_e32 v60, v61, v60
	global_store_short v134, v183, s[4:5]
	global_store_short v134, v199, s[4:5] offset:512
	s_add_u32 s4, s4, s56
	s_addc_u32 s5, s5, s3
	ds_write_b16 v60, v200
	v_add_u32_e32 v60, v61, v60
	global_store_short v134, v184, s[4:5]
	global_store_short v134, v200, s[4:5] offset:512
	s_add_u32 s4, s4, s56
	s_addc_u32 s5, s5, s3
	ds_write_b16 v60, v201
	v_add_u32_e32 v60, v61, v60
	global_store_short v134, v185, s[4:5]
	global_store_short v134, v201, s[4:5] offset:512
	s_add_u32 s4, s4, s56
	s_addc_u32 s5, s5, s3
	ds_write_b16 v60, v202
	v_add_u32_e32 v60, v61, v60
	global_store_short v134, v186, s[4:5]
	global_store_short v134, v202, s[4:5] offset:512
	s_add_u32 s4, s4, s56
	s_addc_u32 s5, s5, s3
	ds_write_b16 v60, v203
	v_add_u32_e32 v60, v61, v60
	global_store_short v134, v187, s[4:5]
	global_store_short v134, v203, s[4:5] offset:512
	s_add_u32 s4, s4, s56
	s_addc_u32 s5, s5, s3
	ds_write_b16 v60, v204
	v_add_u32_e32 v60, v61, v60
	global_store_short v134, v188, s[4:5]
	global_store_short v134, v204, s[4:5] offset:512
	s_add_u32 s4, s4, s56
	s_addc_u32 s5, s5, s3
	ds_write_b16 v60, v205
	v_add_u32_e32 v60, v61, v60
	global_store_short v134, v189, s[4:5]
	global_store_short v134, v205, s[4:5] offset:512
	s_add_u32 s4, s4, s56
	s_addc_u32 s5, s5, s3
	ds_write_b16 v60, v206
	v_add_u32_e32 v60, v61, v60
	global_store_short v134, v190, s[4:5]
	global_store_short v134, v206, s[4:5] offset:512
	s_add_u32 s4, s4, s56
	s_addc_u32 s5, s5, s3
	ds_write_b16 v60, v207
	v_add_u32_e32 v60, v61, v60
	global_store_short v134, v191, s[4:5]
	global_store_short v134, v207, s[4:5] offset:512
	s_add_u32 s4, s4, s56
	s_addc_u32 s5, s5, s3
	ds_write_b16 v60, v208
	v_add_u32_e32 v60, v61, v60
	global_store_short v134, v192, s[4:5]
	global_store_short v134, v208, s[4:5] offset:512
	s_add_u32 s4, s4, s56
	s_addc_u32 s5, s5, s3
	ds_write_b16 v60, v209
	v_add_u32_e32 v60, v61, v60
	global_store_short v134, v193, s[4:5]
	global_store_short v134, v209, s[4:5] offset:512
	s_add_u32 s4, s4, s56
	s_addc_u32 s5, s5, s3
	ds_write_b16 v60, v210
	v_add_u32_e32 v60, v61, v60
	global_store_short v134, v194, s[4:5]
	global_store_short v134, v210, s[4:5] offset:512
	s_add_u32 s4, s4, s56
	s_addc_u32 s5, s5, s3
	ds_write_b16 v60, v211
	v_add_u32_e32 v60, v61, v60
	global_store_short v134, v195, s[4:5]
	global_store_short v134, v211, s[4:5] offset:512
	s_add_u32 s4, s4, s56
	s_addc_u32 s5, s5, s3
	v_mov_b32_e32 v236, v16
	v_readlane_b32 s45, v0, s30
	v_readlane_b32 s46, v1, s30
	v_readlane_b32 s47, v2, s30
	v_readlane_b32 s48, v3, s30
	v_readlane_b32 s49, v4, s30
	v_readlane_b32 s50, v5, s30
	v_readlane_b32 s51, v6, s30
	v_readlane_b32 s52, v7, s30
	s_add_i32 s30, s30, s2
	v_dot2c_f32_bf16_e32 v236, s45, v8
	v_dot2c_f32_bf16_e32 v236, s46, v9
	v_dot2c_f32_bf16_e32 v236, s47, v10
	v_dot2c_f32_bf16_e32 v236, s48, v11
	v_dot2c_f32_bf16_e32 v236, s49, v12
	v_dot2c_f32_bf16_e32 v236, s50, v13
	v_dot2c_f32_bf16_e32 v236, s51, v14
	v_dot2c_f32_bf16_e32 v236, s52, v15
	v_mov_b32_e32 v237, v16
	v_readlane_b32 s45, v0, s30
	v_readlane_b32 s46, v1, s30
	v_readlane_b32 s47, v2, s30
	v_readlane_b32 s48, v3, s30
	v_readlane_b32 s49, v4, s30
	v_readlane_b32 s50, v5, s30
	v_readlane_b32 s51, v6, s30
	v_readlane_b32 s52, v7, s30
	s_add_i32 s30, s30, s2
	v_dot2c_f32_bf16_e32 v237, s45, v8
	v_dot2c_f32_bf16_e32 v237, s46, v9
	v_dot2c_f32_bf16_e32 v237, s47, v10
	v_dot2c_f32_bf16_e32 v237, s48, v11
	v_dot2c_f32_bf16_e32 v237, s49, v12
	v_dot2c_f32_bf16_e32 v237, s50, v13
	v_dot2c_f32_bf16_e32 v237, s51, v14
	v_dot2c_f32_bf16_e32 v237, s52, v15
	v_mov_b32_e32 v238, v16
	v_readlane_b32 s45, v0, s30
	v_readlane_b32 s46, v1, s30
	v_readlane_b32 s47, v2, s30
	v_readlane_b32 s48, v3, s30
	v_readlane_b32 s49, v4, s30
	v_readlane_b32 s50, v5, s30
	v_readlane_b32 s51, v6, s30
	v_readlane_b32 s52, v7, s30
	s_add_i32 s30, s30, s2
	v_dot2c_f32_bf16_e32 v238, s45, v8
	v_dot2c_f32_bf16_e32 v238, s46, v9
	v_dot2c_f32_bf16_e32 v238, s47, v10
	v_dot2c_f32_bf16_e32 v238, s48, v11
	v_dot2c_f32_bf16_e32 v238, s49, v12
	v_dot2c_f32_bf16_e32 v238, s50, v13
	v_dot2c_f32_bf16_e32 v238, s51, v14
	v_dot2c_f32_bf16_e32 v238, s52, v15
	v_mov_b32_e32 v239, v16
	v_readlane_b32 s45, v0, s30
	v_readlane_b32 s46, v1, s30
	v_readlane_b32 s47, v2, s30
	v_readlane_b32 s48, v3, s30
	v_readlane_b32 s49, v4, s30
	v_readlane_b32 s50, v5, s30
	v_readlane_b32 s51, v6, s30
	v_readlane_b32 s52, v7, s30
	s_add_i32 s30, s30, s2
	v_dot2c_f32_bf16_e32 v239, s45, v8
	v_dot2c_f32_bf16_e32 v239, s46, v9
	v_dot2c_f32_bf16_e32 v239, s47, v10
	v_dot2c_f32_bf16_e32 v239, s48, v11
	v_dot2c_f32_bf16_e32 v239, s49, v12
	v_dot2c_f32_bf16_e32 v239, s50, v13
	v_dot2c_f32_bf16_e32 v239, s51, v14
	v_dot2c_f32_bf16_e32 v239, s52, v15
	v_mov_b32_e32 v240, v16
	v_readlane_b32 s45, v0, s30
	v_readlane_b32 s46, v1, s30
	v_readlane_b32 s47, v2, s30
	v_readlane_b32 s48, v3, s30
	v_readlane_b32 s49, v4, s30
	v_readlane_b32 s50, v5, s30
	v_readlane_b32 s51, v6, s30
	v_readlane_b32 s52, v7, s30
	s_add_i32 s30, s30, s2
	v_dot2c_f32_bf16_e32 v240, s45, v8
	v_dot2c_f32_bf16_e32 v240, s46, v9
	v_dot2c_f32_bf16_e32 v240, s47, v10
	v_dot2c_f32_bf16_e32 v240, s48, v11
	v_dot2c_f32_bf16_e32 v240, s49, v12
	v_dot2c_f32_bf16_e32 v240, s50, v13
	v_dot2c_f32_bf16_e32 v240, s51, v14
	v_dot2c_f32_bf16_e32 v240, s52, v15
	v_mov_b32_e32 v241, v16
	v_readlane_b32 s45, v0, s30
	v_readlane_b32 s46, v1, s30
	v_readlane_b32 s47, v2, s30
	v_readlane_b32 s48, v3, s30
	v_readlane_b32 s49, v4, s30
	v_readlane_b32 s50, v5, s30
	v_readlane_b32 s51, v6, s30
	v_readlane_b32 s52, v7, s30
	s_add_i32 s30, s30, s2
; __device__ __forceinline__ void gl1_item(PREF p, int l, int item, bool valid, LAS unsigned char* pl, int sw, int lane) {
;     ...
;             for (int ss = 0; ss < 16; ++ss) { const int s = g4 * 16 + ss; const int i = d ? 63 - s : s;
;                 float z = bup;
; #pragma unroll
;                 for (int r2 = 0; r2 < 8; ++r2) { const unsigned w = (unsigned)__builtin_amdgcn_readlane((int)lrp[r2], i);
;                     z = __builtin_amdgcn_fdot2_f32_bf16(__builtin_bit_cast(bf16x2_t, w), __builtin_bit_cast(bf16x2_t, wupp[r2]), z, false); }
	v_dot2c_f32_bf16_e32 v241, s45, v8
	v_dot2c_f32_bf16_e32 v241, s46, v9
	v_dot2c_f32_bf16_e32 v241, s47, v10
	v_dot2c_f32_bf16_e32 v241, s48, v11
	v_dot2c_f32_bf16_e32 v241, s49, v12
	v_dot2c_f32_bf16_e32 v241, s50, v13
	v_dot2c_f32_bf16_e32 v241, s51, v14
	v_dot2c_f32_bf16_e32 v241, s52, v15
	v_mov_b32_e32 v242, v16
	v_readlane_b32 s45, v0, s30
	v_readlane_b32 s46, v1, s30
	v_readlane_b32 s47, v2, s30
	v_readlane_b32 s48, v3, s30
	v_readlane_b32 s49, v4, s30
	v_readlane_b32 s50, v5, s30
	v_readlane_b32 s51, v6, s30
	v_readlane_b32 s52, v7, s30
	s_add_i32 s30, s30, s2
	v_dot2c_f32_bf16_e32 v242, s45, v8
	v_dot2c_f32_bf16_e32 v242, s46, v9
	v_dot2c_f32_bf16_e32 v242, s47, v10
	v_dot2c_f32_bf16_e32 v242, s48, v11
	v_dot2c_f32_bf16_e32 v242, s49, v12
	v_dot2c_f32_bf16_e32 v242, s50, v13
	v_dot2c_f32_bf16_e32 v242, s51, v14
	v_dot2c_f32_bf16_e32 v242, s52, v15
	v_mov_b32_e32 v243, v16
	v_readlane_b32 s45, v0, s30
	v_readlane_b32 s46, v1, s30
	v_readlane_b32 s47, v2, s30
	v_readlane_b32 s48, v3, s30
	v_readlane_b32 s49, v4, s30
	v_readlane_b32 s50, v5, s30
	v_readlane_b32 s51, v6, s30
	v_readlane_b32 s52, v7, s30
	s_add_i32 s30, s30, s2
	v_dot2c_f32_bf16_e32 v243, s45, v8
	v_dot2c_f32_bf16_e32 v243, s46, v9
	v_dot2c_f32_bf16_e32 v243, s47, v10
	v_dot2c_f32_bf16_e32 v243, s48, v11
	v_dot2c_f32_bf16_e32 v243, s49, v12
	v_dot2c_f32_bf16_e32 v243, s50, v13
	v_dot2c_f32_bf16_e32 v243, s51, v14
	v_dot2c_f32_bf16_e32 v243, s52, v15
	v_mov_b32_e32 v244, v16
	v_readlane_b32 s45, v0, s30
	v_readlane_b32 s46, v1, s30
	v_readlane_b32 s47, v2, s30
	v_readlane_b32 s48, v3, s30
	v_readlane_b32 s49, v4, s30
	v_readlane_b32 s50, v5, s30
	v_readlane_b32 s51, v6, s30
	v_readlane_b32 s52, v7, s30
	s_add_i32 s30, s30, s2
	v_dot2c_f32_bf16_e32 v244, s45, v8
	v_dot2c_f32_bf16_e32 v244, s46, v9
	v_dot2c_f32_bf16_e32 v244, s47, v10
	v_dot2c_f32_bf16_e32 v244, s48, v11
	v_dot2c_f32_bf16_e32 v244, s49, v12
	v_dot2c_f32_bf16_e32 v244, s50, v13
	v_dot2c_f32_bf16_e32 v244, s51, v14
	v_dot2c_f32_bf16_e32 v244, s52, v15
	v_mov_b32_e32 v245, v16
	v_readlane_b32 s45, v0, s30
	v_readlane_b32 s46, v1, s30
	v_readlane_b32 s47, v2, s30
	v_readlane_b32 s48, v3, s30
	v_readlane_b32 s49, v4, s30
	v_readlane_b32 s50, v5, s30
	v_readlane_b32 s51, v6, s30
	v_readlane_b32 s52, v7, s30
	s_add_i32 s30, s30, s2
	v_dot2c_f32_bf16_e32 v245, s45, v8
	v_dot2c_f32_bf16_e32 v245, s46, v9
	v_dot2c_f32_bf16_e32 v245, s47, v10
	v_dot2c_f32_bf16_e32 v245, s48, v11
	v_dot2c_f32_bf16_e32 v245, s49, v12
	v_dot2c_f32_bf16_e32 v245, s50, v13
	v_dot2c_f32_bf16_e32 v245, s51, v14
	v_dot2c_f32_bf16_e32 v245, s52, v15
	v_mov_b32_e32 v246, v16
	v_readlane_b32 s45, v0, s30
	v_readlane_b32 s46, v1, s30
	v_readlane_b32 s47, v2, s30
	v_readlane_b32 s48, v3, s30
	v_readlane_b32 s49, v4, s30
	v_readlane_b32 s50, v5, s30
	v_readlane_b32 s51, v6, s30
	v_readlane_b32 s52, v7, s30
	s_add_i32 s30, s30, s2
	v_dot2c_f32_bf16_e32 v246, s45, v8
	v_dot2c_f32_bf16_e32 v246, s46, v9
	v_dot2c_f32_bf16_e32 v246, s47, v10
	v_dot2c_f32_bf16_e32 v246, s48, v11
	v_dot2c_f32_bf16_e32 v246, s49, v12
	v_dot2c_f32_bf16_e32 v246, s50, v13
	v_dot2c_f32_bf16_e32 v246, s51, v14
	v_dot2c_f32_bf16_e32 v246, s52, v15
	v_mov_b32_e32 v247, v16
	v_readlane_b32 s45, v0, s30
	v_readlane_b32 s46, v1, s30
	v_readlane_b32 s47, v2, s30
	v_readlane_b32 s48, v3, s30
	v_readlane_b32 s49, v4, s30
	v_readlane_b32 s50, v5, s30
	v_readlane_b32 s51, v6, s30
	v_readlane_b32 s52, v7, s30
	s_add_i32 s30, s30, s2
	v_dot2c_f32_bf16_e32 v247, s45, v8
	v_dot2c_f32_bf16_e32 v247, s46, v9
	v_dot2c_f32_bf16_e32 v247, s47, v10
	v_dot2c_f32_bf16_e32 v247, s48, v11
	v_dot2c_f32_bf16_e32 v247, s49, v12
	v_dot2c_f32_bf16_e32 v247, s50, v13
	v_dot2c_f32_bf16_e32 v247, s51, v14
	v_dot2c_f32_bf16_e32 v247, s52, v15
	v_mov_b32_e32 v248, v16
	v_readlane_b32 s45, v0, s30
	v_readlane_b32 s46, v1, s30
	v_readlane_b32 s47, v2, s30
	v_readlane_b32 s48, v3, s30
	v_readlane_b32 s49, v4, s30
	v_readlane_b32 s50, v5, s30
	v_readlane_b32 s51, v6, s30
	v_readlane_b32 s52, v7, s30
	s_add_i32 s30, s30, s2
	v_dot2c_f32_bf16_e32 v248, s45, v8
	v_dot2c_f32_bf16_e32 v248, s46, v9
	v_dot2c_f32_bf16_e32 v248, s47, v10
	v_dot2c_f32_bf16_e32 v248, s48, v11
	v_dot2c_f32_bf16_e32 v248, s49, v12
	v_dot2c_f32_bf16_e32 v248, s50, v13
	v_dot2c_f32_bf16_e32 v248, s51, v14
	v_dot2c_f32_bf16_e32 v248, s52, v15
	v_mov_b32_e32 v249, v16
	v_readlane_b32 s45, v0, s30
	v_readlane_b32 s46, v1, s30
	v_readlane_b32 s47, v2, s30
	v_readlane_b32 s48, v3, s30
	v_readlane_b32 s49, v4, s30
	v_readlane_b32 s50, v5, s30
	v_readlane_b32 s51, v6, s30
	v_readlane_b32 s52, v7, s30
	s_add_i32 s30, s30, s2
	v_dot2c_f32_bf16_e32 v249, s45, v8
	v_dot2c_f32_bf16_e32 v249, s46, v9
	v_dot2c_f32_bf16_e32 v249, s47, v10
	v_dot2c_f32_bf16_e32 v249, s48, v11
	v_dot2c_f32_bf16_e32 v249, s49, v12
	v_dot2c_f32_bf16_e32 v249, s50, v13
	v_dot2c_f32_bf16_e32 v249, s51, v14
	v_dot2c_f32_bf16_e32 v249, s52, v15
	v_mov_b32_e32 v250, v16
	v_readlane_b32 s45, v0, s30
	v_readlane_b32 s46, v1, s30
	v_readlane_b32 s47, v2, s30
	v_readlane_b32 s48, v3, s30
	v_readlane_b32 s49, v4, s30
	v_readlane_b32 s50, v5, s30
	v_readlane_b32 s51, v6, s30
	v_readlane_b32 s52, v7, s30
	s_add_i32 s30, s30, s2
	v_dot2c_f32_bf16_e32 v250, s45, v8
	v_dot2c_f32_bf16_e32 v250, s46, v9
	v_dot2c_f32_bf16_e32 v250, s47, v10
	v_dot2c_f32_bf16_e32 v250, s48, v11
	v_dot2c_f32_bf16_e32 v250, s49, v12
	v_dot2c_f32_bf16_e32 v250, s50, v13
	v_dot2c_f32_bf16_e32 v250, s51, v14
	v_dot2c_f32_bf16_e32 v250, s52, v15
	v_mov_b32_e32 v251, v16
	v_readlane_b32 s45, v0, s30
	v_readlane_b32 s46, v1, s30
	v_readlane_b32 s47, v2, s30
	v_readlane_b32 s48, v3, s30
	v_readlane_b32 s49, v4, s30
; __device__ __forceinline__ void gl1_item(PREF p, int l, int item, bool valid, LAS unsigned char* pl, int sw, int lane) {
;     ...
;             for (int ss = 0; ss < 16; ++ss) { const int s = g4 * 16 + ss; const int i = d ? 63 - s : s;
;                 float z = bup;
; #pragma unroll
;                 for (int r2 = 0; r2 < 8; ++r2) { const unsigned w = (unsigned)__builtin_amdgcn_readlane((int)lrp[r2], i);
;                     z = __builtin_amdgcn_fdot2_f32_bf16(__builtin_bit_cast(bf16x2_t, w), __builtin_bit_cast(bf16x2_t, wupp[r2]), z, false); }
;                 gv[ss] = -(fmaxf(-z, 0.f) + __logf(1.f + __expf(-fabsf(z)))) * (1.f / 16.f);
;                 __builtin_amdgcn_sched_barrier(0);
;             }
; #pragma unroll
;             for (int ss = 0; ss < 16; ++ss) { const int s = g4 * 16 + ss; const int i = d ? 63 - s : s; const size_t rowi = (size_t)(row0 + i * rstride);
;                 bc += gv[ss];
;                 const float en = __expf(-bc), ep = __expf(bc);
;                 const float kt = kc[ss] * en, qt = qc[ss] * 0.125f * ep;
	v_readlane_b32 s50, v5, s30
	v_readlane_b32 s51, v6, s30
	v_readlane_b32 s52, v7, s30
	s_add_i32 s30, s30, s2
	v_dot2c_f32_bf16_e32 v251, s45, v8
	v_dot2c_f32_bf16_e32 v251, s46, v9
	v_dot2c_f32_bf16_e32 v251, s47, v10
	v_dot2c_f32_bf16_e32 v251, s48, v11
	v_dot2c_f32_bf16_e32 v251, s49, v12
	v_dot2c_f32_bf16_e32 v251, s50, v13
	v_dot2c_f32_bf16_e32 v251, s51, v14
	v_dot2c_f32_bf16_e32 v251, s52, v15
	s_nop 2
	v_mul_f32_e64 v18, |v236|, s1
	v_mul_f32_e64 v19, |v237|, s1
	v_mul_f32_e64 v20, |v238|, s1
	v_mul_f32_e64 v21, |v239|, s1
	v_mul_f32_e64 v22, |v240|, s1
	v_mul_f32_e64 v23, |v241|, s1
	v_mul_f32_e64 v24, |v242|, s1
	v_mul_f32_e64 v25, |v243|, s1
	v_mul_f32_e64 v26, |v244|, s1
	v_mul_f32_e64 v27, |v245|, s1
	v_mul_f32_e64 v28, |v246|, s1
	v_mul_f32_e64 v29, |v247|, s1
	v_mul_f32_e64 v30, |v248|, s1
	v_mul_f32_e64 v31, |v249|, s1
	v_mul_f32_e64 v32, |v250|, s1
	v_mul_f32_e64 v33, |v251|, s1
	v_exp_f32_e32 v18, v18
	v_exp_f32_e32 v19, v19
	v_exp_f32_e32 v20, v20
	v_exp_f32_e32 v21, v21
	v_exp_f32_e32 v22, v22
	v_exp_f32_e32 v23, v23
	v_exp_f32_e32 v24, v24
	v_exp_f32_e32 v25, v25
	v_exp_f32_e32 v26, v26
	v_exp_f32_e32 v27, v27
	v_exp_f32_e32 v28, v28
	v_exp_f32_e32 v29, v29
	v_exp_f32_e32 v30, v30
	v_exp_f32_e32 v31, v31
	v_exp_f32_e32 v32, v32
	v_exp_f32_e32 v33, v33
	v_max_f32_e64 v236, -v236, -v236
	v_max_f32_e64 v237, -v237, -v237
	v_max_f32_e64 v238, -v238, -v238
	v_max_f32_e64 v239, -v239, -v239
	v_max_f32_e64 v240, -v240, -v240
	v_max_f32_e64 v241, -v241, -v241
	v_max_f32_e64 v242, -v242, -v242
	v_max_f32_e64 v243, -v243, -v243
	v_max_f32_e64 v244, -v244, -v244
	v_max_f32_e64 v245, -v245, -v245
	v_max_f32_e64 v246, -v246, -v246
	v_max_f32_e64 v247, -v247, -v247
	v_max_f32_e64 v248, -v248, -v248
	v_max_f32_e64 v249, -v249, -v249
	v_max_f32_e64 v250, -v250, -v250
	v_max_f32_e64 v251, -v251, -v251
	v_max_f32_e32 v236, 0, v236
	v_max_f32_e32 v237, 0, v237
	v_max_f32_e32 v238, 0, v238
	v_max_f32_e32 v239, 0, v239
	v_max_f32_e32 v240, 0, v240
	v_max_f32_e32 v241, 0, v241
	v_max_f32_e32 v242, 0, v242
	v_max_f32_e32 v243, 0, v243
	v_max_f32_e32 v244, 0, v244
	v_max_f32_e32 v245, 0, v245
	v_max_f32_e32 v246, 0, v246
	v_max_f32_e32 v247, 0, v247
	v_max_f32_e32 v248, 0, v248
	v_max_f32_e32 v249, 0, v249
	v_max_f32_e32 v250, 0, v250
	v_max_f32_e32 v251, 0, v251
	v_add_f32_e32 v18, 1.0, v18
	v_add_f32_e32 v19, 1.0, v19
	v_add_f32_e32 v20, 1.0, v20
	v_add_f32_e32 v21, 1.0, v21
	v_add_f32_e32 v22, 1.0, v22
	v_add_f32_e32 v23, 1.0, v23
	v_add_f32_e32 v24, 1.0, v24
	v_add_f32_e32 v25, 1.0, v25
	v_add_f32_e32 v26, 1.0, v26
	v_add_f32_e32 v27, 1.0, v27
	v_add_f32_e32 v28, 1.0, v28
	v_add_f32_e32 v29, 1.0, v29
	v_add_f32_e32 v30, 1.0, v30
	v_add_f32_e32 v31, 1.0, v31
	v_add_f32_e32 v32, 1.0, v32
	v_add_f32_e32 v33, 1.0, v33
	v_log_f32_e32 v18, v18
	v_log_f32_e32 v19, v19
	v_log_f32_e32 v20, v20
	v_log_f32_e32 v21, v21
	v_log_f32_e32 v22, v22
	v_log_f32_e32 v23, v23
	v_log_f32_e32 v24, v24
	v_log_f32_e32 v25, v25
	v_log_f32_e32 v26, v26
	v_log_f32_e32 v27, v27
	v_log_f32_e32 v28, v28
	v_log_f32_e32 v29, v29
	v_log_f32_e32 v30, v30
	v_log_f32_e32 v31, v31
	v_log_f32_e32 v32, v32
	v_log_f32_e32 v33, v33
	s_mov_b32 s45, 0x3f317217
	v_mul_f32_e32 v70, 0x3f317217, v18
	v_mul_f32_e32 v71, 0x3f317217, v19
	v_mul_f32_e32 v72, 0x3f317217, v20
	v_mul_f32_e32 v73, 0x3f317217, v21
	v_mul_f32_e32 v74, 0x3f317217, v22
	v_mul_f32_e32 v75, 0x3f317217, v23
	v_mul_f32_e32 v76, 0x3f317217, v24
	v_mul_f32_e32 v77, 0x3f317217, v25
	v_mul_f32_e32 v78, 0x3f317217, v26
	v_mul_f32_e32 v79, 0x3f317217, v27
	v_mul_f32_e32 v80, 0x3f317217, v28
	v_mul_f32_e32 v81, 0x3f317217, v29
	v_mul_f32_e32 v82, 0x3f317217, v30
	v_mul_f32_e32 v83, 0x3f317217, v31
	v_mul_f32_e32 v84, 0x3f317217, v32
	v_mul_f32_e32 v85, 0x3f317217, v33
	v_fma_f32 v70, v18, s45, -v70
	v_fma_f32 v71, v19, s45, -v71
	v_fma_f32 v72, v20, s45, -v72
	v_fma_f32 v73, v21, s45, -v73
	v_fma_f32 v74, v22, s45, -v74
	v_fma_f32 v75, v23, s45, -v75
	v_fma_f32 v76, v24, s45, -v76
	v_fma_f32 v77, v25, s45, -v77
	v_fma_f32 v78, v26, s45, -v78
	v_fma_f32 v79, v27, s45, -v79
	v_fma_f32 v80, v28, s45, -v80
	v_fma_f32 v81, v29, s45, -v81
	v_fma_f32 v82, v30, s45, -v82
	v_fma_f32 v83, v31, s45, -v83
	v_fma_f32 v84, v32, s45, -v84
	v_fma_f32 v85, v33, s45, -v85
	v_fmac_f32_e32 v70, 0x3377d1cf, v18
	v_fmac_f32_e32 v71, 0x3377d1cf, v19
	v_fmac_f32_e32 v72, 0x3377d1cf, v20
	v_fmac_f32_e32 v73, 0x3377d1cf, v21
	v_fmac_f32_e32 v74, 0x3377d1cf, v22
	v_fmac_f32_e32 v75, 0x3377d1cf, v23
	v_fmac_f32_e32 v76, 0x3377d1cf, v24
	v_fmac_f32_e32 v77, 0x3377d1cf, v25
	v_fmac_f32_e32 v78, 0x3377d1cf, v26
	v_fmac_f32_e32 v79, 0x3377d1cf, v27
	v_fmac_f32_e32 v80, 0x3377d1cf, v28
	v_fmac_f32_e32 v81, 0x3377d1cf, v29
	v_fmac_f32_e32 v82, 0x3377d1cf, v30
	v_fmac_f32_e32 v83, 0x3377d1cf, v31
	v_fmac_f32_e32 v84, 0x3377d1cf, v32
	v_fmac_f32_e32 v85, 0x3377d1cf, v33
	v_fmac_f32_e32 v70, 0x3f317217, v18
	v_fmac_f32_e32 v71, 0x3f317217, v19
	v_fmac_f32_e32 v72, 0x3f317217, v20
	v_fmac_f32_e32 v73, 0x3f317217, v21
	v_fmac_f32_e32 v74, 0x3f317217, v22
	v_fmac_f32_e32 v75, 0x3f317217, v23
	v_fmac_f32_e32 v76, 0x3f317217, v24
	v_fmac_f32_e32 v77, 0x3f317217, v25
	v_fmac_f32_e32 v78, 0x3f317217, v26
	v_fmac_f32_e32 v79, 0x3f317217, v27
	v_fmac_f32_e32 v80, 0x3f317217, v28
	v_fmac_f32_e32 v81, 0x3f317217, v29
	v_fmac_f32_e32 v82, 0x3f317217, v30
	v_fmac_f32_e32 v83, 0x3f317217, v31
	v_fmac_f32_e32 v84, 0x3f317217, v32
	v_fmac_f32_e32 v85, 0x3f317217, v33
	v_add_f32_e32 v236, v236, v70
	v_add_f32_e32 v237, v237, v71
	v_add_f32_e32 v238, v238, v72
	v_add_f32_e32 v239, v239, v73
	v_add_f32_e32 v240, v240, v74
	v_add_f32_e32 v241, v241, v75
	v_add_f32_e32 v242, v242, v76
	v_add_f32_e32 v243, v243, v77
	v_add_f32_e32 v244, v244, v78
	v_add_f32_e32 v245, v245, v79
	v_add_f32_e32 v246, v246, v80
	v_add_f32_e32 v247, v247, v81
	v_add_f32_e32 v248, v248, v82
	v_add_f32_e32 v249, v249, v83
	v_add_f32_e32 v250, v250, v84
	v_add_f32_e32 v251, v251, v85
	v_mov_b32_e32 v70, v17
	v_fmac_f32_e32 v70, 0xbd800000, v236
	v_mov_b32_e32 v71, v70
	v_fmac_f32_e32 v71, 0xbd800000, v237
	v_mov_b32_e32 v72, v71
	v_fmac_f32_e32 v72, 0xbd800000, v238
	v_mov_b32_e32 v73, v72
	v_fmac_f32_e32 v73, 0xbd800000, v239
	v_mov_b32_e32 v74, v73
	v_fmac_f32_e32 v74, 0xbd800000, v240
	v_mov_b32_e32 v75, v74
	v_fmac_f32_e32 v75, 0xbd800000, v241
	v_mov_b32_e32 v76, v75
	v_fmac_f32_e32 v76, 0xbd800000, v242
	v_mov_b32_e32 v77, v76
	v_fmac_f32_e32 v77, 0xbd800000, v243
	v_mov_b32_e32 v78, v77
	v_fmac_f32_e32 v78, 0xbd800000, v244
	v_mov_b32_e32 v79, v78
	v_fmac_f32_e32 v79, 0xbd800000, v245
	v_mov_b32_e32 v80, v79
	v_fmac_f32_e32 v80, 0xbd800000, v246
	v_mov_b32_e32 v81, v80
	v_fmac_f32_e32 v81, 0xbd800000, v247
	v_mov_b32_e32 v82, v81
	v_fmac_f32_e32 v82, 0xbd800000, v248
	v_mov_b32_e32 v83, v82
	v_fmac_f32_e32 v83, 0xbd800000, v249
	v_mov_b32_e32 v84, v83
	v_fmac_f32_e32 v84, 0xbd800000, v250
	v_mov_b32_e32 v85, v84
	v_fmac_f32_e32 v85, 0xbd800000, v251
	v_mov_b32_e32 v17, v85
	s_waitcnt vmcnt(32)
; __device__ __forceinline__ void gl1_item(PREF p, int l, int item, bool valid, LAS unsigned char* pl, int sw, int lane) {
;     ...
;                 for (int ss = 0; ss < 16; ++ss) { const int s = (g4 + 1) * 16 + ss; const int i = d ? 63 - s : s; const bf16_t* pr = P + (size_t)(row0 + i * rstride) * PW + h * 64 + lane;
;                     qn[ss] = __builtin_bit_cast(float, (unsigned)pr[1024]); kn[ss] = __builtin_bit_cast(float, (unsigned)pr[1280]); }
;     ...
;                 const float en = __expf(-bc), ep = __expf(bc);
;                 const float kt = kc[ss] * en, qt = qc[ss] * 0.125f * ep;
	global_load_ushort v180, v134, s[6:7]
	global_load_ushort v196, v134, s[6:7] offset:512
	s_add_u32 s6, s6, s54
	s_addc_u32 s7, s7, s55
	global_load_ushort v181, v134, s[6:7]
	global_load_ushort v197, v134, s[6:7] offset:512
	s_add_u32 s6, s6, s54
	s_addc_u32 s7, s7, s55
	global_load_ushort v182, v134, s[6:7]
	global_load_ushort v198, v134, s[6:7] offset:512
	s_add_u32 s6, s6, s54
	s_addc_u32 s7, s7, s55
	global_load_ushort v183, v134, s[6:7]
	global_load_ushort v199, v134, s[6:7] offset:512
	s_add_u32 s6, s6, s54
	s_addc_u32 s7, s7, s55
	global_load_ushort v184, v134, s[6:7]
	global_load_ushort v200, v134, s[6:7] offset:512
	s_add_u32 s6, s6, s54
	s_addc_u32 s7, s7, s55
	global_load_ushort v185, v134, s[6:7]
	global_load_ushort v201, v134, s[6:7] offset:512
	s_add_u32 s6, s6, s54
	s_addc_u32 s7, s7, s55
	global_load_ushort v186, v134, s[6:7]
	global_load_ushort v202, v134, s[6:7] offset:512
	s_add_u32 s6, s6, s54
	s_addc_u32 s7, s7, s55
	global_load_ushort v187, v134, s[6:7]
	global_load_ushort v203, v134, s[6:7] offset:512
	s_add_u32 s6, s6, s54
	s_addc_u32 s7, s7, s55
	global_load_ushort v188, v134, s[6:7]
	global_load_ushort v204, v134, s[6:7] offset:512
	s_add_u32 s6, s6, s54
	s_addc_u32 s7, s7, s55
	global_load_ushort v189, v134, s[6:7]
	global_load_ushort v205, v134, s[6:7] offset:512
	s_add_u32 s6, s6, s54
	s_addc_u32 s7, s7, s55
	global_load_ushort v190, v134, s[6:7]
	global_load_ushort v206, v134, s[6:7] offset:512
	s_add_u32 s6, s6, s54
	s_addc_u32 s7, s7, s55
	global_load_ushort v191, v134, s[6:7]
	global_load_ushort v207, v134, s[6:7] offset:512
	s_add_u32 s6, s6, s54
	s_addc_u32 s7, s7, s55
	global_load_ushort v192, v134, s[6:7]
	global_load_ushort v208, v134, s[6:7] offset:512
	s_add_u32 s6, s6, s54
	s_addc_u32 s7, s7, s55
	global_load_ushort v193, v134, s[6:7]
	global_load_ushort v209, v134, s[6:7] offset:512
	s_add_u32 s6, s6, s54
	s_addc_u32 s7, s7, s55
	global_load_ushort v194, v134, s[6:7]
	global_load_ushort v210, v134, s[6:7] offset:512
	s_add_u32 s6, s6, s54
	s_addc_u32 s7, s7, s55
	global_load_ushort v195, v134, s[6:7]
	global_load_ushort v211, v134, s[6:7] offset:512
	s_add_u32 s6, s6, s54
	s_addc_u32 s7, s7, s55
	v_mul_f32_e32 v18, 0xbfb8aa3b, v70
	v_mul_f32_e32 v19, 0xbfb8aa3b, v71
	v_mul_f32_e32 v20, 0xbfb8aa3b, v72
	v_mul_f32_e32 v21, 0xbfb8aa3b, v73
	v_mul_f32_e32 v22, 0xbfb8aa3b, v74
	v_mul_f32_e32 v23, 0xbfb8aa3b, v75
	v_mul_f32_e32 v24, 0xbfb8aa3b, v76
	v_mul_f32_e32 v25, 0xbfb8aa3b, v77
	v_mul_f32_e32 v26, 0xbfb8aa3b, v78
	v_mul_f32_e32 v27, 0xbfb8aa3b, v79
	v_mul_f32_e32 v28, 0xbfb8aa3b, v80
	v_mul_f32_e32 v29, 0xbfb8aa3b, v81
	v_mul_f32_e32 v30, 0xbfb8aa3b, v82
	v_mul_f32_e32 v31, 0xbfb8aa3b, v83
	v_mul_f32_e32 v32, 0xbfb8aa3b, v84
	v_mul_f32_e32 v33, 0xbfb8aa3b, v85
	v_mul_f32_e32 v236, 0x3fb8aa3b, v70
	v_mul_f32_e32 v237, 0x3fb8aa3b, v71
	v_mul_f32_e32 v238, 0x3fb8aa3b, v72
	v_mul_f32_e32 v239, 0x3fb8aa3b, v73
	v_mul_f32_e32 v240, 0x3fb8aa3b, v74
	v_mul_f32_e32 v241, 0x3fb8aa3b, v75
	v_mul_f32_e32 v242, 0x3fb8aa3b, v76
	v_mul_f32_e32 v243, 0x3fb8aa3b, v77
	v_mul_f32_e32 v244, 0x3fb8aa3b, v78
	v_mul_f32_e32 v245, 0x3fb8aa3b, v79
	v_mul_f32_e32 v246, 0x3fb8aa3b, v80
	v_mul_f32_e32 v247, 0x3fb8aa3b, v81
	v_mul_f32_e32 v248, 0x3fb8aa3b, v82
	v_mul_f32_e32 v249, 0x3fb8aa3b, v83
	v_mul_f32_e32 v250, 0x3fb8aa3b, v84
	v_mul_f32_e32 v251, 0x3fb8aa3b, v85
	v_exp_f32_e32 v18, v18
	v_exp_f32_e32 v19, v19
	v_exp_f32_e32 v20, v20
	v_exp_f32_e32 v21, v21
	v_exp_f32_e32 v22, v22
	v_exp_f32_e32 v23, v23
	v_exp_f32_e32 v24, v24
	v_exp_f32_e32 v25, v25
	v_exp_f32_e32 v26, v26
	v_exp_f32_e32 v27, v27
	v_exp_f32_e32 v28, v28
	v_exp_f32_e32 v29, v29
	v_exp_f32_e32 v30, v30
	v_exp_f32_e32 v31, v31
	v_exp_f32_e32 v32, v32
	v_exp_f32_e32 v33, v33
	v_exp_f32_e32 v236, v236
	v_exp_f32_e32 v237, v237
	v_exp_f32_e32 v238, v238
	v_exp_f32_e32 v239, v239
	v_exp_f32_e32 v240, v240
	v_exp_f32_e32 v241, v241
	v_exp_f32_e32 v242, v242
	v_exp_f32_e32 v243, v243
	v_exp_f32_e32 v244, v244
	v_exp_f32_e32 v245, v245
	v_exp_f32_e32 v246, v246
	v_exp_f32_e32 v247, v247
	v_exp_f32_e32 v248, v248
	v_exp_f32_e32 v249, v249
	v_exp_f32_e32 v250, v250
	v_exp_f32_e32 v251, v251
	v_lshlrev_b32_e32 v164, 16, v164
	v_lshlrev_b32_e32 v165, 16, v165
	v_lshlrev_b32_e32 v166, 16, v166
	v_lshlrev_b32_e32 v167, 16, v167
	v_lshlrev_b32_e32 v168, 16, v168
	v_lshlrev_b32_e32 v169, 16, v169
	v_lshlrev_b32_e32 v170, 16, v170
	v_lshlrev_b32_e32 v171, 16, v171
	v_lshlrev_b32_e32 v172, 16, v172
	v_lshlrev_b32_e32 v173, 16, v173
	v_lshlrev_b32_e32 v174, 16, v174
	v_lshlrev_b32_e32 v175, 16, v175
	v_lshlrev_b32_e32 v176, 16, v176
	v_lshlrev_b32_e32 v177, 16, v177
	v_lshlrev_b32_e32 v178, 16, v178
	v_lshlrev_b32_e32 v179, 16, v179
	v_lshlrev_b32_e32 v148, 16, v148
	v_lshlrev_b32_e32 v149, 16, v149
	v_lshlrev_b32_e32 v150, 16, v150
	v_lshlrev_b32_e32 v151, 16, v151
	v_lshlrev_b32_e32 v152, 16, v152
	v_lshlrev_b32_e32 v153, 16, v153
	v_lshlrev_b32_e32 v154, 16, v154
	v_lshlrev_b32_e32 v155, 16, v155
	v_lshlrev_b32_e32 v156, 16, v156
	v_lshlrev_b32_e32 v157, 16, v157
	v_lshlrev_b32_e32 v158, 16, v158
	v_lshlrev_b32_e32 v159, 16, v159
	v_lshlrev_b32_e32 v160, 16, v160
	v_lshlrev_b32_e32 v161, 16, v161
	v_lshlrev_b32_e32 v162, 16, v162
	v_lshlrev_b32_e32 v163, 16, v163
	v_mul_f32_e32 v164, v18, v164
	v_mul_f32_e32 v165, v19, v165
	v_mul_f32_e32 v166, v20, v166
	v_mul_f32_e32 v167, v21, v167
	v_mul_f32_e32 v168, v22, v168
	v_mul_f32_e32 v169, v23, v169
	v_mul_f32_e32 v170, v24, v170
	v_mul_f32_e32 v171, v25, v171
	v_mul_f32_e32 v172, v26, v172
	v_mul_f32_e32 v173, v27, v173
	v_mul_f32_e32 v174, v28, v174
	v_mul_f32_e32 v175, v29, v175
	v_mul_f32_e32 v176, v30, v176
; __device__ __forceinline__ unsigned f2bf(float f) { unsigned r; asm("v_cvt_pk_bf16_f32 %0, %1, %1" : "=v"(r) : "v"(f)); return r & 0xffffu; }
; __device__ __forceinline__ void gl1_item(PREF p, int l, int item, bool valid, LAS unsigned char* pl, int sw, int lane) {
;     ...
;             for (int ss = 0; ss < 16; ++ss) { const int s = g4 * 16 + ss; const int i = d ? 63 - s : s;
;                 float z = bup;
; #pragma unroll
;                 for (int r2 = 0; r2 < 8; ++r2) { const unsigned w = (unsigned)__builtin_amdgcn_readlane((int)lrp[r2], i);
;                     z = __builtin_amdgcn_fdot2_f32_bf16(__builtin_bit_cast(bf16x2_t, w), __builtin_bit_cast(bf16x2_t, wupp[r2]), z, false); }
;     ...
;                 const float kt = kc[ss] * en, qt = qc[ss] * 0.125f * ep;
;                 const unsigned ktb = f2bf(kt);
;                 sKt[lane * 72 + i] = (bf16_t)ktb;
;                 QK[rowi * 1024 + d * 512 + h * 64 + lane] = (bf16_t)f2bf(qt);
;                 QK[rowi * 1024 + d * 512 + 256 + h * 64 + lane] = (bf16_t)ktb;
;             }
	v_mul_f32_e32 v177, v31, v177
	v_mul_f32_e32 v178, v32, v178
	v_mul_f32_e32 v179, v33, v179
	v_mul_f32_e32 v148, 0x3e000000, v148
	v_mul_f32_e32 v149, 0x3e000000, v149
	v_mul_f32_e32 v150, 0x3e000000, v150
	v_mul_f32_e32 v151, 0x3e000000, v151
	v_mul_f32_e32 v152, 0x3e000000, v152
	v_mul_f32_e32 v153, 0x3e000000, v153
	v_mul_f32_e32 v154, 0x3e000000, v154
	v_mul_f32_e32 v155, 0x3e000000, v155
	v_mul_f32_e32 v156, 0x3e000000, v156
	v_mul_f32_e32 v157, 0x3e000000, v157
	v_mul_f32_e32 v158, 0x3e000000, v158
	v_mul_f32_e32 v159, 0x3e000000, v159
	v_mul_f32_e32 v160, 0x3e000000, v160
	v_mul_f32_e32 v161, 0x3e000000, v161
	v_mul_f32_e32 v162, 0x3e000000, v162
	v_mul_f32_e32 v163, 0x3e000000, v163
	v_mul_f32_e32 v148, v148, v236
	v_mul_f32_e32 v149, v149, v237
	v_mul_f32_e32 v150, v150, v238
	v_mul_f32_e32 v151, v151, v239
	v_mul_f32_e32 v152, v152, v240
	v_mul_f32_e32 v153, v153, v241
	v_mul_f32_e32 v154, v154, v242
	v_mul_f32_e32 v155, v155, v243
	v_mul_f32_e32 v156, v156, v244
	v_mul_f32_e32 v157, v157, v245
	v_mul_f32_e32 v158, v158, v246
	v_mul_f32_e32 v159, v159, v247
	v_mul_f32_e32 v160, v160, v248
	v_mul_f32_e32 v161, v161, v249
	v_mul_f32_e32 v162, v162, v250
	v_mul_f32_e32 v163, v163, v251
	v_cvt_pk_bf16_f32 v164, v164, v164
	v_cvt_pk_bf16_f32 v165, v165, v165
	v_cvt_pk_bf16_f32 v166, v166, v166
	v_cvt_pk_bf16_f32 v167, v167, v167
	v_cvt_pk_bf16_f32 v168, v168, v168
	v_cvt_pk_bf16_f32 v169, v169, v169
	v_cvt_pk_bf16_f32 v170, v170, v170
	v_cvt_pk_bf16_f32 v171, v171, v171
	v_cvt_pk_bf16_f32 v172, v172, v172
	v_cvt_pk_bf16_f32 v173, v173, v173
	v_cvt_pk_bf16_f32 v174, v174, v174
	v_cvt_pk_bf16_f32 v175, v175, v175
	v_cvt_pk_bf16_f32 v176, v176, v176
	v_cvt_pk_bf16_f32 v177, v177, v177
	v_cvt_pk_bf16_f32 v178, v178, v178
	v_cvt_pk_bf16_f32 v179, v179, v179
	v_cvt_pk_bf16_f32 v148, v148, v148
	v_cvt_pk_bf16_f32 v149, v149, v149
	v_cvt_pk_bf16_f32 v150, v150, v150
	v_cvt_pk_bf16_f32 v151, v151, v151
	v_cvt_pk_bf16_f32 v152, v152, v152
	v_cvt_pk_bf16_f32 v153, v153, v153
	v_cvt_pk_bf16_f32 v154, v154, v154
	v_cvt_pk_bf16_f32 v155, v155, v155
	v_cvt_pk_bf16_f32 v156, v156, v156
	v_cvt_pk_bf16_f32 v157, v157, v157
	v_cvt_pk_bf16_f32 v158, v158, v158
	v_cvt_pk_bf16_f32 v159, v159, v159
	v_cvt_pk_bf16_f32 v160, v160, v160
	v_cvt_pk_bf16_f32 v161, v161, v161
	v_cvt_pk_bf16_f32 v162, v162, v162
	v_cvt_pk_bf16_f32 v163, v163, v163
	ds_write_b16 v60, v164
	v_add_u32_e32 v60, v61, v60
	global_store_short v134, v148, s[4:5]
	global_store_short v134, v164, s[4:5] offset:512
	s_add_u32 s4, s4, s56
	s_addc_u32 s5, s5, s3
	ds_write_b16 v60, v165
	v_add_u32_e32 v60, v61, v60
	global_store_short v134, v149, s[4:5]
	global_store_short v134, v165, s[4:5] offset:512
	s_add_u32 s4, s4, s56
	s_addc_u32 s5, s5, s3
	ds_write_b16 v60, v166
	v_add_u32_e32 v60, v61, v60
	global_store_short v134, v150, s[4:5]
	global_store_short v134, v166, s[4:5] offset:512
	s_add_u32 s4, s4, s56
	s_addc_u32 s5, s5, s3
	ds_write_b16 v60, v167
	v_add_u32_e32 v60, v61, v60
	global_store_short v134, v151, s[4:5]
	global_store_short v134, v167, s[4:5] offset:512
	s_add_u32 s4, s4, s56
	s_addc_u32 s5, s5, s3
	ds_write_b16 v60, v168
	v_add_u32_e32 v60, v61, v60
	global_store_short v134, v152, s[4:5]
	global_store_short v134, v168, s[4:5] offset:512
	s_add_u32 s4, s4, s56
	s_addc_u32 s5, s5, s3
	ds_write_b16 v60, v169
	v_add_u32_e32 v60, v61, v60
	global_store_short v134, v153, s[4:5]
	global_store_short v134, v169, s[4:5] offset:512
	s_add_u32 s4, s4, s56
	s_addc_u32 s5, s5, s3
	ds_write_b16 v60, v170
	v_add_u32_e32 v60, v61, v60
	global_store_short v134, v154, s[4:5]
	global_store_short v134, v170, s[4:5] offset:512
	s_add_u32 s4, s4, s56
	s_addc_u32 s5, s5, s3
	ds_write_b16 v60, v171
	v_add_u32_e32 v60, v61, v60
	global_store_short v134, v155, s[4:5]
	global_store_short v134, v171, s[4:5] offset:512
	s_add_u32 s4, s4, s56
	s_addc_u32 s5, s5, s3
	ds_write_b16 v60, v172
	v_add_u32_e32 v60, v61, v60
	global_store_short v134, v156, s[4:5]
	global_store_short v134, v172, s[4:5] offset:512
	s_add_u32 s4, s4, s56
	s_addc_u32 s5, s5, s3
	ds_write_b16 v60, v173
	v_add_u32_e32 v60, v61, v60
	global_store_short v134, v157, s[4:5]
	global_store_short v134, v173, s[4:5] offset:512
	s_add_u32 s4, s4, s56
	s_addc_u32 s5, s5, s3
	ds_write_b16 v60, v174
	v_add_u32_e32 v60, v61, v60
	global_store_short v134, v158, s[4:5]
	global_store_short v134, v174, s[4:5] offset:512
	s_add_u32 s4, s4, s56
	s_addc_u32 s5, s5, s3
	ds_write_b16 v60, v175
	v_add_u32_e32 v60, v61, v60
	global_store_short v134, v159, s[4:5]
	global_store_short v134, v175, s[4:5] offset:512
	s_add_u32 s4, s4, s56
	s_addc_u32 s5, s5, s3
	ds_write_b16 v60, v176
	v_add_u32_e32 v60, v61, v60
	global_store_short v134, v160, s[4:5]
	global_store_short v134, v176, s[4:5] offset:512
	s_add_u32 s4, s4, s56
	s_addc_u32 s5, s5, s3
	ds_write_b16 v60, v177
	v_add_u32_e32 v60, v61, v60
	global_store_short v134, v161, s[4:5]
	global_store_short v134, v177, s[4:5] offset:512
	s_add_u32 s4, s4, s56
	s_addc_u32 s5, s5, s3
	ds_write_b16 v60, v178
	v_add_u32_e32 v60, v61, v60
	global_store_short v134, v162, s[4:5]
	global_store_short v134, v178, s[4:5] offset:512
	s_add_u32 s4, s4, s56
	s_addc_u32 s5, s5, s3
	ds_write_b16 v60, v179
	v_add_u32_e32 v60, v61, v60
	global_store_short v134, v163, s[4:5]
	global_store_short v134, v179, s[4:5] offset:512
	s_add_u32 s4, s4, s56
	s_addc_u32 s5, s5, s3
	v_mov_b32_e32 v236, v16
	v_readlane_b32 s45, v0, s30
	v_readlane_b32 s46, v1, s30
	v_readlane_b32 s47, v2, s30
	v_readlane_b32 s48, v3, s30
	v_readlane_b32 s49, v4, s30
	v_readlane_b32 s50, v5, s30
	v_readlane_b32 s51, v6, s30
	v_readlane_b32 s52, v7, s30
; __device__ __forceinline__ void gl1_item(PREF p, int l, int item, bool valid, LAS unsigned char* pl, int sw, int lane) {
;     ...
;             for (int ss = 0; ss < 16; ++ss) { const int s = g4 * 16 + ss; const int i = d ? 63 - s : s;
;                 float z = bup;
; #pragma unroll
;                 for (int r2 = 0; r2 < 8; ++r2) { const unsigned w = (unsigned)__builtin_amdgcn_readlane((int)lrp[r2], i);
;                     z = __builtin_amdgcn_fdot2_f32_bf16(__builtin_bit_cast(bf16x2_t, w), __builtin_bit_cast(bf16x2_t, wupp[r2]), z, false); }
	s_add_i32 s30, s30, s2
	v_dot2c_f32_bf16_e32 v236, s45, v8
	v_dot2c_f32_bf16_e32 v236, s46, v9
	v_dot2c_f32_bf16_e32 v236, s47, v10
	v_dot2c_f32_bf16_e32 v236, s48, v11
	v_dot2c_f32_bf16_e32 v236, s49, v12
	v_dot2c_f32_bf16_e32 v236, s50, v13
	v_dot2c_f32_bf16_e32 v236, s51, v14
	v_dot2c_f32_bf16_e32 v236, s52, v15
	v_mov_b32_e32 v237, v16
	v_readlane_b32 s45, v0, s30
	v_readlane_b32 s46, v1, s30
	v_readlane_b32 s47, v2, s30
	v_readlane_b32 s48, v3, s30
	v_readlane_b32 s49, v4, s30
	v_readlane_b32 s50, v5, s30
	v_readlane_b32 s51, v6, s30
	v_readlane_b32 s52, v7, s30
	s_add_i32 s30, s30, s2
	v_dot2c_f32_bf16_e32 v237, s45, v8
	v_dot2c_f32_bf16_e32 v237, s46, v9
	v_dot2c_f32_bf16_e32 v237, s47, v10
	v_dot2c_f32_bf16_e32 v237, s48, v11
	v_dot2c_f32_bf16_e32 v237, s49, v12
	v_dot2c_f32_bf16_e32 v237, s50, v13
	v_dot2c_f32_bf16_e32 v237, s51, v14
	v_dot2c_f32_bf16_e32 v237, s52, v15
	v_mov_b32_e32 v238, v16
	v_readlane_b32 s45, v0, s30
	v_readlane_b32 s46, v1, s30
	v_readlane_b32 s47, v2, s30
	v_readlane_b32 s48, v3, s30
	v_readlane_b32 s49, v4, s30
	v_readlane_b32 s50, v5, s30
	v_readlane_b32 s51, v6, s30
	v_readlane_b32 s52, v7, s30
	s_add_i32 s30, s30, s2
	v_dot2c_f32_bf16_e32 v238, s45, v8
	v_dot2c_f32_bf16_e32 v238, s46, v9
	v_dot2c_f32_bf16_e32 v238, s47, v10
	v_dot2c_f32_bf16_e32 v238, s48, v11
	v_dot2c_f32_bf16_e32 v238, s49, v12
	v_dot2c_f32_bf16_e32 v238, s50, v13
	v_dot2c_f32_bf16_e32 v238, s51, v14
	v_dot2c_f32_bf16_e32 v238, s52, v15
	v_mov_b32_e32 v239, v16
	v_readlane_b32 s45, v0, s30
	v_readlane_b32 s46, v1, s30
	v_readlane_b32 s47, v2, s30
	v_readlane_b32 s48, v3, s30
	v_readlane_b32 s49, v4, s30
	v_readlane_b32 s50, v5, s30
	v_readlane_b32 s51, v6, s30
	v_readlane_b32 s52, v7, s30
	s_add_i32 s30, s30, s2
	v_dot2c_f32_bf16_e32 v239, s45, v8
	v_dot2c_f32_bf16_e32 v239, s46, v9
	v_dot2c_f32_bf16_e32 v239, s47, v10
	v_dot2c_f32_bf16_e32 v239, s48, v11
	v_dot2c_f32_bf16_e32 v239, s49, v12
	v_dot2c_f32_bf16_e32 v239, s50, v13
	v_dot2c_f32_bf16_e32 v239, s51, v14
	v_dot2c_f32_bf16_e32 v239, s52, v15
	v_mov_b32_e32 v240, v16
	v_readlane_b32 s45, v0, s30
	v_readlane_b32 s46, v1, s30
	v_readlane_b32 s47, v2, s30
	v_readlane_b32 s48, v3, s30
	v_readlane_b32 s49, v4, s30
	v_readlane_b32 s50, v5, s30
	v_readlane_b32 s51, v6, s30
	v_readlane_b32 s52, v7, s30
	s_add_i32 s30, s30, s2
	v_dot2c_f32_bf16_e32 v240, s45, v8
	v_dot2c_f32_bf16_e32 v240, s46, v9
	v_dot2c_f32_bf16_e32 v240, s47, v10
	v_dot2c_f32_bf16_e32 v240, s48, v11
	v_dot2c_f32_bf16_e32 v240, s49, v12
	v_dot2c_f32_bf16_e32 v240, s50, v13
	v_dot2c_f32_bf16_e32 v240, s51, v14
	v_dot2c_f32_bf16_e32 v240, s52, v15
	v_mov_b32_e32 v241, v16
	v_readlane_b32 s45, v0, s30
	v_readlane_b32 s46, v1, s30
	v_readlane_b32 s47, v2, s30
	v_readlane_b32 s48, v3, s30
	v_readlane_b32 s49, v4, s30
	v_readlane_b32 s50, v5, s30
	v_readlane_b32 s51, v6, s30
	v_readlane_b32 s52, v7, s30
	s_add_i32 s30, s30, s2
	v_dot2c_f32_bf16_e32 v241, s45, v8
	v_dot2c_f32_bf16_e32 v241, s46, v9
	v_dot2c_f32_bf16_e32 v241, s47, v10
	v_dot2c_f32_bf16_e32 v241, s48, v11
	v_dot2c_f32_bf16_e32 v241, s49, v12
	v_dot2c_f32_bf16_e32 v241, s50, v13
	v_dot2c_f32_bf16_e32 v241, s51, v14
	v_dot2c_f32_bf16_e32 v241, s52, v15
	v_mov_b32_e32 v242, v16
	v_readlane_b32 s45, v0, s30
	v_readlane_b32 s46, v1, s30
	v_readlane_b32 s47, v2, s30
	v_readlane_b32 s48, v3, s30
	v_readlane_b32 s49, v4, s30
	v_readlane_b32 s50, v5, s30
	v_readlane_b32 s51, v6, s30
	v_readlane_b32 s52, v7, s30
	s_add_i32 s30, s30, s2
	v_dot2c_f32_bf16_e32 v242, s45, v8
	v_dot2c_f32_bf16_e32 v242, s46, v9
	v_dot2c_f32_bf16_e32 v242, s47, v10
	v_dot2c_f32_bf16_e32 v242, s48, v11
	v_dot2c_f32_bf16_e32 v242, s49, v12
	v_dot2c_f32_bf16_e32 v242, s50, v13
	v_dot2c_f32_bf16_e32 v242, s51, v14
	v_dot2c_f32_bf16_e32 v242, s52, v15
	v_mov_b32_e32 v243, v16
	v_readlane_b32 s45, v0, s30
	v_readlane_b32 s46, v1, s30
	v_readlane_b32 s47, v2, s30
	v_readlane_b32 s48, v3, s30
	v_readlane_b32 s49, v4, s30
	v_readlane_b32 s50, v5, s30
	v_readlane_b32 s51, v6, s30
	v_readlane_b32 s52, v7, s30
	s_add_i32 s30, s30, s2
	v_dot2c_f32_bf16_e32 v243, s45, v8
	v_dot2c_f32_bf16_e32 v243, s46, v9
	v_dot2c_f32_bf16_e32 v243, s47, v10
	v_dot2c_f32_bf16_e32 v243, s48, v11
	v_dot2c_f32_bf16_e32 v243, s49, v12
	v_dot2c_f32_bf16_e32 v243, s50, v13
	v_dot2c_f32_bf16_e32 v243, s51, v14
	v_dot2c_f32_bf16_e32 v243, s52, v15
	v_mov_b32_e32 v244, v16
	v_readlane_b32 s45, v0, s30
	v_readlane_b32 s46, v1, s30
	v_readlane_b32 s47, v2, s30
	v_readlane_b32 s48, v3, s30
	v_readlane_b32 s49, v4, s30
	v_readlane_b32 s50, v5, s30
	v_readlane_b32 s51, v6, s30
	v_readlane_b32 s52, v7, s30
	s_add_i32 s30, s30, s2
	v_dot2c_f32_bf16_e32 v244, s45, v8
	v_dot2c_f32_bf16_e32 v244, s46, v9
	v_dot2c_f32_bf16_e32 v244, s47, v10
	v_dot2c_f32_bf16_e32 v244, s48, v11
	v_dot2c_f32_bf16_e32 v244, s49, v12
	v_dot2c_f32_bf16_e32 v244, s50, v13
	v_dot2c_f32_bf16_e32 v244, s51, v14
	v_dot2c_f32_bf16_e32 v244, s52, v15
	v_mov_b32_e32 v245, v16
	v_readlane_b32 s45, v0, s30
	v_readlane_b32 s46, v1, s30
	v_readlane_b32 s47, v2, s30
	v_readlane_b32 s48, v3, s30
	v_readlane_b32 s49, v4, s30
	v_readlane_b32 s50, v5, s30
	v_readlane_b32 s51, v6, s30
	v_readlane_b32 s52, v7, s30
	s_add_i32 s30, s30, s2
	v_dot2c_f32_bf16_e32 v245, s45, v8
	v_dot2c_f32_bf16_e32 v245, s46, v9
	v_dot2c_f32_bf16_e32 v245, s47, v10
	v_dot2c_f32_bf16_e32 v245, s48, v11
	v_dot2c_f32_bf16_e32 v245, s49, v12
	v_dot2c_f32_bf16_e32 v245, s50, v13
	v_dot2c_f32_bf16_e32 v245, s51, v14
	v_dot2c_f32_bf16_e32 v245, s52, v15
	v_mov_b32_e32 v246, v16
	v_readlane_b32 s45, v0, s30
	v_readlane_b32 s46, v1, s30
	v_readlane_b32 s47, v2, s30
	v_readlane_b32 s48, v3, s30
; __device__ __forceinline__ void gl1_item(PREF p, int l, int item, bool valid, LAS unsigned char* pl, int sw, int lane) {
;     ...
;             for (int ss = 0; ss < 16; ++ss) { const int s = g4 * 16 + ss; const int i = d ? 63 - s : s;
;                 float z = bup;
; #pragma unroll
;                 for (int r2 = 0; r2 < 8; ++r2) { const unsigned w = (unsigned)__builtin_amdgcn_readlane((int)lrp[r2], i);
;                     z = __builtin_amdgcn_fdot2_f32_bf16(__builtin_bit_cast(bf16x2_t, w), __builtin_bit_cast(bf16x2_t, wupp[r2]), z, false); }
;                 gv[ss] = -(fmaxf(-z, 0.f) + __logf(1.f + __expf(-fabsf(z)))) * (1.f / 16.f);
	v_readlane_b32 s49, v4, s30
	v_readlane_b32 s50, v5, s30
	v_readlane_b32 s51, v6, s30
	v_readlane_b32 s52, v7, s30
	s_add_i32 s30, s30, s2
	v_dot2c_f32_bf16_e32 v246, s45, v8
	v_dot2c_f32_bf16_e32 v246, s46, v9
	v_dot2c_f32_bf16_e32 v246, s47, v10
	v_dot2c_f32_bf16_e32 v246, s48, v11
	v_dot2c_f32_bf16_e32 v246, s49, v12
	v_dot2c_f32_bf16_e32 v246, s50, v13
	v_dot2c_f32_bf16_e32 v246, s51, v14
	v_dot2c_f32_bf16_e32 v246, s52, v15
	v_mov_b32_e32 v247, v16
	v_readlane_b32 s45, v0, s30
	v_readlane_b32 s46, v1, s30
	v_readlane_b32 s47, v2, s30
	v_readlane_b32 s48, v3, s30
	v_readlane_b32 s49, v4, s30
	v_readlane_b32 s50, v5, s30
	v_readlane_b32 s51, v6, s30
	v_readlane_b32 s52, v7, s30
	s_add_i32 s30, s30, s2
	v_dot2c_f32_bf16_e32 v247, s45, v8
	v_dot2c_f32_bf16_e32 v247, s46, v9
	v_dot2c_f32_bf16_e32 v247, s47, v10
	v_dot2c_f32_bf16_e32 v247, s48, v11
	v_dot2c_f32_bf16_e32 v247, s49, v12
	v_dot2c_f32_bf16_e32 v247, s50, v13
	v_dot2c_f32_bf16_e32 v247, s51, v14
	v_dot2c_f32_bf16_e32 v247, s52, v15
	v_mov_b32_e32 v248, v16
	v_readlane_b32 s45, v0, s30
	v_readlane_b32 s46, v1, s30
	v_readlane_b32 s47, v2, s30
	v_readlane_b32 s48, v3, s30
	v_readlane_b32 s49, v4, s30
	v_readlane_b32 s50, v5, s30
	v_readlane_b32 s51, v6, s30
	v_readlane_b32 s52, v7, s30
	s_add_i32 s30, s30, s2
	v_dot2c_f32_bf16_e32 v248, s45, v8
	v_dot2c_f32_bf16_e32 v248, s46, v9
	v_dot2c_f32_bf16_e32 v248, s47, v10
	v_dot2c_f32_bf16_e32 v248, s48, v11
	v_dot2c_f32_bf16_e32 v248, s49, v12
	v_dot2c_f32_bf16_e32 v248, s50, v13
	v_dot2c_f32_bf16_e32 v248, s51, v14
	v_dot2c_f32_bf16_e32 v248, s52, v15
	v_mov_b32_e32 v249, v16
	v_readlane_b32 s45, v0, s30
	v_readlane_b32 s46, v1, s30
	v_readlane_b32 s47, v2, s30
	v_readlane_b32 s48, v3, s30
	v_readlane_b32 s49, v4, s30
	v_readlane_b32 s50, v5, s30
	v_readlane_b32 s51, v6, s30
	v_readlane_b32 s52, v7, s30
	s_add_i32 s30, s30, s2
	v_dot2c_f32_bf16_e32 v249, s45, v8
	v_dot2c_f32_bf16_e32 v249, s46, v9
	v_dot2c_f32_bf16_e32 v249, s47, v10
	v_dot2c_f32_bf16_e32 v249, s48, v11
	v_dot2c_f32_bf16_e32 v249, s49, v12
	v_dot2c_f32_bf16_e32 v249, s50, v13
	v_dot2c_f32_bf16_e32 v249, s51, v14
	v_dot2c_f32_bf16_e32 v249, s52, v15
	v_mov_b32_e32 v250, v16
	v_readlane_b32 s45, v0, s30
	v_readlane_b32 s46, v1, s30
	v_readlane_b32 s47, v2, s30
	v_readlane_b32 s48, v3, s30
	v_readlane_b32 s49, v4, s30
	v_readlane_b32 s50, v5, s30
	v_readlane_b32 s51, v6, s30
	v_readlane_b32 s52, v7, s30
	s_add_i32 s30, s30, s2
	v_dot2c_f32_bf16_e32 v250, s45, v8
	v_dot2c_f32_bf16_e32 v250, s46, v9
	v_dot2c_f32_bf16_e32 v250, s47, v10
	v_dot2c_f32_bf16_e32 v250, s48, v11
	v_dot2c_f32_bf16_e32 v250, s49, v12
	v_dot2c_f32_bf16_e32 v250, s50, v13
	v_dot2c_f32_bf16_e32 v250, s51, v14
	v_dot2c_f32_bf16_e32 v250, s52, v15
	v_mov_b32_e32 v251, v16
	v_readlane_b32 s45, v0, s30
	v_readlane_b32 s46, v1, s30
	v_readlane_b32 s47, v2, s30
	v_readlane_b32 s48, v3, s30
	v_readlane_b32 s49, v4, s30
	v_readlane_b32 s50, v5, s30
	v_readlane_b32 s51, v6, s30
	v_readlane_b32 s52, v7, s30
	s_add_i32 s30, s30, s2
	v_dot2c_f32_bf16_e32 v251, s45, v8
	v_dot2c_f32_bf16_e32 v251, s46, v9
	v_dot2c_f32_bf16_e32 v251, s47, v10
	v_dot2c_f32_bf16_e32 v251, s48, v11
	v_dot2c_f32_bf16_e32 v251, s49, v12
	v_dot2c_f32_bf16_e32 v251, s50, v13
	v_dot2c_f32_bf16_e32 v251, s51, v14
	v_dot2c_f32_bf16_e32 v251, s52, v15
	s_nop 2
	v_mul_f32_e64 v18, |v236|, s1
	v_mul_f32_e64 v19, |v237|, s1
	v_mul_f32_e64 v20, |v238|, s1
	v_mul_f32_e64 v21, |v239|, s1
	v_mul_f32_e64 v22, |v240|, s1
	v_mul_f32_e64 v23, |v241|, s1
	v_mul_f32_e64 v24, |v242|, s1
	v_mul_f32_e64 v25, |v243|, s1
	v_mul_f32_e64 v26, |v244|, s1
	v_mul_f32_e64 v27, |v245|, s1
	v_mul_f32_e64 v28, |v246|, s1
	v_mul_f32_e64 v29, |v247|, s1
	v_mul_f32_e64 v30, |v248|, s1
	v_mul_f32_e64 v31, |v249|, s1
	v_mul_f32_e64 v32, |v250|, s1
	v_mul_f32_e64 v33, |v251|, s1
	v_exp_f32_e32 v18, v18
	v_exp_f32_e32 v19, v19
	v_exp_f32_e32 v20, v20
	v_exp_f32_e32 v21, v21
	v_exp_f32_e32 v22, v22
	v_exp_f32_e32 v23, v23
	v_exp_f32_e32 v24, v24
	v_exp_f32_e32 v25, v25
	v_exp_f32_e32 v26, v26
	v_exp_f32_e32 v27, v27
	v_exp_f32_e32 v28, v28
	v_exp_f32_e32 v29, v29
	v_exp_f32_e32 v30, v30
	v_exp_f32_e32 v31, v31
	v_exp_f32_e32 v32, v32
	v_exp_f32_e32 v33, v33
	v_max_f32_e64 v236, -v236, -v236
	v_max_f32_e64 v237, -v237, -v237
	v_max_f32_e64 v238, -v238, -v238
	v_max_f32_e64 v239, -v239, -v239
	v_max_f32_e64 v240, -v240, -v240
	v_max_f32_e64 v241, -v241, -v241
	v_max_f32_e64 v242, -v242, -v242
	v_max_f32_e64 v243, -v243, -v243
	v_max_f32_e64 v244, -v244, -v244
	v_max_f32_e64 v245, -v245, -v245
	v_max_f32_e64 v246, -v246, -v246
	v_max_f32_e64 v247, -v247, -v247
	v_max_f32_e64 v248, -v248, -v248
	v_max_f32_e64 v249, -v249, -v249
	v_max_f32_e64 v250, -v250, -v250
	v_max_f32_e64 v251, -v251, -v251
	v_max_f32_e32 v236, 0, v236
	v_max_f32_e32 v237, 0, v237
	v_max_f32_e32 v238, 0, v238
	v_max_f32_e32 v239, 0, v239
	v_max_f32_e32 v240, 0, v240
	v_max_f32_e32 v241, 0, v241
	v_max_f32_e32 v242, 0, v242
	v_max_f32_e32 v243, 0, v243
	v_max_f32_e32 v244, 0, v244
	v_max_f32_e32 v245, 0, v245
	v_max_f32_e32 v246, 0, v246
	v_max_f32_e32 v247, 0, v247
	v_max_f32_e32 v248, 0, v248
	v_max_f32_e32 v249, 0, v249
	v_max_f32_e32 v250, 0, v250
	v_max_f32_e32 v251, 0, v251
	v_add_f32_e32 v18, 1.0, v18
	v_add_f32_e32 v19, 1.0, v19
	v_add_f32_e32 v20, 1.0, v20
	v_add_f32_e32 v21, 1.0, v21
	v_add_f32_e32 v22, 1.0, v22
	v_add_f32_e32 v23, 1.0, v23
	v_add_f32_e32 v24, 1.0, v24
	v_add_f32_e32 v25, 1.0, v25
	v_add_f32_e32 v26, 1.0, v26
	v_add_f32_e32 v27, 1.0, v27
	v_add_f32_e32 v28, 1.0, v28
	v_add_f32_e32 v29, 1.0, v29
	v_add_f32_e32 v30, 1.0, v30
	v_add_f32_e32 v31, 1.0, v31
	v_add_f32_e32 v32, 1.0, v32
; __device__ __forceinline__ void gl1_item(PREF p, int l, int item, bool valid, LAS unsigned char* pl, int sw, int lane) {
;     ...
;                 gv[ss] = -(fmaxf(-z, 0.f) + __logf(1.f + __expf(-fabsf(z)))) * (1.f / 16.f);
;                 __builtin_amdgcn_sched_barrier(0);
;             }
; #pragma unroll
;             for (int ss = 0; ss < 16; ++ss) { const int s = g4 * 16 + ss; const int i = d ? 63 - s : s; const size_t rowi = (size_t)(row0 + i * rstride);
;                 bc += gv[ss];
;                 const float en = __expf(-bc), ep = __expf(bc);
;                 const float kt = kc[ss] * en, qt = qc[ss] * 0.125f * ep;
	v_add_f32_e32 v33, 1.0, v33
	v_log_f32_e32 v18, v18
	v_log_f32_e32 v19, v19
	v_log_f32_e32 v20, v20
	v_log_f32_e32 v21, v21
	v_log_f32_e32 v22, v22
	v_log_f32_e32 v23, v23
	v_log_f32_e32 v24, v24
	v_log_f32_e32 v25, v25
	v_log_f32_e32 v26, v26
	v_log_f32_e32 v27, v27
	v_log_f32_e32 v28, v28
	v_log_f32_e32 v29, v29
	v_log_f32_e32 v30, v30
	v_log_f32_e32 v31, v31
	v_log_f32_e32 v32, v32
	v_log_f32_e32 v33, v33
	s_mov_b32 s45, 0x3f317217
	v_mul_f32_e32 v70, 0x3f317217, v18
	v_mul_f32_e32 v71, 0x3f317217, v19
	v_mul_f32_e32 v72, 0x3f317217, v20
	v_mul_f32_e32 v73, 0x3f317217, v21
	v_mul_f32_e32 v74, 0x3f317217, v22
	v_mul_f32_e32 v75, 0x3f317217, v23
	v_mul_f32_e32 v76, 0x3f317217, v24
	v_mul_f32_e32 v77, 0x3f317217, v25
	v_mul_f32_e32 v78, 0x3f317217, v26
	v_mul_f32_e32 v79, 0x3f317217, v27
	v_mul_f32_e32 v80, 0x3f317217, v28
	v_mul_f32_e32 v81, 0x3f317217, v29
	v_mul_f32_e32 v82, 0x3f317217, v30
	v_mul_f32_e32 v83, 0x3f317217, v31
	v_mul_f32_e32 v84, 0x3f317217, v32
	v_mul_f32_e32 v85, 0x3f317217, v33
	v_fma_f32 v70, v18, s45, -v70
	v_fma_f32 v71, v19, s45, -v71
	v_fma_f32 v72, v20, s45, -v72
	v_fma_f32 v73, v21, s45, -v73
	v_fma_f32 v74, v22, s45, -v74
	v_fma_f32 v75, v23, s45, -v75
	v_fma_f32 v76, v24, s45, -v76
	v_fma_f32 v77, v25, s45, -v77
	v_fma_f32 v78, v26, s45, -v78
	v_fma_f32 v79, v27, s45, -v79
	v_fma_f32 v80, v28, s45, -v80
	v_fma_f32 v81, v29, s45, -v81
	v_fma_f32 v82, v30, s45, -v82
	v_fma_f32 v83, v31, s45, -v83
	v_fma_f32 v84, v32, s45, -v84
	v_fma_f32 v85, v33, s45, -v85
	v_fmac_f32_e32 v70, 0x3377d1cf, v18
	v_fmac_f32_e32 v71, 0x3377d1cf, v19
	v_fmac_f32_e32 v72, 0x3377d1cf, v20
	v_fmac_f32_e32 v73, 0x3377d1cf, v21
	v_fmac_f32_e32 v74, 0x3377d1cf, v22
	v_fmac_f32_e32 v75, 0x3377d1cf, v23
	v_fmac_f32_e32 v76, 0x3377d1cf, v24
	v_fmac_f32_e32 v77, 0x3377d1cf, v25
	v_fmac_f32_e32 v78, 0x3377d1cf, v26
	v_fmac_f32_e32 v79, 0x3377d1cf, v27
	v_fmac_f32_e32 v80, 0x3377d1cf, v28
	v_fmac_f32_e32 v81, 0x3377d1cf, v29
	v_fmac_f32_e32 v82, 0x3377d1cf, v30
	v_fmac_f32_e32 v83, 0x3377d1cf, v31
	v_fmac_f32_e32 v84, 0x3377d1cf, v32
	v_fmac_f32_e32 v85, 0x3377d1cf, v33
	v_fmac_f32_e32 v70, 0x3f317217, v18
	v_fmac_f32_e32 v71, 0x3f317217, v19
	v_fmac_f32_e32 v72, 0x3f317217, v20
	v_fmac_f32_e32 v73, 0x3f317217, v21
	v_fmac_f32_e32 v74, 0x3f317217, v22
	v_fmac_f32_e32 v75, 0x3f317217, v23
	v_fmac_f32_e32 v76, 0x3f317217, v24
	v_fmac_f32_e32 v77, 0x3f317217, v25
	v_fmac_f32_e32 v78, 0x3f317217, v26
	v_fmac_f32_e32 v79, 0x3f317217, v27
	v_fmac_f32_e32 v80, 0x3f317217, v28
	v_fmac_f32_e32 v81, 0x3f317217, v29
	v_fmac_f32_e32 v82, 0x3f317217, v30
	v_fmac_f32_e32 v83, 0x3f317217, v31
	v_fmac_f32_e32 v84, 0x3f317217, v32
	v_fmac_f32_e32 v85, 0x3f317217, v33
	v_add_f32_e32 v236, v236, v70
	v_add_f32_e32 v237, v237, v71
	v_add_f32_e32 v238, v238, v72
	v_add_f32_e32 v239, v239, v73
	v_add_f32_e32 v240, v240, v74
	v_add_f32_e32 v241, v241, v75
	v_add_f32_e32 v242, v242, v76
	v_add_f32_e32 v243, v243, v77
	v_add_f32_e32 v244, v244, v78
	v_add_f32_e32 v245, v245, v79
	v_add_f32_e32 v246, v246, v80
	v_add_f32_e32 v247, v247, v81
	v_add_f32_e32 v248, v248, v82
	v_add_f32_e32 v249, v249, v83
	v_add_f32_e32 v250, v250, v84
	v_add_f32_e32 v251, v251, v85
	v_mov_b32_e32 v70, v17
	v_fmac_f32_e32 v70, 0xbd800000, v236
	v_mov_b32_e32 v71, v70
	v_fmac_f32_e32 v71, 0xbd800000, v237
	v_mov_b32_e32 v72, v71
	v_fmac_f32_e32 v72, 0xbd800000, v238
	v_mov_b32_e32 v73, v72
	v_fmac_f32_e32 v73, 0xbd800000, v239
	v_mov_b32_e32 v74, v73
	v_fmac_f32_e32 v74, 0xbd800000, v240
	v_mov_b32_e32 v75, v74
	v_fmac_f32_e32 v75, 0xbd800000, v241
	v_mov_b32_e32 v76, v75
	v_fmac_f32_e32 v76, 0xbd800000, v242
	v_mov_b32_e32 v77, v76
	v_fmac_f32_e32 v77, 0xbd800000, v243
	v_mov_b32_e32 v78, v77
	v_fmac_f32_e32 v78, 0xbd800000, v244
	v_mov_b32_e32 v79, v78
	v_fmac_f32_e32 v79, 0xbd800000, v245
	v_mov_b32_e32 v80, v79
	v_fmac_f32_e32 v80, 0xbd800000, v246
	v_mov_b32_e32 v81, v80
	v_fmac_f32_e32 v81, 0xbd800000, v247
	v_mov_b32_e32 v82, v81
	v_fmac_f32_e32 v82, 0xbd800000, v248
	v_mov_b32_e32 v83, v82
	v_fmac_f32_e32 v83, 0xbd800000, v249
	v_mov_b32_e32 v84, v83
	v_fmac_f32_e32 v84, 0xbd800000, v250
	v_mov_b32_e32 v85, v84
	v_fmac_f32_e32 v85, 0xbd800000, v251
	v_mov_b32_e32 v17, v85
	s_waitcnt vmcnt(32)
	v_mul_f32_e32 v18, 0xbfb8aa3b, v70
	v_mul_f32_e32 v19, 0xbfb8aa3b, v71
	v_mul_f32_e32 v20, 0xbfb8aa3b, v72
	v_mul_f32_e32 v21, 0xbfb8aa3b, v73
	v_mul_f32_e32 v22, 0xbfb8aa3b, v74
	v_mul_f32_e32 v23, 0xbfb8aa3b, v75
	v_mul_f32_e32 v24, 0xbfb8aa3b, v76
	v_mul_f32_e32 v25, 0xbfb8aa3b, v77
	v_mul_f32_e32 v26, 0xbfb8aa3b, v78
	v_mul_f32_e32 v27, 0xbfb8aa3b, v79
	v_mul_f32_e32 v28, 0xbfb8aa3b, v80
	v_mul_f32_e32 v29, 0xbfb8aa3b, v81
	v_mul_f32_e32 v30, 0xbfb8aa3b, v82
	v_mul_f32_e32 v31, 0xbfb8aa3b, v83
	v_mul_f32_e32 v32, 0xbfb8aa3b, v84
	v_mul_f32_e32 v33, 0xbfb8aa3b, v85
	v_mul_f32_e32 v236, 0x3fb8aa3b, v70
	v_mul_f32_e32 v237, 0x3fb8aa3b, v71
	v_mul_f32_e32 v238, 0x3fb8aa3b, v72
	v_mul_f32_e32 v239, 0x3fb8aa3b, v73
	v_mul_f32_e32 v240, 0x3fb8aa3b, v74
	v_mul_f32_e32 v241, 0x3fb8aa3b, v75
	v_mul_f32_e32 v242, 0x3fb8aa3b, v76
	v_mul_f32_e32 v243, 0x3fb8aa3b, v77
	v_mul_f32_e32 v244, 0x3fb8aa3b, v78
	v_mul_f32_e32 v245, 0x3fb8aa3b, v79
	v_mul_f32_e32 v246, 0x3fb8aa3b, v80
	v_mul_f32_e32 v247, 0x3fb8aa3b, v81
	v_mul_f32_e32 v248, 0x3fb8aa3b, v82
	v_mul_f32_e32 v249, 0x3fb8aa3b, v83
	v_mul_f32_e32 v250, 0x3fb8aa3b, v84
	v_mul_f32_e32 v251, 0x3fb8aa3b, v85
	v_exp_f32_e32 v18, v18
	v_exp_f32_e32 v19, v19
	v_exp_f32_e32 v20, v20
	v_exp_f32_e32 v21, v21
	v_exp_f32_e32 v22, v22
	v_exp_f32_e32 v23, v23
	v_exp_f32_e32 v24, v24
	v_exp_f32_e32 v25, v25
	v_exp_f32_e32 v26, v26
	v_exp_f32_e32 v27, v27
; __device__ __forceinline__ unsigned f2bf(float f) { unsigned r; asm("v_cvt_pk_bf16_f32 %0, %1, %1" : "=v"(r) : "v"(f)); return r & 0xffffu; }
; __device__ __forceinline__ void gl1_item(PREF p, int l, int item, bool valid, LAS unsigned char* pl, int sw, int lane) {
;     ...
;                 const float en = __expf(-bc), ep = __expf(bc);
;                 const float kt = kc[ss] * en, qt = qc[ss] * 0.125f * ep;
;                 const unsigned ktb = f2bf(kt);
;                 sKt[lane * 72 + i] = (bf16_t)ktb;
;                 QK[rowi * 1024 + d * 512 + h * 64 + lane] = (bf16_t)f2bf(qt);
	v_exp_f32_e32 v28, v28
	v_exp_f32_e32 v29, v29
	v_exp_f32_e32 v30, v30
	v_exp_f32_e32 v31, v31
	v_exp_f32_e32 v32, v32
	v_exp_f32_e32 v33, v33
	v_exp_f32_e32 v236, v236
	v_exp_f32_e32 v237, v237
	v_exp_f32_e32 v238, v238
	v_exp_f32_e32 v239, v239
	v_exp_f32_e32 v240, v240
	v_exp_f32_e32 v241, v241
	v_exp_f32_e32 v242, v242
	v_exp_f32_e32 v243, v243
	v_exp_f32_e32 v244, v244
	v_exp_f32_e32 v245, v245
	v_exp_f32_e32 v246, v246
	v_exp_f32_e32 v247, v247
	v_exp_f32_e32 v248, v248
	v_exp_f32_e32 v249, v249
	v_exp_f32_e32 v250, v250
	v_exp_f32_e32 v251, v251
	v_lshlrev_b32_e32 v196, 16, v196
	v_lshlrev_b32_e32 v197, 16, v197
	v_lshlrev_b32_e32 v198, 16, v198
	v_lshlrev_b32_e32 v199, 16, v199
	v_lshlrev_b32_e32 v200, 16, v200
	v_lshlrev_b32_e32 v201, 16, v201
	v_lshlrev_b32_e32 v202, 16, v202
	v_lshlrev_b32_e32 v203, 16, v203
	v_lshlrev_b32_e32 v204, 16, v204
	v_lshlrev_b32_e32 v205, 16, v205
	v_lshlrev_b32_e32 v206, 16, v206
	v_lshlrev_b32_e32 v207, 16, v207
	v_lshlrev_b32_e32 v208, 16, v208
	v_lshlrev_b32_e32 v209, 16, v209
	v_lshlrev_b32_e32 v210, 16, v210
	v_lshlrev_b32_e32 v211, 16, v211
	v_lshlrev_b32_e32 v180, 16, v180
	v_lshlrev_b32_e32 v181, 16, v181
	v_lshlrev_b32_e32 v182, 16, v182
	v_lshlrev_b32_e32 v183, 16, v183
	v_lshlrev_b32_e32 v184, 16, v184
	v_lshlrev_b32_e32 v185, 16, v185
	v_lshlrev_b32_e32 v186, 16, v186
	v_lshlrev_b32_e32 v187, 16, v187
	v_lshlrev_b32_e32 v188, 16, v188
	v_lshlrev_b32_e32 v189, 16, v189
	v_lshlrev_b32_e32 v190, 16, v190
	v_lshlrev_b32_e32 v191, 16, v191
	v_lshlrev_b32_e32 v192, 16, v192
	v_lshlrev_b32_e32 v193, 16, v193
	v_lshlrev_b32_e32 v194, 16, v194
	v_lshlrev_b32_e32 v195, 16, v195
	v_mul_f32_e32 v196, v18, v196
	v_mul_f32_e32 v197, v19, v197
	v_mul_f32_e32 v198, v20, v198
	v_mul_f32_e32 v199, v21, v199
	v_mul_f32_e32 v200, v22, v200
	v_mul_f32_e32 v201, v23, v201
	v_mul_f32_e32 v202, v24, v202
	v_mul_f32_e32 v203, v25, v203
	v_mul_f32_e32 v204, v26, v204
	v_mul_f32_e32 v205, v27, v205
	v_mul_f32_e32 v206, v28, v206
	v_mul_f32_e32 v207, v29, v207
	v_mul_f32_e32 v208, v30, v208
	v_mul_f32_e32 v209, v31, v209
	v_mul_f32_e32 v210, v32, v210
	v_mul_f32_e32 v211, v33, v211
	v_mul_f32_e32 v180, 0x3e000000, v180
	v_mul_f32_e32 v181, 0x3e000000, v181
	v_mul_f32_e32 v182, 0x3e000000, v182
	v_mul_f32_e32 v183, 0x3e000000, v183
	v_mul_f32_e32 v184, 0x3e000000, v184
	v_mul_f32_e32 v185, 0x3e000000, v185
	v_mul_f32_e32 v186, 0x3e000000, v186
	v_mul_f32_e32 v187, 0x3e000000, v187
	v_mul_f32_e32 v188, 0x3e000000, v188
	v_mul_f32_e32 v189, 0x3e000000, v189
	v_mul_f32_e32 v190, 0x3e000000, v190
	v_mul_f32_e32 v191, 0x3e000000, v191
	v_mul_f32_e32 v192, 0x3e000000, v192
	v_mul_f32_e32 v193, 0x3e000000, v193
	v_mul_f32_e32 v194, 0x3e000000, v194
	v_mul_f32_e32 v195, 0x3e000000, v195
	v_mul_f32_e32 v180, v180, v236
	v_mul_f32_e32 v181, v181, v237
	v_mul_f32_e32 v182, v182, v238
	v_mul_f32_e32 v183, v183, v239
	v_mul_f32_e32 v184, v184, v240
	v_mul_f32_e32 v185, v185, v241
	v_mul_f32_e32 v186, v186, v242
	v_mul_f32_e32 v187, v187, v243
	v_mul_f32_e32 v188, v188, v244
	v_mul_f32_e32 v189, v189, v245
	v_mul_f32_e32 v190, v190, v246
	v_mul_f32_e32 v191, v191, v247
	v_mul_f32_e32 v192, v192, v248
	v_mul_f32_e32 v193, v193, v249
	v_mul_f32_e32 v194, v194, v250
	v_mul_f32_e32 v195, v195, v251
	v_cvt_pk_bf16_f32 v196, v196, v196
	v_cvt_pk_bf16_f32 v197, v197, v197
	v_cvt_pk_bf16_f32 v198, v198, v198
	v_cvt_pk_bf16_f32 v199, v199, v199
	v_cvt_pk_bf16_f32 v200, v200, v200
	v_cvt_pk_bf16_f32 v201, v201, v201
	v_cvt_pk_bf16_f32 v202, v202, v202
	v_cvt_pk_bf16_f32 v203, v203, v203
	v_cvt_pk_bf16_f32 v204, v204, v204
	v_cvt_pk_bf16_f32 v205, v205, v205
	v_cvt_pk_bf16_f32 v206, v206, v206
	v_cvt_pk_bf16_f32 v207, v207, v207
	v_cvt_pk_bf16_f32 v208, v208, v208
	v_cvt_pk_bf16_f32 v209, v209, v209
	v_cvt_pk_bf16_f32 v210, v210, v210
	v_cvt_pk_bf16_f32 v211, v211, v211
	v_cvt_pk_bf16_f32 v180, v180, v180
	v_cvt_pk_bf16_f32 v181, v181, v181
	v_cvt_pk_bf16_f32 v182, v182, v182
	v_cvt_pk_bf16_f32 v183, v183, v183
	v_cvt_pk_bf16_f32 v184, v184, v184
	v_cvt_pk_bf16_f32 v185, v185, v185
; __device__ __forceinline__ unsigned f2bf(float f) { unsigned r; asm("v_cvt_pk_bf16_f32 %0, %1, %1" : "=v"(r) : "v"(f)); return r & 0xffffu; }
; __device__ __forceinline__ void gl1_item(PREF p, int l, int item, bool valid, LAS unsigned char* pl, int sw, int lane) {
;     ...
;                 sKt[lane * 72 + i] = (bf16_t)ktb;
;                 QK[rowi * 1024 + d * 512 + h * 64 + lane] = (bf16_t)f2bf(qt);
;                 QK[rowi * 1024 + d * 512 + 256 + h * 64 + lane] = (bf16_t)ktb;
;             }
; #pragma unroll
;             for (int ss = 0; ss < 16; ++ss) { qc[ss] = bf2f(__builtin_bit_cast(unsigned, qn[ss])); kc[ss] = bf2f(__builtin_bit_cast(unsigned, kn[ss])); }
;         }
;         const float Dv = __expf(bc);
;         sD[lane] = Dv; GLD[(size_t)(seq * NCH + cj) * 64 + lane] = Dv;
	v_cvt_pk_bf16_f32 v186, v186, v186
	v_cvt_pk_bf16_f32 v187, v187, v187
	v_cvt_pk_bf16_f32 v188, v188, v188
	v_cvt_pk_bf16_f32 v189, v189, v189
	v_cvt_pk_bf16_f32 v190, v190, v190
	v_cvt_pk_bf16_f32 v191, v191, v191
	v_cvt_pk_bf16_f32 v192, v192, v192
	v_cvt_pk_bf16_f32 v193, v193, v193
	v_cvt_pk_bf16_f32 v194, v194, v194
	v_cvt_pk_bf16_f32 v195, v195, v195
	ds_write_b16 v60, v196
	v_add_u32_e32 v60, v61, v60
	global_store_short v134, v180, s[4:5]
	global_store_short v134, v196, s[4:5] offset:512
	s_add_u32 s4, s4, s56
	s_addc_u32 s5, s5, s3
	ds_write_b16 v60, v197
	v_add_u32_e32 v60, v61, v60
	global_store_short v134, v181, s[4:5]
	global_store_short v134, v197, s[4:5] offset:512
	s_add_u32 s4, s4, s56
	s_addc_u32 s5, s5, s3
	ds_write_b16 v60, v198
	v_add_u32_e32 v60, v61, v60
	global_store_short v134, v182, s[4:5]
	global_store_short v134, v198, s[4:5] offset:512
	s_add_u32 s4, s4, s56
	s_addc_u32 s5, s5, s3
	ds_write_b16 v60, v199
	v_add_u32_e32 v60, v61, v60
	global_store_short v134, v183, s[4:5]
	global_store_short v134, v199, s[4:5] offset:512
	s_add_u32 s4, s4, s56
	s_addc_u32 s5, s5, s3
	ds_write_b16 v60, v200
	v_add_u32_e32 v60, v61, v60
	global_store_short v134, v184, s[4:5]
	global_store_short v134, v200, s[4:5] offset:512
	s_add_u32 s4, s4, s56
	s_addc_u32 s5, s5, s3
	ds_write_b16 v60, v201
	v_add_u32_e32 v60, v61, v60
	global_store_short v134, v185, s[4:5]
	global_store_short v134, v201, s[4:5] offset:512
	s_add_u32 s4, s4, s56
	s_addc_u32 s5, s5, s3
	ds_write_b16 v60, v202
	v_add_u32_e32 v60, v61, v60
	global_store_short v134, v186, s[4:5]
	global_store_short v134, v202, s[4:5] offset:512
	s_add_u32 s4, s4, s56
	s_addc_u32 s5, s5, s3
	ds_write_b16 v60, v203
	v_add_u32_e32 v60, v61, v60
	global_store_short v134, v187, s[4:5]
	global_store_short v134, v203, s[4:5] offset:512
	s_add_u32 s4, s4, s56
	s_addc_u32 s5, s5, s3
	ds_write_b16 v60, v204
	v_add_u32_e32 v60, v61, v60
	global_store_short v134, v188, s[4:5]
	global_store_short v134, v204, s[4:5] offset:512
	s_add_u32 s4, s4, s56
	s_addc_u32 s5, s5, s3
	ds_write_b16 v60, v205
	v_add_u32_e32 v60, v61, v60
	global_store_short v134, v189, s[4:5]
	global_store_short v134, v205, s[4:5] offset:512
	s_add_u32 s4, s4, s56
	s_addc_u32 s5, s5, s3
	ds_write_b16 v60, v206
	v_add_u32_e32 v60, v61, v60
	global_store_short v134, v190, s[4:5]
	global_store_short v134, v206, s[4:5] offset:512
	s_add_u32 s4, s4, s56
	s_addc_u32 s5, s5, s3
	ds_write_b16 v60, v207
	v_add_u32_e32 v60, v61, v60
	global_store_short v134, v191, s[4:5]
	global_store_short v134, v207, s[4:5] offset:512
	s_add_u32 s4, s4, s56
	s_addc_u32 s5, s5, s3
	ds_write_b16 v60, v208
	v_add_u32_e32 v60, v61, v60
	global_store_short v134, v192, s[4:5]
	global_store_short v134, v208, s[4:5] offset:512
	s_add_u32 s4, s4, s56
	s_addc_u32 s5, s5, s3
	ds_write_b16 v60, v209
	v_add_u32_e32 v60, v61, v60
	global_store_short v134, v193, s[4:5]
	global_store_short v134, v209, s[4:5] offset:512
	s_add_u32 s4, s4, s56
	s_addc_u32 s5, s5, s3
	ds_write_b16 v60, v210
	v_add_u32_e32 v60, v61, v60
	global_store_short v134, v194, s[4:5]
	global_store_short v134, v210, s[4:5] offset:512
	s_add_u32 s4, s4, s56
	s_addc_u32 s5, s5, s3
	ds_write_b16 v60, v211
	v_add_u32_e32 v60, v61, v60
	global_store_short v134, v195, s[4:5]
	global_store_short v134, v211, s[4:5] offset:512
	s_add_u32 s4, s4, s56
	s_addc_u32 s5, s5, s3
	v_mul_f32_e32 v18, 0x3fb8aa3b, v17
	v_exp_f32_e32 v18, v18
	v_readlane_b32 s50, v253, 55
	v_readlane_b32 s51, v253, 56
	v_readlane_b32 s45, v254, 11
	s_nop 3
	s_load_dwordx2 s[46:47], s[50:51], 0xc0
	s_and_b32 s48, s38, 1
	s_lshr_b32 s45, s45, 7
	s_mul_i32 s45, s45, 0x9200
	s_lshl_b32 s48, s48, 8
	s_add_i32 s45, s45, s48
	v_lshl_add_u32 v86, v64, 2, s45
	ds_write_b32 v86, v18 offset:36864
	s_or_b32 s45, s42, s38
	s_mulk_i32 s45, 0x104
	s_add_i32 s45, s45, s41
	s_lshl_b32 s45, s45, 8
	s_waitcnt lgkmcnt(0)
	s_add_u32 s46, s46, 0xd00000
	s_addc_u32 s47, s47, 0
	s_add_u32 s46, s46, s45
	s_addc_u32 s47, s47, 0
	global_store_dword v135, v18, s[46:47]
